# PEER phase rewritten by hand: fp6 expert tables stored column-sliced per XCD (L2-resident slices), stage A/B process 8 rows per wave-instruction, partial dots + w via workspace, final rmsnorm pass; sa
# speedup vs baseline: 1.0921x; 1.0486x over previous
.LBB0_100:
	s_or_b64 exec, exec, s[8:9]
	s_movk_i32 s0, 0x4000
	v_cmp_gt_i32_e64 s[8:9], s0, v174
	v_mul_u32_u24_e32 v130, 24, v236
	s_mul_hi_i32 s13, s80, 0x600
	s_mul_i32 s12, s80, 0x600
	s_and_saveexec_b64 s[14:15], s[8:9]
	s_cbranch_execz .LBB0_361
	v_mbcnt_hi_u32_b32 v0, -1, v152
	v_and_b32_e32 v2, 64, v0
	v_xor_b32_e32 v1, 32, v0
	v_add_u32_e32 v2, 64, v2
	v_cmp_lt_i32_e32 vcc, v1, v2
	s_load_dwordx2 s[0:1], s[76:77], 0x50
	s_load_dwordx2 s[6:7], s[76:77], 0x98
	s_load_dwordx2 s[16:17], s[76:77], 0xa8
	v_cndmask_b32_e32 v1, v0, v1, vcc
	v_lshlrev_b32_e32 v39, 2, v1
	v_xor_b32_e32 v1, 16, v0
	v_cmp_lt_i32_e32 vcc, v1, v2
	v_mov_b32_e32 v131, 0
	s_ashr_i32 s81, s80, 31
	v_cndmask_b32_e32 v1, v0, v1, vcc
	v_lshlrev_b32_e32 v40, 2, v1
	v_xor_b32_e32 v1, 8, v0
	v_cmp_lt_i32_e32 vcc, v1, v2
	v_cmp_eq_u32_e64 s[10:11], 0, v236
	s_waitcnt lgkmcnt(0)
	v_lshl_add_u64 v[32:33], v[174:175], 2, s[16:17]
	v_cndmask_b32_e32 v1, v0, v1, vcc
	v_lshlrev_b32_e32 v41, 2, v1
	v_xor_b32_e32 v1, 4, v0
	v_cmp_lt_i32_e32 vcc, v1, v2
	s_lshl_b64 s[16:17], s[80:81], 2
	s_lshl_b64 s[18:19], s[80:81], 13
	v_cndmask_b32_e32 v1, v0, v1, vcc
	v_lshlrev_b32_e32 v42, 2, v1
	v_xor_b32_e32 v1, 2, v0
	v_cmp_lt_i32_e32 vcc, v1, v2
	s_mov_b64 s[20:21], 0
	s_mov_b32 s3, 0x40f00000
	v_cndmask_b32_e32 v1, v0, v1, vcc
	v_lshlrev_b32_e32 v43, 2, v1
	v_xor_b32_e32 v1, 1, v0
	v_cmp_lt_i32_e32 vcc, v1, v2
	v_mov_b32_e32 v45, v174
	s_nop 0
	v_cndmask_b32_e32 v0, v0, v1, vcc
	v_lshlrev_b32_e32 v44, 2, v0
	v_lshlrev_b64 v[0:1], 13, v[174:175]
	v_lshl_or_b32 v0, v236, 4, v0
	v_lshl_add_u64 v[0:1], s[0:1], 0, v[0:1]
	s_mov_b64 s[0:1], 0x1000
	v_lshl_add_u64 v[34:35], v[0:1], 0, s[0:1]
	s_movk_i32 s0, 0xc0
	v_lshrrev_b32_e32 v46, 3, v236
	v_and_b32_e32 v47, 7, v236
	v_mul_u32_u24_e32 v46, 0x300000, v46
	v_mul_u32_u24_e32 v47, 24, v47
	v_add_u32_e32 v46, v46, v47
	v_mov_b32_e32 v47, 0
	s_lshr_b64 s[98:99], s[12:13], 3
	v_mad_i64_i32 v[0:1], s[0:1], v174, s0, v[46:47]
	v_lshl_add_u64 v[0:1], s[6:7], 0, v[0:1]
	v_lshl_add_u64 v[36:37], v[0:1], 0, 8
	s_mov_b32 s6, 0x41000000
	s_movk_i32 s7, 0x3fff
	s_branch .LBB0_103
.LBB0_102:
	s_or_b64 exec, exec, s[22:23]
	v_add_u32_e32 v45, s80, v45
	v_cmp_lt_i32_e32 vcc, s7, v45
	v_lshl_add_u64 v[32:33], v[32:33], 0, s[16:17]
	v_lshl_add_u64 v[34:35], v[34:35], 0, s[18:19]
	s_or_b64 s[20:21], vcc, s[20:21]
	v_lshl_add_u64 v[36:37], v[36:37], 0, s[98:99]
	s_andn2_b64 exec, exec, s[20:21]
	s_cbranch_execz .LBB0_361

.LBB0_361:
	s_or_b64 exec, exec, s[14:15]
	s_and_saveexec_b64 s[10:11], s[8:9]
	s_cbranch_execz .LBB0_622
	v_mbcnt_hi_u32_b32 v0, -1, v152
	v_and_b32_e32 v2, 64, v0
	v_xor_b32_e32 v1, 32, v0
	v_add_u32_e32 v2, 64, v2
	v_cmp_lt_i32_e32 vcc, v1, v2
	s_load_dwordx2 s[0:1], s[76:77], 0x58
	s_load_dwordx2 s[6:7], s[76:77], 0xa0
	s_load_dwordx2 s[14:15], s[76:77], 0xb0
	v_cndmask_b32_e32 v1, v0, v1, vcc
	v_lshlrev_b32_e32 v39, 2, v1
	v_xor_b32_e32 v1, 16, v0
	v_cmp_lt_i32_e32 vcc, v1, v2
	v_mov_b32_e32 v131, 0
	s_ashr_i32 s81, s80, 31
	v_cndmask_b32_e32 v1, v0, v1, vcc
	v_lshlrev_b32_e32 v40, 2, v1
	v_xor_b32_e32 v1, 8, v0
	v_cmp_lt_i32_e32 vcc, v1, v2
	v_cmp_eq_u32_e64 s[8:9], 0, v236
	s_waitcnt lgkmcnt(0)
	v_lshl_add_u64 v[32:33], v[174:175], 2, s[14:15]
	v_cndmask_b32_e32 v1, v0, v1, vcc
	v_lshlrev_b32_e32 v41, 2, v1
	v_xor_b32_e32 v1, 4, v0
	v_cmp_lt_i32_e32 vcc, v1, v2
	s_lshl_b64 s[14:15], s[80:81], 2
	s_lshl_b64 s[16:17], s[80:81], 13
	v_cndmask_b32_e32 v1, v0, v1, vcc
	v_lshlrev_b32_e32 v42, 2, v1
	v_xor_b32_e32 v1, 2, v0
	v_cmp_lt_i32_e32 vcc, v1, v2
	s_mov_b64 s[18:19], 0
	s_mov_b32 s3, 0x40f00000
	v_cndmask_b32_e32 v1, v0, v1, vcc
	v_lshlrev_b32_e32 v43, 2, v1
	v_xor_b32_e32 v1, 1, v0
	v_cmp_lt_i32_e32 vcc, v1, v2
	v_mov_b32_e32 v45, v174
	s_nop 0
	v_cndmask_b32_e32 v0, v0, v1, vcc
	v_lshlrev_b32_e32 v44, 2, v0
	v_lshlrev_b64 v[0:1], 13, v[174:175]
	v_lshl_or_b32 v0, v236, 4, v0
	v_lshl_add_u64 v[0:1], s[0:1], 0, v[0:1]
	s_mov_b64 s[0:1], 0x1000
	v_lshl_add_u64 v[34:35], v[0:1], 0, s[0:1]
	s_movk_i32 s0, 0xc0
	v_lshrrev_b32_e32 v46, 3, v236
	v_and_b32_e32 v47, 7, v236
	v_mul_u32_u24_e32 v46, 0x300000, v46
	v_mul_u32_u24_e32 v47, 24, v47
	v_add_u32_e32 v46, v46, v47
	v_mov_b32_e32 v47, 0
	s_lshr_b64 s[98:99], s[12:13], 3
	v_mad_i64_i32 v[0:1], s[0:1], v174, s0, v[46:47]
	v_lshl_add_u64 v[0:1], s[6:7], 0, v[0:1]
	v_lshl_add_u64 v[36:37], v[0:1], 0, 8
	s_mov_b32 s6, 0x41000000
	s_movk_i32 s7, 0x3fff
	s_branch .LBB0_364
.LBB0_363:
	s_or_b64 exec, exec, s[20:21]
	v_add_u32_e32 v45, s80, v45
	v_cmp_lt_i32_e32 vcc, s7, v45
	v_lshl_add_u64 v[32:33], v[32:33], 0, s[14:15]
	v_lshl_add_u64 v[34:35], v[34:35], 0, s[16:17]
	s_or_b64 s[18:19], vcc, s[18:19]
	v_lshl_add_u64 v[36:37], v[36:37], 0, s[98:99]
	s_andn2_b64 exec, exec, s[18:19]
	s_cbranch_execz .LBB0_622

.LBB0_1385:
	s_mov_b64 exec, -1
	s_nop 3
	v_readfirstlane_b32 s20, v174
	s_load_dwordx4 s[4:7], s[52:53], 0x120
	s_load_dwordx2 s[8:9], s[52:53], 0xa0
	s_load_dwordx2 s[10:11], s[52:53], 0x68
	s_load_dwordx2 s[12:13], s[52:53], 0x108
	s_load_dwordx2 s[14:15], s[52:53], 0x140
	s_load_dwordx2 s[16:17], s[52:53], 0x60
	s_load_dwordx2 s[48:49], s[52:53], 0x98
	s_load_dwordx2 s[78:79], s[52:53], 0x100
	s_load_dwordx2 s[54:55], s[52:53], 0x118
	s_load_dwordx2 s[56:57], s[52:53], 0x38
	s_load_dwordx2 s[58:59], s[52:53], 0xa8
	s_load_dwordx2 s[76:77], s[52:53], 0xb0
	s_and_b32 s21, s20, 3
	s_lshr_b32 s22, s20, 2
	s_and_b32 s23, s22, 7
	s_lshr_b32 s24, s22, 3
	s_lshl_b32 s24, s24, 2
	s_add_u32 s24, s24, s21
	s_lshr_b32 s25, s80, 2
	s_lshl_b32 s43, s23, 2
	s_movk_i32 s19, 0xc0
	v_mbcnt_lo_u32_b32 v0, -1, 0
	v_mbcnt_hi_u32_b32 v0, -1, v0
	v_and_b32_e32 v10, 7, v0
	v_lshrrev_b32_e32 v11, 3, v0
	v_mul_u32_u24_e32 v1, 24, v10
	v_lshlrev_b32_e32 v2, 6, v11
	v_mov_b32_e32 v3, 0
	s_mul_i32 s29, s21, 0x2400
	v_mul_u32_u24_e32 v4, 0x90, v0
	v_add_u32_e32 v4, s29, v4
	v_mul_u32_u24_e32 v5, 0x90, v10
	v_lshl_add_u32 v5, v11, 4, v5
	v_add_u32_e32 v5, s29, v5
	v_lshlrev_b32_e32 v6, 10, v11
	v_lshl_add_u32 v6, v10, 4, v6
	s_lshl_b32 s29, s23, 7
	v_add_u32_e32 v6, s29, v6
	v_cmp_eq_u32_e64 s[36:37], 63, v0
	s_waitcnt lgkmcnt(0)
	s_mul_i32 s29, s23, 0x300000
	s_add_u32 s26, s8, s29
	s_addc_u32 s27, s9, 0
	s_add_u32 s48, s48, s29
	s_addc_u32 s49, s49, 0
	s_lshl_b32 s29, s23, 9
	s_add_u32 s50, s78, s29
	s_addc_u32 s51, s79, 0
	v_cmp_eq_u32_e64 s[60:61], 0, v10
	v_cmp_eq_u32_e64 s[62:63], 1, v10
	v_cmp_eq_u32_e64 s[64:65], 2, v10
	v_cmp_eq_u32_e64 s[66:67], 3, v10
	v_cmp_eq_u32_e64 s[68:69], 4, v10
	v_cmp_eq_u32_e64 s[70:71], 5, v10
	v_cmp_eq_u32_e64 s[72:73], 6, v10
	v_cmp_eq_u32_e64 s[74:75], 7, v10
	v_lshlrev_b32_e32 v9, 2, v10
	v_lshl_add_u32 v9, v11, 6, v9
	s_lshl_b32 s29, s23, 7
	v_lshlrev_b32_e32 v13, 4, v10
	v_add_u32_e32 v13, s29, v13
	v_add_u32_e32 v14, 0x1000, v13
	v_lshl_add_u32 v15, v11, 10, v13
	global_load_dwordx4 v[112:115], v15, s[56:57]
	s_mul_i32 s29, s21, 0x2400
	v_mul_u32_u24_e32 v12, 0x90, v10
	v_add_u32_e32 v12, s29, v12
	v_lshl_add_u32 v15, v11, 4, v12
	s_waitcnt vmcnt(0)
	ds_write_b128 v15, v[112:115]
	s_waitcnt lgkmcnt(0)
	v_mov_b32_e32 v124, v12
	v_lshlrev_b32_e32 v125, 4, v10
	s_mov_b32 s28, 0
	s_add_u32 s40, s28, 0
	s_min_u32 s40, s40, 127
	s_lshl_b32 s40, s40, 8
	s_add_u32 s40, s40, s24
	s_lshl_b32 s29, s40, 13
	s_add_u32 s34, s10, s29
	s_addc_u32 s35, s11, 0
	global_load_dwordx4 v[48:51], v13, s[34:35] offset:0
	global_load_dwordx4 v[52:55], v13, s[34:35] offset:1024
	global_load_dwordx4 v[56:59], v13, s[34:35] offset:2048
	global_load_dwordx4 v[60:63], v13, s[34:35] offset:3072
	global_load_dwordx4 v[64:67], v14, s[34:35] offset:0
	global_load_dwordx4 v[68:71], v14, s[34:35] offset:1024
	global_load_dwordx4 v[72:75], v14, s[34:35] offset:2048
	global_load_dwordx4 v[76:79], v14, s[34:35] offset:3072
	s_lshl_b32 s29, s40, 7
	s_add_u32 s38, s54, s29
	s_addc_u32 s39, s55, 0
	global_load_dwordx4 v[112:115], v125, s[38:39]
	s_add_u32 s40, s28, 0
	s_min_u32 s40, s40, 127
	s_lshl_b32 s40, s40, 8
	s_add_u32 s40, s40, s24
	s_lshl_b32 s29, s40, 9
	s_add_u32 s30, s4, s29
	s_addc_u32 s31, s5, 0
	global_load_dwordx4 v[16:19], v2, s[30:31] offset:0
	global_load_dwordx4 v[20:23], v2, s[30:31] offset:16
	global_load_dwordx4 v[24:27], v2, s[30:31] offset:32
	global_load_dwordx4 v[28:31], v2, s[30:31] offset:48
	s_add_u32 s40, s28, 1
	s_min_u32 s40, s40, 127
	s_lshl_b32 s40, s40, 8
	s_add_u32 s40, s40, s24
	s_lshl_b32 s29, s40, 9
	s_add_u32 s30, s4, s29
	s_addc_u32 s31, s5, 0
	global_load_dwordx4 v[32:35], v2, s[30:31] offset:0
	global_load_dwordx4 v[36:39], v2, s[30:31] offset:16
	global_load_dwordx4 v[40:43], v2, s[30:31] offset:32
	global_load_dwordx4 v[44:47], v2, s[30:31] offset:48
	s_waitcnt vmcnt(0)
	v_mad_u32_u24 v7, v16, s19, v1
	global_load_dwordx4 v[160:163], v7, s[48:49]
	global_load_dwordx2 v[164:165], v7, s[48:49] offset:16
	v_mad_u32_u24 v8, v17, s19, v1
	global_load_dwordx4 v[166:169], v8, s[48:49]
	global_load_dwordx2 v[170:171], v8, s[48:49] offset:16
	v_mad_u32_u24 v7, v18, s19, v1
	global_load_dwordx4 v[172:175], v7, s[48:49]
	global_load_dwordx2 v[176:177], v7, s[48:49] offset:16
	v_mad_u32_u24 v8, v19, s19, v1
	global_load_dwordx4 v[178:181], v8, s[48:49]
	global_load_dwordx2 v[182:183], v8, s[48:49] offset:16
	v_mad_u32_u24 v7, v20, s19, v1
	global_load_dwordx4 v[184:187], v7, s[48:49]
	global_load_dwordx2 v[188:189], v7, s[48:49] offset:16
	v_mad_u32_u24 v8, v21, s19, v1
	global_load_dwordx4 v[190:193], v8, s[48:49]
	global_load_dwordx2 v[194:195], v8, s[48:49] offset:16
	v_mad_u32_u24 v7, v22, s19, v1
	global_load_dwordx4 v[196:199], v7, s[48:49]
	global_load_dwordx2 v[200:201], v7, s[48:49] offset:16
	v_mad_u32_u24 v8, v23, s19, v1
	global_load_dwordx4 v[202:205], v8, s[48:49]
	global_load_dwordx2 v[206:207], v8, s[48:49] offset:16
	v_mad_u32_u24 v7, v24, s19, v1
	global_load_dwordx4 v[208:211], v7, s[48:49]
	global_load_dwordx2 v[212:213], v7, s[48:49] offset:16
	v_mad_u32_u24 v8, v25, s19, v1
	global_load_dwordx4 v[214:217], v8, s[48:49]
	global_load_dwordx2 v[218:219], v8, s[48:49] offset:16
	v_mad_u32_u24 v7, v26, s19, v1
	global_load_dwordx4 v[220:223], v7, s[48:49]
	global_load_dwordx2 v[224:225], v7, s[48:49] offset:16
	v_mad_u32_u24 v8, v27, s19, v1
	global_load_dwordx4 v[226:229], v8, s[48:49]
	global_load_dwordx2 v[230:231], v8, s[48:49] offset:16
	v_mad_u32_u24 v7, v28, s19, v1
	global_load_dwordx4 v[232:235], v7, s[48:49]
	global_load_dwordx2 v[236:237], v7, s[48:49] offset:16
	v_mad_u32_u24 v8, v29, s19, v1
	global_load_dwordx4 v[238:241], v8, s[48:49]
	global_load_dwordx2 v[242:243], v8, s[48:49] offset:16
	v_mad_u32_u24 v7, v30, s19, v1
	global_load_dwordx4 v[244:247], v7, s[48:49]
	global_load_dwordx2 v[248:249], v7, s[48:49] offset:16
	v_mad_u32_u24 v8, v31, s19, v1
	global_load_dwordx4 v[250:253], v8, s[48:49]
	global_load_dwordx2 v[254:255], v8, s[48:49] offset:16
	global_store_dword v3, v3, s[14:15] offset:480
	global_store_dword v3, v3, s[14:15] offset:484
.Lpa_tokloop:
	s_waitcnt vmcnt(34)
	ds_read_b128 v[128:131], v124 offset:0
	ds_read_b128 v[132:135], v124 offset:16
	ds_read_b128 v[136:139], v124 offset:32
	ds_read_b128 v[140:143], v124 offset:48
	ds_read_b128 v[144:147], v124 offset:64
	ds_read_b128 v[148:151], v124 offset:80
	ds_read_b128 v[152:155], v124 offset:96
	ds_read_b128 v[156:159], v124 offset:112
	v_add_f32_e32 v126, v112, v113
	v_add_f32_e32 v127, v114, v115
	v_add_f32_e32 v126, v126, v127
	s_nop 1
	v_add_f32_dpp v126, v126, v126 quad_perm:[1,0,3,2] row_mask:0xf bank_mask:0xf
	s_nop 1
	v_add_f32_dpp v126, v126, v126 quad_perm:[2,3,0,1] row_mask:0xf bank_mask:0xf
	s_nop 1
	v_add_f32_dpp v126, v126, v126 row_half_mirror row_mask:0xf bank_mask:0xf
	s_nop 1
	v_mov_b32_e32 v127, 0x358637bd
	v_fmac_f32_e32 v127, 0x3a000000, v126
	v_rsq_f32_e32 v127, v127
	s_waitcnt lgkmcnt(0)
	v_pk_mul_f32 v[80:81], v[48:49], v[128:129]
	v_pk_mul_f32 v[82:83], v[50:51], v[130:131]
	v_pk_mul_f32 v[84:85], v[52:53], v[132:133]
	v_pk_mul_f32 v[86:87], v[54:55], v[134:135]
	v_pk_mul_f32 v[88:89], v[56:57], v[136:137]
	v_pk_mul_f32 v[90:91], v[58:59], v[138:139]
	v_pk_mul_f32 v[92:93], v[60:61], v[140:141]
	v_pk_mul_f32 v[94:95], v[62:63], v[142:143]
	v_pk_mul_f32 v[96:97], v[64:65], v[144:145]
	v_pk_mul_f32 v[98:99], v[66:67], v[146:147]
	v_pk_mul_f32 v[100:101], v[68:69], v[148:149]
	v_pk_mul_f32 v[102:103], v[70:71], v[150:151]
	v_pk_mul_f32 v[104:105], v[72:73], v[152:153]
	v_pk_mul_f32 v[106:107], v[74:75], v[154:155]
	v_pk_mul_f32 v[108:109], v[76:77], v[156:157]
	v_pk_mul_f32 v[110:111], v[78:79], v[158:159]
	s_add_u32 s40, s28, 0
	s_min_u32 s40, s40, 127
	s_lshl_b32 s40, s40, 8
	s_add_u32 s40, s40, s24
	s_lshl_b32 s29, s40, 12
	s_add_u32 s44, s50, s29
	s_addc_u32 s45, s51, 0
	s_add_u32 s40, s28, 1
	s_min_u32 s40, s40, 127
	s_lshl_b32 s40, s40, 8
	s_add_u32 s40, s40, s24
	s_lshl_b32 s29, s40, 13
	s_add_u32 s34, s10, s29
	s_addc_u32 s35, s11, 0
	global_load_dwordx4 v[48:51], v13, s[34:35] offset:0
	global_load_dwordx4 v[52:55], v13, s[34:35] offset:1024
	global_load_dwordx4 v[56:59], v13, s[34:35] offset:2048
	global_load_dwordx4 v[60:63], v13, s[34:35] offset:3072
	global_load_dwordx4 v[64:67], v14, s[34:35] offset:0
	global_load_dwordx4 v[68:71], v14, s[34:35] offset:1024
	global_load_dwordx4 v[72:75], v14, s[34:35] offset:2048
	global_load_dwordx4 v[76:79], v14, s[34:35] offset:3072
	s_lshl_b32 s29, s40, 7
	s_add_u32 s38, s54, s29
	s_addc_u32 s39, s55, 0
	global_load_dwordx4 v[112:115], v125, s[38:39]
	s_add_u32 s40, s28, 2
	s_min_u32 s40, s40, 127
	s_lshl_b32 s40, s40, 8
	s_add_u32 s40, s40, s24
	s_lshl_b32 s29, s40, 9
	s_add_u32 s30, s4, s29
	s_addc_u32 s31, s5, 0
	global_load_dwordx4 v[16:19], v2, s[30:31] offset:0
	global_load_dwordx4 v[20:23], v2, s[30:31] offset:16
	global_load_dwordx4 v[24:27], v2, s[30:31] offset:32
	global_load_dwordx4 v[28:31], v2, s[30:31] offset:48
	s_waitcnt vmcnt(45)
	v_cvt_scalef32_pk32_f32_fp6 v[128:159], v[160:165], 1.0
	v_pk_mul_f32 v[116:117], v[128:129], v[80:81]
	v_pk_mul_f32 v[118:119], v[130:131], v[82:83]
	v_pk_mul_f32 v[120:121], v[132:133], v[84:85]
	v_pk_mul_f32 v[122:123], v[134:135], v[86:87]
	v_pk_fma_f32 v[116:117], v[136:137], v[88:89], v[116:117]
	v_pk_fma_f32 v[118:119], v[138:139], v[90:91], v[118:119]
	v_pk_fma_f32 v[120:121], v[140:141], v[92:93], v[120:121]
	v_pk_fma_f32 v[122:123], v[142:143], v[94:95], v[122:123]
	v_pk_fma_f32 v[116:117], v[144:145], v[96:97], v[116:117]
	v_pk_fma_f32 v[118:119], v[146:147], v[98:99], v[118:119]
	v_pk_fma_f32 v[120:121], v[148:149], v[100:101], v[120:121]
	v_pk_fma_f32 v[122:123], v[150:151], v[102:103], v[122:123]
	v_pk_fma_f32 v[116:117], v[152:153], v[104:105], v[116:117]
	v_pk_fma_f32 v[118:119], v[154:155], v[106:107], v[118:119]
	v_pk_fma_f32 v[120:121], v[156:157], v[108:109], v[120:121]
	v_pk_fma_f32 v[122:123], v[158:159], v[110:111], v[122:123]
	v_pk_add_f32 v[116:117], v[116:117], v[118:119]
	v_pk_add_f32 v[120:121], v[120:121], v[122:123]
	v_pk_add_f32 v[116:117], v[116:117], v[120:121]
	v_add_f32_e32 v126, v116, v117
	v_mad_u32_u24 v7, v32, s19, v1
	s_nop 0
	v_add_f32_dpp v126, v126, v126 quad_perm:[1,0,3,2] row_mask:0xf bank_mask:0xf
	global_load_dwordx4 v[160:163], v7, s[48:49]
	s_nop 0
	v_add_f32_dpp v126, v126, v126 quad_perm:[2,3,0,1] row_mask:0xf bank_mask:0xf
	global_load_dwordx2 v[164:165], v7, s[48:49] offset:16
	s_nop 0
	v_add_f32_dpp v126, v126, v126 row_half_mirror row_mask:0xf bank_mask:0xf
	v_cndmask_b32_e64 v12, v12, v126, s[60:61]
	s_waitcnt vmcnt(45)
	v_cvt_scalef32_pk32_f32_fp6 v[128:159], v[166:171], 1.0
	v_pk_mul_f32 v[116:117], v[128:129], v[80:81]
	v_pk_mul_f32 v[118:119], v[130:131], v[82:83]
	v_pk_mul_f32 v[120:121], v[132:133], v[84:85]
	v_pk_mul_f32 v[122:123], v[134:135], v[86:87]
	v_pk_fma_f32 v[116:117], v[136:137], v[88:89], v[116:117]
	v_pk_fma_f32 v[118:119], v[138:139], v[90:91], v[118:119]
	v_pk_fma_f32 v[120:121], v[140:141], v[92:93], v[120:121]
	v_pk_fma_f32 v[122:123], v[142:143], v[94:95], v[122:123]
	v_pk_fma_f32 v[116:117], v[144:145], v[96:97], v[116:117]
	v_pk_fma_f32 v[118:119], v[146:147], v[98:99], v[118:119]
	v_pk_fma_f32 v[120:121], v[148:149], v[100:101], v[120:121]
	v_pk_fma_f32 v[122:123], v[150:151], v[102:103], v[122:123]
	v_pk_fma_f32 v[116:117], v[152:153], v[104:105], v[116:117]
	v_pk_fma_f32 v[118:119], v[154:155], v[106:107], v[118:119]
	v_pk_fma_f32 v[120:121], v[156:157], v[108:109], v[120:121]
	v_pk_fma_f32 v[122:123], v[158:159], v[110:111], v[122:123]
	v_pk_add_f32 v[116:117], v[116:117], v[118:119]
	v_pk_add_f32 v[120:121], v[120:121], v[122:123]
	v_pk_add_f32 v[116:117], v[116:117], v[120:121]
	v_add_f32_e32 v126, v116, v117
	v_mad_u32_u24 v8, v33, s19, v1
	s_nop 0
	v_add_f32_dpp v126, v126, v126 quad_perm:[1,0,3,2] row_mask:0xf bank_mask:0xf
	global_load_dwordx4 v[166:169], v8, s[48:49]
	s_nop 0
	v_add_f32_dpp v126, v126, v126 quad_perm:[2,3,0,1] row_mask:0xf bank_mask:0xf
	global_load_dwordx2 v[170:171], v8, s[48:49] offset:16
	s_nop 0
	v_add_f32_dpp v126, v126, v126 row_half_mirror row_mask:0xf bank_mask:0xf
	v_cndmask_b32_e64 v12, v12, v126, s[62:63]
	s_waitcnt vmcnt(45)
	v_cvt_scalef32_pk32_f32_fp6 v[128:159], v[172:177], 1.0
	v_pk_mul_f32 v[116:117], v[128:129], v[80:81]
	v_pk_mul_f32 v[118:119], v[130:131], v[82:83]
	v_pk_mul_f32 v[120:121], v[132:133], v[84:85]
	v_pk_mul_f32 v[122:123], v[134:135], v[86:87]
	v_pk_fma_f32 v[116:117], v[136:137], v[88:89], v[116:117]
	v_pk_fma_f32 v[118:119], v[138:139], v[90:91], v[118:119]
	v_pk_fma_f32 v[120:121], v[140:141], v[92:93], v[120:121]
	v_pk_fma_f32 v[122:123], v[142:143], v[94:95], v[122:123]
	v_pk_fma_f32 v[116:117], v[144:145], v[96:97], v[116:117]
	v_pk_fma_f32 v[118:119], v[146:147], v[98:99], v[118:119]
	v_pk_fma_f32 v[120:121], v[148:149], v[100:101], v[120:121]
	v_pk_fma_f32 v[122:123], v[150:151], v[102:103], v[122:123]
	v_pk_fma_f32 v[116:117], v[152:153], v[104:105], v[116:117]
	v_pk_fma_f32 v[118:119], v[154:155], v[106:107], v[118:119]
	v_pk_fma_f32 v[120:121], v[156:157], v[108:109], v[120:121]
	v_pk_fma_f32 v[122:123], v[158:159], v[110:111], v[122:123]
	v_pk_add_f32 v[116:117], v[116:117], v[118:119]
	v_pk_add_f32 v[120:121], v[120:121], v[122:123]
	v_pk_add_f32 v[116:117], v[116:117], v[120:121]
	v_add_f32_e32 v126, v116, v117
	v_mad_u32_u24 v7, v34, s19, v1
	s_nop 0
	v_add_f32_dpp v126, v126, v126 quad_perm:[1,0,3,2] row_mask:0xf bank_mask:0xf
	global_load_dwordx4 v[172:175], v7, s[48:49]
	s_nop 0
	v_add_f32_dpp v126, v126, v126 quad_perm:[2,3,0,1] row_mask:0xf bank_mask:0xf
	global_load_dwordx2 v[176:177], v7, s[48:49] offset:16
	s_nop 0
	v_add_f32_dpp v126, v126, v126 row_half_mirror row_mask:0xf bank_mask:0xf
	v_cndmask_b32_e64 v12, v12, v126, s[64:65]
	s_waitcnt vmcnt(45)
	v_cvt_scalef32_pk32_f32_fp6 v[128:159], v[178:183], 1.0
	v_pk_mul_f32 v[116:117], v[128:129], v[80:81]
	v_pk_mul_f32 v[118:119], v[130:131], v[82:83]
	v_pk_mul_f32 v[120:121], v[132:133], v[84:85]
	v_pk_mul_f32 v[122:123], v[134:135], v[86:87]
	v_pk_fma_f32 v[116:117], v[136:137], v[88:89], v[116:117]
	v_pk_fma_f32 v[118:119], v[138:139], v[90:91], v[118:119]
	v_pk_fma_f32 v[120:121], v[140:141], v[92:93], v[120:121]
	v_pk_fma_f32 v[122:123], v[142:143], v[94:95], v[122:123]
	v_pk_fma_f32 v[116:117], v[144:145], v[96:97], v[116:117]
	v_pk_fma_f32 v[118:119], v[146:147], v[98:99], v[118:119]
	v_pk_fma_f32 v[120:121], v[148:149], v[100:101], v[120:121]
	v_pk_fma_f32 v[122:123], v[150:151], v[102:103], v[122:123]
	v_pk_fma_f32 v[116:117], v[152:153], v[104:105], v[116:117]
	v_pk_fma_f32 v[118:119], v[154:155], v[106:107], v[118:119]
	v_pk_fma_f32 v[120:121], v[156:157], v[108:109], v[120:121]
	v_pk_fma_f32 v[122:123], v[158:159], v[110:111], v[122:123]
	v_pk_add_f32 v[116:117], v[116:117], v[118:119]
	v_pk_add_f32 v[120:121], v[120:121], v[122:123]
	v_pk_add_f32 v[116:117], v[116:117], v[120:121]
	v_add_f32_e32 v126, v116, v117
	v_mad_u32_u24 v8, v35, s19, v1
	s_nop 0
	v_add_f32_dpp v126, v126, v126 quad_perm:[1,0,3,2] row_mask:0xf bank_mask:0xf
	global_load_dwordx4 v[178:181], v8, s[48:49]
	s_nop 0
	v_add_f32_dpp v126, v126, v126 quad_perm:[2,3,0,1] row_mask:0xf bank_mask:0xf
	global_load_dwordx2 v[182:183], v8, s[48:49] offset:16
	s_nop 0
	v_add_f32_dpp v126, v126, v126 row_half_mirror row_mask:0xf bank_mask:0xf
	v_cndmask_b32_e64 v12, v12, v126, s[66:67]
	s_waitcnt vmcnt(45)
	v_cvt_scalef32_pk32_f32_fp6 v[128:159], v[184:189], 1.0
	v_pk_mul_f32 v[116:117], v[128:129], v[80:81]
	v_pk_mul_f32 v[118:119], v[130:131], v[82:83]
	v_pk_mul_f32 v[120:121], v[132:133], v[84:85]
	v_pk_mul_f32 v[122:123], v[134:135], v[86:87]
	v_pk_fma_f32 v[116:117], v[136:137], v[88:89], v[116:117]
	v_pk_fma_f32 v[118:119], v[138:139], v[90:91], v[118:119]
	v_pk_fma_f32 v[120:121], v[140:141], v[92:93], v[120:121]
	v_pk_fma_f32 v[122:123], v[142:143], v[94:95], v[122:123]
	v_pk_fma_f32 v[116:117], v[144:145], v[96:97], v[116:117]
	v_pk_fma_f32 v[118:119], v[146:147], v[98:99], v[118:119]
	v_pk_fma_f32 v[120:121], v[148:149], v[100:101], v[120:121]
	v_pk_fma_f32 v[122:123], v[150:151], v[102:103], v[122:123]
	v_pk_fma_f32 v[116:117], v[152:153], v[104:105], v[116:117]
	v_pk_fma_f32 v[118:119], v[154:155], v[106:107], v[118:119]
	v_pk_fma_f32 v[120:121], v[156:157], v[108:109], v[120:121]
	v_pk_fma_f32 v[122:123], v[158:159], v[110:111], v[122:123]
	v_pk_add_f32 v[116:117], v[116:117], v[118:119]
	v_pk_add_f32 v[120:121], v[120:121], v[122:123]
	v_pk_add_f32 v[116:117], v[116:117], v[120:121]
	v_add_f32_e32 v126, v116, v117
	v_mad_u32_u24 v7, v36, s19, v1
	s_nop 0
	v_add_f32_dpp v126, v126, v126 quad_perm:[1,0,3,2] row_mask:0xf bank_mask:0xf
	global_load_dwordx4 v[184:187], v7, s[48:49]
	s_nop 0
	v_add_f32_dpp v126, v126, v126 quad_perm:[2,3,0,1] row_mask:0xf bank_mask:0xf
	global_load_dwordx2 v[188:189], v7, s[48:49] offset:16
	s_nop 0
	v_add_f32_dpp v126, v126, v126 row_half_mirror row_mask:0xf bank_mask:0xf
	v_cndmask_b32_e64 v12, v12, v126, s[68:69]
	s_waitcnt vmcnt(45)
	v_cvt_scalef32_pk32_f32_fp6 v[128:159], v[190:195], 1.0
	v_pk_mul_f32 v[116:117], v[128:129], v[80:81]
	v_pk_mul_f32 v[118:119], v[130:131], v[82:83]
	v_pk_mul_f32 v[120:121], v[132:133], v[84:85]
	v_pk_mul_f32 v[122:123], v[134:135], v[86:87]
	v_pk_fma_f32 v[116:117], v[136:137], v[88:89], v[116:117]
	v_pk_fma_f32 v[118:119], v[138:139], v[90:91], v[118:119]
	v_pk_fma_f32 v[120:121], v[140:141], v[92:93], v[120:121]
	v_pk_fma_f32 v[122:123], v[142:143], v[94:95], v[122:123]
	v_pk_fma_f32 v[116:117], v[144:145], v[96:97], v[116:117]
	v_pk_fma_f32 v[118:119], v[146:147], v[98:99], v[118:119]
	v_pk_fma_f32 v[120:121], v[148:149], v[100:101], v[120:121]
	v_pk_fma_f32 v[122:123], v[150:151], v[102:103], v[122:123]
	v_pk_fma_f32 v[116:117], v[152:153], v[104:105], v[116:117]
	v_pk_fma_f32 v[118:119], v[154:155], v[106:107], v[118:119]
	v_pk_fma_f32 v[120:121], v[156:157], v[108:109], v[120:121]
	v_pk_fma_f32 v[122:123], v[158:159], v[110:111], v[122:123]
	v_pk_add_f32 v[116:117], v[116:117], v[118:119]
	v_pk_add_f32 v[120:121], v[120:121], v[122:123]
	v_pk_add_f32 v[116:117], v[116:117], v[120:121]
	v_add_f32_e32 v126, v116, v117
	v_mad_u32_u24 v8, v37, s19, v1
	s_nop 0
	v_add_f32_dpp v126, v126, v126 quad_perm:[1,0,3,2] row_mask:0xf bank_mask:0xf
	global_load_dwordx4 v[190:193], v8, s[48:49]
	s_nop 0
	v_add_f32_dpp v126, v126, v126 quad_perm:[2,3,0,1] row_mask:0xf bank_mask:0xf
	global_load_dwordx2 v[194:195], v8, s[48:49] offset:16
	s_nop 0
	v_add_f32_dpp v126, v126, v126 row_half_mirror row_mask:0xf bank_mask:0xf
	v_cndmask_b32_e64 v12, v12, v126, s[70:71]
	s_waitcnt vmcnt(45)
	v_cvt_scalef32_pk32_f32_fp6 v[128:159], v[196:201], 1.0
	v_pk_mul_f32 v[116:117], v[128:129], v[80:81]
	v_pk_mul_f32 v[118:119], v[130:131], v[82:83]
	v_pk_mul_f32 v[120:121], v[132:133], v[84:85]
	v_pk_mul_f32 v[122:123], v[134:135], v[86:87]
	v_pk_fma_f32 v[116:117], v[136:137], v[88:89], v[116:117]
	v_pk_fma_f32 v[118:119], v[138:139], v[90:91], v[118:119]
	v_pk_fma_f32 v[120:121], v[140:141], v[92:93], v[120:121]
	v_pk_fma_f32 v[122:123], v[142:143], v[94:95], v[122:123]
	v_pk_fma_f32 v[116:117], v[144:145], v[96:97], v[116:117]
	v_pk_fma_f32 v[118:119], v[146:147], v[98:99], v[118:119]
	v_pk_fma_f32 v[120:121], v[148:149], v[100:101], v[120:121]
	v_pk_fma_f32 v[122:123], v[150:151], v[102:103], v[122:123]
	v_pk_fma_f32 v[116:117], v[152:153], v[104:105], v[116:117]
	v_pk_fma_f32 v[118:119], v[154:155], v[106:107], v[118:119]
	v_pk_fma_f32 v[120:121], v[156:157], v[108:109], v[120:121]
	v_pk_fma_f32 v[122:123], v[158:159], v[110:111], v[122:123]
	v_pk_add_f32 v[116:117], v[116:117], v[118:119]
	v_pk_add_f32 v[120:121], v[120:121], v[122:123]
	v_pk_add_f32 v[116:117], v[116:117], v[120:121]
	v_add_f32_e32 v126, v116, v117
	v_mad_u32_u24 v7, v38, s19, v1
	s_nop 0
	v_add_f32_dpp v126, v126, v126 quad_perm:[1,0,3,2] row_mask:0xf bank_mask:0xf
	global_load_dwordx4 v[196:199], v7, s[48:49]
	s_nop 0
	v_add_f32_dpp v126, v126, v126 quad_perm:[2,3,0,1] row_mask:0xf bank_mask:0xf
	global_load_dwordx2 v[200:201], v7, s[48:49] offset:16
	s_nop 0
	v_add_f32_dpp v126, v126, v126 row_half_mirror row_mask:0xf bank_mask:0xf
	v_cndmask_b32_e64 v12, v12, v126, s[72:73]
	s_waitcnt vmcnt(45)
	v_cvt_scalef32_pk32_f32_fp6 v[128:159], v[202:207], 1.0
	v_pk_mul_f32 v[116:117], v[128:129], v[80:81]
	v_pk_mul_f32 v[118:119], v[130:131], v[82:83]
	v_pk_mul_f32 v[120:121], v[132:133], v[84:85]
	v_pk_mul_f32 v[122:123], v[134:135], v[86:87]
	v_pk_fma_f32 v[116:117], v[136:137], v[88:89], v[116:117]
	v_pk_fma_f32 v[118:119], v[138:139], v[90:91], v[118:119]
	v_pk_fma_f32 v[120:121], v[140:141], v[92:93], v[120:121]
	v_pk_fma_f32 v[122:123], v[142:143], v[94:95], v[122:123]
	v_pk_fma_f32 v[116:117], v[144:145], v[96:97], v[116:117]
	v_pk_fma_f32 v[118:119], v[146:147], v[98:99], v[118:119]
	v_pk_fma_f32 v[120:121], v[148:149], v[100:101], v[120:121]
	v_pk_fma_f32 v[122:123], v[150:151], v[102:103], v[122:123]
	v_pk_fma_f32 v[116:117], v[152:153], v[104:105], v[116:117]
	v_pk_fma_f32 v[118:119], v[154:155], v[106:107], v[118:119]
	v_pk_fma_f32 v[120:121], v[156:157], v[108:109], v[120:121]
	v_pk_fma_f32 v[122:123], v[158:159], v[110:111], v[122:123]
	v_pk_add_f32 v[116:117], v[116:117], v[118:119]
	v_pk_add_f32 v[120:121], v[120:121], v[122:123]
	v_pk_add_f32 v[116:117], v[116:117], v[120:121]
	v_add_f32_e32 v126, v116, v117
	v_mad_u32_u24 v8, v39, s19, v1
	s_nop 0
	v_add_f32_dpp v126, v126, v126 quad_perm:[1,0,3,2] row_mask:0xf bank_mask:0xf
	global_load_dwordx4 v[202:205], v8, s[48:49]
	s_nop 0
	v_add_f32_dpp v126, v126, v126 quad_perm:[2,3,0,1] row_mask:0xf bank_mask:0xf
	global_load_dwordx2 v[206:207], v8, s[48:49] offset:16
	s_nop 0
	v_add_f32_dpp v126, v126, v126 row_half_mirror row_mask:0xf bank_mask:0xf
	v_cndmask_b32_e64 v12, v12, v126, s[74:75]
	s_waitcnt vmcnt(45)
	v_cvt_scalef32_pk32_f32_fp6 v[128:159], v[208:213], 1.0
	v_pk_mul_f32 v[116:117], v[128:129], v[80:81]
	v_pk_mul_f32 v[118:119], v[130:131], v[82:83]
	v_pk_mul_f32 v[120:121], v[132:133], v[84:85]
	v_pk_mul_f32 v[122:123], v[134:135], v[86:87]
	v_pk_fma_f32 v[116:117], v[136:137], v[88:89], v[116:117]
	v_pk_fma_f32 v[118:119], v[138:139], v[90:91], v[118:119]
	v_pk_fma_f32 v[120:121], v[140:141], v[92:93], v[120:121]
	v_pk_fma_f32 v[122:123], v[142:143], v[94:95], v[122:123]
	v_pk_fma_f32 v[116:117], v[144:145], v[96:97], v[116:117]
	v_pk_fma_f32 v[118:119], v[146:147], v[98:99], v[118:119]
	v_pk_fma_f32 v[120:121], v[148:149], v[100:101], v[120:121]
	v_pk_fma_f32 v[122:123], v[150:151], v[102:103], v[122:123]
	v_pk_fma_f32 v[116:117], v[152:153], v[104:105], v[116:117]
	v_pk_fma_f32 v[118:119], v[154:155], v[106:107], v[118:119]
	v_pk_fma_f32 v[120:121], v[156:157], v[108:109], v[120:121]
	v_pk_fma_f32 v[122:123], v[158:159], v[110:111], v[122:123]
	v_pk_add_f32 v[116:117], v[116:117], v[118:119]
	v_pk_add_f32 v[120:121], v[120:121], v[122:123]
	v_pk_add_f32 v[116:117], v[116:117], v[120:121]
	v_add_f32_e32 v126, v116, v117
	v_mad_u32_u24 v7, v40, s19, v1
	s_nop 0
	v_add_f32_dpp v126, v126, v126 quad_perm:[1,0,3,2] row_mask:0xf bank_mask:0xf
	global_load_dwordx4 v[208:211], v7, s[48:49]
	s_nop 0
	v_add_f32_dpp v126, v126, v126 quad_perm:[2,3,0,1] row_mask:0xf bank_mask:0xf
	global_load_dwordx2 v[212:213], v7, s[48:49] offset:16
	s_nop 0
	v_add_f32_dpp v126, v126, v126 row_half_mirror row_mask:0xf bank_mask:0xf
	v_cndmask_b32_e64 v15, v15, v126, s[60:61]
	s_waitcnt vmcnt(45)
	v_cvt_scalef32_pk32_f32_fp6 v[128:159], v[214:219], 1.0
	v_pk_mul_f32 v[116:117], v[128:129], v[80:81]
	v_pk_mul_f32 v[118:119], v[130:131], v[82:83]
	v_pk_mul_f32 v[120:121], v[132:133], v[84:85]
	v_pk_mul_f32 v[122:123], v[134:135], v[86:87]
	v_pk_fma_f32 v[116:117], v[136:137], v[88:89], v[116:117]
	v_pk_fma_f32 v[118:119], v[138:139], v[90:91], v[118:119]
	v_pk_fma_f32 v[120:121], v[140:141], v[92:93], v[120:121]
	v_pk_fma_f32 v[122:123], v[142:143], v[94:95], v[122:123]
	v_pk_fma_f32 v[116:117], v[144:145], v[96:97], v[116:117]
	v_pk_fma_f32 v[118:119], v[146:147], v[98:99], v[118:119]
	v_pk_fma_f32 v[120:121], v[148:149], v[100:101], v[120:121]
	v_pk_fma_f32 v[122:123], v[150:151], v[102:103], v[122:123]
	v_pk_fma_f32 v[116:117], v[152:153], v[104:105], v[116:117]
	v_pk_fma_f32 v[118:119], v[154:155], v[106:107], v[118:119]
	v_pk_fma_f32 v[120:121], v[156:157], v[108:109], v[120:121]
	v_pk_fma_f32 v[122:123], v[158:159], v[110:111], v[122:123]
	v_pk_add_f32 v[116:117], v[116:117], v[118:119]
	v_pk_add_f32 v[120:121], v[120:121], v[122:123]
	v_pk_add_f32 v[116:117], v[116:117], v[120:121]
	v_add_f32_e32 v126, v116, v117
	v_mad_u32_u24 v8, v41, s19, v1
	s_nop 0
	v_add_f32_dpp v126, v126, v126 quad_perm:[1,0,3,2] row_mask:0xf bank_mask:0xf
	global_load_dwordx4 v[214:217], v8, s[48:49]
	s_nop 0
	v_add_f32_dpp v126, v126, v126 quad_perm:[2,3,0,1] row_mask:0xf bank_mask:0xf
	global_load_dwordx2 v[218:219], v8, s[48:49] offset:16
	s_nop 0
	v_add_f32_dpp v126, v126, v126 row_half_mirror row_mask:0xf bank_mask:0xf
	v_cndmask_b32_e64 v15, v15, v126, s[62:63]
	s_waitcnt vmcnt(45)
	v_cvt_scalef32_pk32_f32_fp6 v[128:159], v[220:225], 1.0
	v_pk_mul_f32 v[116:117], v[128:129], v[80:81]
	v_pk_mul_f32 v[118:119], v[130:131], v[82:83]
	v_pk_mul_f32 v[120:121], v[132:133], v[84:85]
	v_pk_mul_f32 v[122:123], v[134:135], v[86:87]
	v_pk_fma_f32 v[116:117], v[136:137], v[88:89], v[116:117]
	v_pk_fma_f32 v[118:119], v[138:139], v[90:91], v[118:119]
	v_pk_fma_f32 v[120:121], v[140:141], v[92:93], v[120:121]
	v_pk_fma_f32 v[122:123], v[142:143], v[94:95], v[122:123]
	v_pk_fma_f32 v[116:117], v[144:145], v[96:97], v[116:117]
	v_pk_fma_f32 v[118:119], v[146:147], v[98:99], v[118:119]
	v_pk_fma_f32 v[120:121], v[148:149], v[100:101], v[120:121]
	v_pk_fma_f32 v[122:123], v[150:151], v[102:103], v[122:123]
	v_pk_fma_f32 v[116:117], v[152:153], v[104:105], v[116:117]
	v_pk_fma_f32 v[118:119], v[154:155], v[106:107], v[118:119]
	v_pk_fma_f32 v[120:121], v[156:157], v[108:109], v[120:121]
	v_pk_fma_f32 v[122:123], v[158:159], v[110:111], v[122:123]
	v_pk_add_f32 v[116:117], v[116:117], v[118:119]
	v_pk_add_f32 v[120:121], v[120:121], v[122:123]
	v_pk_add_f32 v[116:117], v[116:117], v[120:121]
	v_add_f32_e32 v126, v116, v117
	v_mad_u32_u24 v7, v42, s19, v1
	s_nop 0
	v_add_f32_dpp v126, v126, v126 quad_perm:[1,0,3,2] row_mask:0xf bank_mask:0xf
	global_load_dwordx4 v[220:223], v7, s[48:49]
	s_nop 0
	v_add_f32_dpp v126, v126, v126 quad_perm:[2,3,0,1] row_mask:0xf bank_mask:0xf
	global_load_dwordx2 v[224:225], v7, s[48:49] offset:16
	s_nop 0
	v_add_f32_dpp v126, v126, v126 row_half_mirror row_mask:0xf bank_mask:0xf
	v_cndmask_b32_e64 v15, v15, v126, s[64:65]
	s_waitcnt vmcnt(45)
	v_cvt_scalef32_pk32_f32_fp6 v[128:159], v[226:231], 1.0
	v_pk_mul_f32 v[116:117], v[128:129], v[80:81]
	v_pk_mul_f32 v[118:119], v[130:131], v[82:83]
	v_pk_mul_f32 v[120:121], v[132:133], v[84:85]
	v_pk_mul_f32 v[122:123], v[134:135], v[86:87]
	v_pk_fma_f32 v[116:117], v[136:137], v[88:89], v[116:117]
	v_pk_fma_f32 v[118:119], v[138:139], v[90:91], v[118:119]
	v_pk_fma_f32 v[120:121], v[140:141], v[92:93], v[120:121]
	v_pk_fma_f32 v[122:123], v[142:143], v[94:95], v[122:123]
	v_pk_fma_f32 v[116:117], v[144:145], v[96:97], v[116:117]
	v_pk_fma_f32 v[118:119], v[146:147], v[98:99], v[118:119]
	v_pk_fma_f32 v[120:121], v[148:149], v[100:101], v[120:121]
	v_pk_fma_f32 v[122:123], v[150:151], v[102:103], v[122:123]
	v_pk_fma_f32 v[116:117], v[152:153], v[104:105], v[116:117]
	v_pk_fma_f32 v[118:119], v[154:155], v[106:107], v[118:119]
	v_pk_fma_f32 v[120:121], v[156:157], v[108:109], v[120:121]
	v_pk_fma_f32 v[122:123], v[158:159], v[110:111], v[122:123]
	v_pk_add_f32 v[116:117], v[116:117], v[118:119]
	v_pk_add_f32 v[120:121], v[120:121], v[122:123]
	v_pk_add_f32 v[116:117], v[116:117], v[120:121]
	v_add_f32_e32 v126, v116, v117
	v_mad_u32_u24 v8, v43, s19, v1
	s_nop 0
	v_add_f32_dpp v126, v126, v126 quad_perm:[1,0,3,2] row_mask:0xf bank_mask:0xf
	global_load_dwordx4 v[226:229], v8, s[48:49]
	s_nop 0
	v_add_f32_dpp v126, v126, v126 quad_perm:[2,3,0,1] row_mask:0xf bank_mask:0xf
	global_load_dwordx2 v[230:231], v8, s[48:49] offset:16
	s_nop 0
	v_add_f32_dpp v126, v126, v126 row_half_mirror row_mask:0xf bank_mask:0xf
	v_cndmask_b32_e64 v15, v15, v126, s[66:67]
	s_waitcnt vmcnt(45)
	v_cvt_scalef32_pk32_f32_fp6 v[128:159], v[232:237], 1.0
	v_pk_mul_f32 v[116:117], v[128:129], v[80:81]
	v_pk_mul_f32 v[118:119], v[130:131], v[82:83]
	v_pk_mul_f32 v[120:121], v[132:133], v[84:85]
	v_pk_mul_f32 v[122:123], v[134:135], v[86:87]
	v_pk_fma_f32 v[116:117], v[136:137], v[88:89], v[116:117]
	v_pk_fma_f32 v[118:119], v[138:139], v[90:91], v[118:119]
	v_pk_fma_f32 v[120:121], v[140:141], v[92:93], v[120:121]
	v_pk_fma_f32 v[122:123], v[142:143], v[94:95], v[122:123]
	v_pk_fma_f32 v[116:117], v[144:145], v[96:97], v[116:117]
	v_pk_fma_f32 v[118:119], v[146:147], v[98:99], v[118:119]
	v_pk_fma_f32 v[120:121], v[148:149], v[100:101], v[120:121]
	v_pk_fma_f32 v[122:123], v[150:151], v[102:103], v[122:123]
	v_pk_fma_f32 v[116:117], v[152:153], v[104:105], v[116:117]
	v_pk_fma_f32 v[118:119], v[154:155], v[106:107], v[118:119]
	v_pk_fma_f32 v[120:121], v[156:157], v[108:109], v[120:121]
	v_pk_fma_f32 v[122:123], v[158:159], v[110:111], v[122:123]
	v_pk_add_f32 v[116:117], v[116:117], v[118:119]
	v_pk_add_f32 v[120:121], v[120:121], v[122:123]
	v_pk_add_f32 v[116:117], v[116:117], v[120:121]
	v_add_f32_e32 v126, v116, v117
	v_mad_u32_u24 v7, v44, s19, v1
	s_nop 0
	v_add_f32_dpp v126, v126, v126 quad_perm:[1,0,3,2] row_mask:0xf bank_mask:0xf
	global_load_dwordx4 v[232:235], v7, s[48:49]
	s_nop 0
	v_add_f32_dpp v126, v126, v126 quad_perm:[2,3,0,1] row_mask:0xf bank_mask:0xf
	global_load_dwordx2 v[236:237], v7, s[48:49] offset:16
	s_nop 0
	v_add_f32_dpp v126, v126, v126 row_half_mirror row_mask:0xf bank_mask:0xf
	v_cndmask_b32_e64 v15, v15, v126, s[68:69]
	s_waitcnt vmcnt(45)
	v_cvt_scalef32_pk32_f32_fp6 v[128:159], v[238:243], 1.0
	v_pk_mul_f32 v[116:117], v[128:129], v[80:81]
	v_pk_mul_f32 v[118:119], v[130:131], v[82:83]
	v_pk_mul_f32 v[120:121], v[132:133], v[84:85]
	v_pk_mul_f32 v[122:123], v[134:135], v[86:87]
	v_pk_fma_f32 v[116:117], v[136:137], v[88:89], v[116:117]
	v_pk_fma_f32 v[118:119], v[138:139], v[90:91], v[118:119]
	v_pk_fma_f32 v[120:121], v[140:141], v[92:93], v[120:121]
	v_pk_fma_f32 v[122:123], v[142:143], v[94:95], v[122:123]
	v_pk_fma_f32 v[116:117], v[144:145], v[96:97], v[116:117]
	v_pk_fma_f32 v[118:119], v[146:147], v[98:99], v[118:119]
	v_pk_fma_f32 v[120:121], v[148:149], v[100:101], v[120:121]
	v_pk_fma_f32 v[122:123], v[150:151], v[102:103], v[122:123]
	v_pk_fma_f32 v[116:117], v[152:153], v[104:105], v[116:117]
	v_pk_fma_f32 v[118:119], v[154:155], v[106:107], v[118:119]
	v_pk_fma_f32 v[120:121], v[156:157], v[108:109], v[120:121]
	v_pk_fma_f32 v[122:123], v[158:159], v[110:111], v[122:123]
	v_pk_add_f32 v[116:117], v[116:117], v[118:119]
	v_pk_add_f32 v[120:121], v[120:121], v[122:123]
	v_pk_add_f32 v[116:117], v[116:117], v[120:121]
	v_add_f32_e32 v126, v116, v117
	v_mad_u32_u24 v8, v45, s19, v1
	s_nop 0
	v_add_f32_dpp v126, v126, v126 quad_perm:[1,0,3,2] row_mask:0xf bank_mask:0xf
	global_load_dwordx4 v[238:241], v8, s[48:49]
	s_nop 0
	v_add_f32_dpp v126, v126, v126 quad_perm:[2,3,0,1] row_mask:0xf bank_mask:0xf
	global_load_dwordx2 v[242:243], v8, s[48:49] offset:16
	s_nop 0
	v_add_f32_dpp v126, v126, v126 row_half_mirror row_mask:0xf bank_mask:0xf
	v_cndmask_b32_e64 v15, v15, v126, s[70:71]
	s_waitcnt vmcnt(45)
	v_cvt_scalef32_pk32_f32_fp6 v[128:159], v[244:249], 1.0
	v_pk_mul_f32 v[116:117], v[128:129], v[80:81]
	v_pk_mul_f32 v[118:119], v[130:131], v[82:83]
	v_pk_mul_f32 v[120:121], v[132:133], v[84:85]
	v_pk_mul_f32 v[122:123], v[134:135], v[86:87]
	v_pk_fma_f32 v[116:117], v[136:137], v[88:89], v[116:117]
	v_pk_fma_f32 v[118:119], v[138:139], v[90:91], v[118:119]
	v_pk_fma_f32 v[120:121], v[140:141], v[92:93], v[120:121]
	v_pk_fma_f32 v[122:123], v[142:143], v[94:95], v[122:123]
	v_pk_fma_f32 v[116:117], v[144:145], v[96:97], v[116:117]
	v_pk_fma_f32 v[118:119], v[146:147], v[98:99], v[118:119]
	v_pk_fma_f32 v[120:121], v[148:149], v[100:101], v[120:121]
	v_pk_fma_f32 v[122:123], v[150:151], v[102:103], v[122:123]
	v_pk_fma_f32 v[116:117], v[152:153], v[104:105], v[116:117]
	v_pk_fma_f32 v[118:119], v[154:155], v[106:107], v[118:119]
	v_pk_fma_f32 v[120:121], v[156:157], v[108:109], v[120:121]
	v_pk_fma_f32 v[122:123], v[158:159], v[110:111], v[122:123]
	v_pk_add_f32 v[116:117], v[116:117], v[118:119]
	v_pk_add_f32 v[120:121], v[120:121], v[122:123]
	v_pk_add_f32 v[116:117], v[116:117], v[120:121]
	v_add_f32_e32 v126, v116, v117
	v_mad_u32_u24 v7, v46, s19, v1
	s_nop 0
	v_add_f32_dpp v126, v126, v126 quad_perm:[1,0,3,2] row_mask:0xf bank_mask:0xf
	global_load_dwordx4 v[244:247], v7, s[48:49]
	s_nop 0
	v_add_f32_dpp v126, v126, v126 quad_perm:[2,3,0,1] row_mask:0xf bank_mask:0xf
	global_load_dwordx2 v[248:249], v7, s[48:49] offset:16
	s_nop 0
	v_add_f32_dpp v126, v126, v126 row_half_mirror row_mask:0xf bank_mask:0xf
	v_cndmask_b32_e64 v15, v15, v126, s[72:73]
	s_waitcnt vmcnt(45)
	v_cvt_scalef32_pk32_f32_fp6 v[128:159], v[250:255], 1.0
	v_pk_mul_f32 v[116:117], v[128:129], v[80:81]
	v_pk_mul_f32 v[118:119], v[130:131], v[82:83]
	v_pk_mul_f32 v[120:121], v[132:133], v[84:85]
	v_pk_mul_f32 v[122:123], v[134:135], v[86:87]
	v_pk_fma_f32 v[116:117], v[136:137], v[88:89], v[116:117]
	v_pk_fma_f32 v[118:119], v[138:139], v[90:91], v[118:119]
	v_pk_fma_f32 v[120:121], v[140:141], v[92:93], v[120:121]
	v_pk_fma_f32 v[122:123], v[142:143], v[94:95], v[122:123]
	v_pk_fma_f32 v[116:117], v[144:145], v[96:97], v[116:117]
	v_pk_fma_f32 v[118:119], v[146:147], v[98:99], v[118:119]
	v_pk_fma_f32 v[120:121], v[148:149], v[100:101], v[120:121]
	v_pk_fma_f32 v[122:123], v[150:151], v[102:103], v[122:123]
	v_pk_fma_f32 v[116:117], v[152:153], v[104:105], v[116:117]
	v_pk_fma_f32 v[118:119], v[154:155], v[106:107], v[118:119]
	v_pk_fma_f32 v[120:121], v[156:157], v[108:109], v[120:121]
	v_pk_fma_f32 v[122:123], v[158:159], v[110:111], v[122:123]
	v_pk_add_f32 v[116:117], v[116:117], v[118:119]
	v_pk_add_f32 v[120:121], v[120:121], v[122:123]
	v_pk_add_f32 v[116:117], v[116:117], v[120:121]
	v_add_f32_e32 v126, v116, v117
	v_mad_u32_u24 v8, v47, s19, v1
	s_nop 0
	v_add_f32_dpp v126, v126, v126 quad_perm:[1,0,3,2] row_mask:0xf bank_mask:0xf
	global_load_dwordx4 v[250:253], v8, s[48:49]
	s_nop 0
	v_add_f32_dpp v126, v126, v126 quad_perm:[2,3,0,1] row_mask:0xf bank_mask:0xf
	global_load_dwordx2 v[254:255], v8, s[48:49] offset:16
	s_nop 0
	v_add_f32_dpp v126, v126, v126 row_half_mirror row_mask:0xf bank_mask:0xf
	v_cndmask_b32_e64 v15, v15, v126, s[74:75]
	v_mul_f32_e32 v12, v12, v127
	v_mul_f32_e32 v15, v15, v127
	global_store_dword v9, v12, s[44:45]
	global_store_dword v9, v15, s[44:45] offset:32
	s_add_u32 s28, s28, 1
	s_waitcnt vmcnt(34)
	ds_read_b128 v[128:131], v124 offset:0
	ds_read_b128 v[132:135], v124 offset:16
	ds_read_b128 v[136:139], v124 offset:32
	ds_read_b128 v[140:143], v124 offset:48
	ds_read_b128 v[144:147], v124 offset:64
	ds_read_b128 v[148:151], v124 offset:80
	ds_read_b128 v[152:155], v124 offset:96
	ds_read_b128 v[156:159], v124 offset:112
	v_add_f32_e32 v126, v112, v113
	v_add_f32_e32 v127, v114, v115
	v_add_f32_e32 v126, v126, v127
	s_nop 1
	v_add_f32_dpp v126, v126, v126 quad_perm:[1,0,3,2] row_mask:0xf bank_mask:0xf
	s_nop 1
	v_add_f32_dpp v126, v126, v126 quad_perm:[2,3,0,1] row_mask:0xf bank_mask:0xf
	s_nop 1
	v_add_f32_dpp v126, v126, v126 row_half_mirror row_mask:0xf bank_mask:0xf
	s_nop 1
	v_mov_b32_e32 v127, 0x358637bd
	v_fmac_f32_e32 v127, 0x3a000000, v126
	v_rsq_f32_e32 v127, v127
	s_waitcnt lgkmcnt(0)
	v_pk_mul_f32 v[80:81], v[48:49], v[128:129]
	v_pk_mul_f32 v[82:83], v[50:51], v[130:131]
	v_pk_mul_f32 v[84:85], v[52:53], v[132:133]
	v_pk_mul_f32 v[86:87], v[54:55], v[134:135]
	v_pk_mul_f32 v[88:89], v[56:57], v[136:137]
	v_pk_mul_f32 v[90:91], v[58:59], v[138:139]
	v_pk_mul_f32 v[92:93], v[60:61], v[140:141]
	v_pk_mul_f32 v[94:95], v[62:63], v[142:143]
	v_pk_mul_f32 v[96:97], v[64:65], v[144:145]
	v_pk_mul_f32 v[98:99], v[66:67], v[146:147]
	v_pk_mul_f32 v[100:101], v[68:69], v[148:149]
	v_pk_mul_f32 v[102:103], v[70:71], v[150:151]
	v_pk_mul_f32 v[104:105], v[72:73], v[152:153]
	v_pk_mul_f32 v[106:107], v[74:75], v[154:155]
	v_pk_mul_f32 v[108:109], v[76:77], v[156:157]
	v_pk_mul_f32 v[110:111], v[78:79], v[158:159]
	s_add_u32 s40, s28, 0
	s_min_u32 s40, s40, 127
	s_lshl_b32 s40, s40, 8
	s_add_u32 s40, s40, s24
	s_lshl_b32 s29, s40, 12
	s_add_u32 s44, s50, s29
	s_addc_u32 s45, s51, 0
	s_add_u32 s40, s28, 1
	s_min_u32 s40, s40, 127
	s_lshl_b32 s40, s40, 8
	s_add_u32 s40, s40, s24
	s_lshl_b32 s29, s40, 13
	s_add_u32 s34, s10, s29
	s_addc_u32 s35, s11, 0
	global_load_dwordx4 v[48:51], v13, s[34:35] offset:0
	global_load_dwordx4 v[52:55], v13, s[34:35] offset:1024
	global_load_dwordx4 v[56:59], v13, s[34:35] offset:2048
	global_load_dwordx4 v[60:63], v13, s[34:35] offset:3072
	global_load_dwordx4 v[64:67], v14, s[34:35] offset:0
	global_load_dwordx4 v[68:71], v14, s[34:35] offset:1024
	global_load_dwordx4 v[72:75], v14, s[34:35] offset:2048
	global_load_dwordx4 v[76:79], v14, s[34:35] offset:3072
	s_lshl_b32 s29, s40, 7
	s_add_u32 s38, s54, s29
	s_addc_u32 s39, s55, 0
	global_load_dwordx4 v[112:115], v125, s[38:39]
	s_add_u32 s40, s28, 2
	s_min_u32 s40, s40, 127
	s_lshl_b32 s40, s40, 8
	s_add_u32 s40, s40, s24
	s_lshl_b32 s29, s40, 9
	s_add_u32 s30, s4, s29
	s_addc_u32 s31, s5, 0
	global_load_dwordx4 v[32:35], v2, s[30:31] offset:0
	global_load_dwordx4 v[36:39], v2, s[30:31] offset:16
	global_load_dwordx4 v[40:43], v2, s[30:31] offset:32
	global_load_dwordx4 v[44:47], v2, s[30:31] offset:48
	s_waitcnt vmcnt(45)
	v_cvt_scalef32_pk32_f32_fp6 v[128:159], v[160:165], 1.0
	v_pk_mul_f32 v[116:117], v[128:129], v[80:81]
	v_pk_mul_f32 v[118:119], v[130:131], v[82:83]
	v_pk_mul_f32 v[120:121], v[132:133], v[84:85]
	v_pk_mul_f32 v[122:123], v[134:135], v[86:87]
	v_pk_fma_f32 v[116:117], v[136:137], v[88:89], v[116:117]
	v_pk_fma_f32 v[118:119], v[138:139], v[90:91], v[118:119]
	v_pk_fma_f32 v[120:121], v[140:141], v[92:93], v[120:121]
	v_pk_fma_f32 v[122:123], v[142:143], v[94:95], v[122:123]
	v_pk_fma_f32 v[116:117], v[144:145], v[96:97], v[116:117]
	v_pk_fma_f32 v[118:119], v[146:147], v[98:99], v[118:119]
	v_pk_fma_f32 v[120:121], v[148:149], v[100:101], v[120:121]
	v_pk_fma_f32 v[122:123], v[150:151], v[102:103], v[122:123]
	v_pk_fma_f32 v[116:117], v[152:153], v[104:105], v[116:117]
	v_pk_fma_f32 v[118:119], v[154:155], v[106:107], v[118:119]
	v_pk_fma_f32 v[120:121], v[156:157], v[108:109], v[120:121]
	v_pk_fma_f32 v[122:123], v[158:159], v[110:111], v[122:123]
	v_pk_add_f32 v[116:117], v[116:117], v[118:119]
	v_pk_add_f32 v[120:121], v[120:121], v[122:123]
	v_pk_add_f32 v[116:117], v[116:117], v[120:121]
	v_add_f32_e32 v126, v116, v117
	v_mad_u32_u24 v7, v16, s19, v1
	s_nop 0
	v_add_f32_dpp v126, v126, v126 quad_perm:[1,0,3,2] row_mask:0xf bank_mask:0xf
	global_load_dwordx4 v[160:163], v7, s[48:49]
	s_nop 0
	v_add_f32_dpp v126, v126, v126 quad_perm:[2,3,0,1] row_mask:0xf bank_mask:0xf
	global_load_dwordx2 v[164:165], v7, s[48:49] offset:16
	s_nop 0
	v_add_f32_dpp v126, v126, v126 row_half_mirror row_mask:0xf bank_mask:0xf
	v_cndmask_b32_e64 v12, v12, v126, s[60:61]
	s_waitcnt vmcnt(45)
	v_cvt_scalef32_pk32_f32_fp6 v[128:159], v[166:171], 1.0
	v_pk_mul_f32 v[116:117], v[128:129], v[80:81]
	v_pk_mul_f32 v[118:119], v[130:131], v[82:83]
	v_pk_mul_f32 v[120:121], v[132:133], v[84:85]
	v_pk_mul_f32 v[122:123], v[134:135], v[86:87]
	v_pk_fma_f32 v[116:117], v[136:137], v[88:89], v[116:117]
	v_pk_fma_f32 v[118:119], v[138:139], v[90:91], v[118:119]
	v_pk_fma_f32 v[120:121], v[140:141], v[92:93], v[120:121]
	v_pk_fma_f32 v[122:123], v[142:143], v[94:95], v[122:123]
	v_pk_fma_f32 v[116:117], v[144:145], v[96:97], v[116:117]
	v_pk_fma_f32 v[118:119], v[146:147], v[98:99], v[118:119]
	v_pk_fma_f32 v[120:121], v[148:149], v[100:101], v[120:121]
	v_pk_fma_f32 v[122:123], v[150:151], v[102:103], v[122:123]
	v_pk_fma_f32 v[116:117], v[152:153], v[104:105], v[116:117]
	v_pk_fma_f32 v[118:119], v[154:155], v[106:107], v[118:119]
	v_pk_fma_f32 v[120:121], v[156:157], v[108:109], v[120:121]
	v_pk_fma_f32 v[122:123], v[158:159], v[110:111], v[122:123]
	v_pk_add_f32 v[116:117], v[116:117], v[118:119]
	v_pk_add_f32 v[120:121], v[120:121], v[122:123]
	v_pk_add_f32 v[116:117], v[116:117], v[120:121]
	v_add_f32_e32 v126, v116, v117
	v_mad_u32_u24 v8, v17, s19, v1
	s_nop 0
	v_add_f32_dpp v126, v126, v126 quad_perm:[1,0,3,2] row_mask:0xf bank_mask:0xf
	global_load_dwordx4 v[166:169], v8, s[48:49]
	s_nop 0
	v_add_f32_dpp v126, v126, v126 quad_perm:[2,3,0,1] row_mask:0xf bank_mask:0xf
	global_load_dwordx2 v[170:171], v8, s[48:49] offset:16
	s_nop 0
	v_add_f32_dpp v126, v126, v126 row_half_mirror row_mask:0xf bank_mask:0xf
	v_cndmask_b32_e64 v12, v12, v126, s[62:63]
	s_waitcnt vmcnt(45)
	v_cvt_scalef32_pk32_f32_fp6 v[128:159], v[172:177], 1.0
	v_pk_mul_f32 v[116:117], v[128:129], v[80:81]
	v_pk_mul_f32 v[118:119], v[130:131], v[82:83]
	v_pk_mul_f32 v[120:121], v[132:133], v[84:85]
	v_pk_mul_f32 v[122:123], v[134:135], v[86:87]
	v_pk_fma_f32 v[116:117], v[136:137], v[88:89], v[116:117]
	v_pk_fma_f32 v[118:119], v[138:139], v[90:91], v[118:119]
	v_pk_fma_f32 v[120:121], v[140:141], v[92:93], v[120:121]
	v_pk_fma_f32 v[122:123], v[142:143], v[94:95], v[122:123]
	v_pk_fma_f32 v[116:117], v[144:145], v[96:97], v[116:117]
	v_pk_fma_f32 v[118:119], v[146:147], v[98:99], v[118:119]
	v_pk_fma_f32 v[120:121], v[148:149], v[100:101], v[120:121]
	v_pk_fma_f32 v[122:123], v[150:151], v[102:103], v[122:123]
	v_pk_fma_f32 v[116:117], v[152:153], v[104:105], v[116:117]
	v_pk_fma_f32 v[118:119], v[154:155], v[106:107], v[118:119]
	v_pk_fma_f32 v[120:121], v[156:157], v[108:109], v[120:121]
	v_pk_fma_f32 v[122:123], v[158:159], v[110:111], v[122:123]
	v_pk_add_f32 v[116:117], v[116:117], v[118:119]
	v_pk_add_f32 v[120:121], v[120:121], v[122:123]
	v_pk_add_f32 v[116:117], v[116:117], v[120:121]
	v_add_f32_e32 v126, v116, v117
	v_mad_u32_u24 v7, v18, s19, v1
	s_nop 0
	v_add_f32_dpp v126, v126, v126 quad_perm:[1,0,3,2] row_mask:0xf bank_mask:0xf
	global_load_dwordx4 v[172:175], v7, s[48:49]
	s_nop 0
	v_add_f32_dpp v126, v126, v126 quad_perm:[2,3,0,1] row_mask:0xf bank_mask:0xf
	global_load_dwordx2 v[176:177], v7, s[48:49] offset:16
	s_nop 0
	v_add_f32_dpp v126, v126, v126 row_half_mirror row_mask:0xf bank_mask:0xf
	v_cndmask_b32_e64 v12, v12, v126, s[64:65]
	s_waitcnt vmcnt(45)
	v_cvt_scalef32_pk32_f32_fp6 v[128:159], v[178:183], 1.0
	v_pk_mul_f32 v[116:117], v[128:129], v[80:81]
	v_pk_mul_f32 v[118:119], v[130:131], v[82:83]
	v_pk_mul_f32 v[120:121], v[132:133], v[84:85]
	v_pk_mul_f32 v[122:123], v[134:135], v[86:87]
	v_pk_fma_f32 v[116:117], v[136:137], v[88:89], v[116:117]
	v_pk_fma_f32 v[118:119], v[138:139], v[90:91], v[118:119]
	v_pk_fma_f32 v[120:121], v[140:141], v[92:93], v[120:121]
	v_pk_fma_f32 v[122:123], v[142:143], v[94:95], v[122:123]
	v_pk_fma_f32 v[116:117], v[144:145], v[96:97], v[116:117]
	v_pk_fma_f32 v[118:119], v[146:147], v[98:99], v[118:119]
	v_pk_fma_f32 v[120:121], v[148:149], v[100:101], v[120:121]
	v_pk_fma_f32 v[122:123], v[150:151], v[102:103], v[122:123]
	v_pk_fma_f32 v[116:117], v[152:153], v[104:105], v[116:117]
	v_pk_fma_f32 v[118:119], v[154:155], v[106:107], v[118:119]
	v_pk_fma_f32 v[120:121], v[156:157], v[108:109], v[120:121]
	v_pk_fma_f32 v[122:123], v[158:159], v[110:111], v[122:123]
	v_pk_add_f32 v[116:117], v[116:117], v[118:119]
	v_pk_add_f32 v[120:121], v[120:121], v[122:123]
	v_pk_add_f32 v[116:117], v[116:117], v[120:121]
	v_add_f32_e32 v126, v116, v117
	v_mad_u32_u24 v8, v19, s19, v1
	s_nop 0
	v_add_f32_dpp v126, v126, v126 quad_perm:[1,0,3,2] row_mask:0xf bank_mask:0xf
	global_load_dwordx4 v[178:181], v8, s[48:49]
	s_nop 0
	v_add_f32_dpp v126, v126, v126 quad_perm:[2,3,0,1] row_mask:0xf bank_mask:0xf
	global_load_dwordx2 v[182:183], v8, s[48:49] offset:16
	s_nop 0
	v_add_f32_dpp v126, v126, v126 row_half_mirror row_mask:0xf bank_mask:0xf
	v_cndmask_b32_e64 v12, v12, v126, s[66:67]
	s_waitcnt vmcnt(45)
	v_cvt_scalef32_pk32_f32_fp6 v[128:159], v[184:189], 1.0
	v_pk_mul_f32 v[116:117], v[128:129], v[80:81]
	v_pk_mul_f32 v[118:119], v[130:131], v[82:83]
	v_pk_mul_f32 v[120:121], v[132:133], v[84:85]
	v_pk_mul_f32 v[122:123], v[134:135], v[86:87]
	v_pk_fma_f32 v[116:117], v[136:137], v[88:89], v[116:117]
	v_pk_fma_f32 v[118:119], v[138:139], v[90:91], v[118:119]
	v_pk_fma_f32 v[120:121], v[140:141], v[92:93], v[120:121]
	v_pk_fma_f32 v[122:123], v[142:143], v[94:95], v[122:123]
	v_pk_fma_f32 v[116:117], v[144:145], v[96:97], v[116:117]
	v_pk_fma_f32 v[118:119], v[146:147], v[98:99], v[118:119]
	v_pk_fma_f32 v[120:121], v[148:149], v[100:101], v[120:121]
	v_pk_fma_f32 v[122:123], v[150:151], v[102:103], v[122:123]
	v_pk_fma_f32 v[116:117], v[152:153], v[104:105], v[116:117]
	v_pk_fma_f32 v[118:119], v[154:155], v[106:107], v[118:119]
	v_pk_fma_f32 v[120:121], v[156:157], v[108:109], v[120:121]
	v_pk_fma_f32 v[122:123], v[158:159], v[110:111], v[122:123]
	v_pk_add_f32 v[116:117], v[116:117], v[118:119]
	v_pk_add_f32 v[120:121], v[120:121], v[122:123]
	v_pk_add_f32 v[116:117], v[116:117], v[120:121]
	v_add_f32_e32 v126, v116, v117
	v_mad_u32_u24 v7, v20, s19, v1
	s_nop 0
	v_add_f32_dpp v126, v126, v126 quad_perm:[1,0,3,2] row_mask:0xf bank_mask:0xf
	global_load_dwordx4 v[184:187], v7, s[48:49]
	s_nop 0
	v_add_f32_dpp v126, v126, v126 quad_perm:[2,3,0,1] row_mask:0xf bank_mask:0xf
	global_load_dwordx2 v[188:189], v7, s[48:49] offset:16
	s_nop 0
	v_add_f32_dpp v126, v126, v126 row_half_mirror row_mask:0xf bank_mask:0xf
	v_cndmask_b32_e64 v12, v12, v126, s[68:69]
	s_waitcnt vmcnt(45)
	v_cvt_scalef32_pk32_f32_fp6 v[128:159], v[190:195], 1.0
	v_pk_mul_f32 v[116:117], v[128:129], v[80:81]
	v_pk_mul_f32 v[118:119], v[130:131], v[82:83]
	v_pk_mul_f32 v[120:121], v[132:133], v[84:85]
	v_pk_mul_f32 v[122:123], v[134:135], v[86:87]
	v_pk_fma_f32 v[116:117], v[136:137], v[88:89], v[116:117]
	v_pk_fma_f32 v[118:119], v[138:139], v[90:91], v[118:119]
	v_pk_fma_f32 v[120:121], v[140:141], v[92:93], v[120:121]
	v_pk_fma_f32 v[122:123], v[142:143], v[94:95], v[122:123]
	v_pk_fma_f32 v[116:117], v[144:145], v[96:97], v[116:117]
	v_pk_fma_f32 v[118:119], v[146:147], v[98:99], v[118:119]
	v_pk_fma_f32 v[120:121], v[148:149], v[100:101], v[120:121]
	v_pk_fma_f32 v[122:123], v[150:151], v[102:103], v[122:123]
	v_pk_fma_f32 v[116:117], v[152:153], v[104:105], v[116:117]
	v_pk_fma_f32 v[118:119], v[154:155], v[106:107], v[118:119]
	v_pk_fma_f32 v[120:121], v[156:157], v[108:109], v[120:121]
	v_pk_fma_f32 v[122:123], v[158:159], v[110:111], v[122:123]
	v_pk_add_f32 v[116:117], v[116:117], v[118:119]
	v_pk_add_f32 v[120:121], v[120:121], v[122:123]
	v_pk_add_f32 v[116:117], v[116:117], v[120:121]
	v_add_f32_e32 v126, v116, v117
	v_mad_u32_u24 v8, v21, s19, v1
	s_nop 0
	v_add_f32_dpp v126, v126, v126 quad_perm:[1,0,3,2] row_mask:0xf bank_mask:0xf
	global_load_dwordx4 v[190:193], v8, s[48:49]
	s_nop 0
	v_add_f32_dpp v126, v126, v126 quad_perm:[2,3,0,1] row_mask:0xf bank_mask:0xf
	global_load_dwordx2 v[194:195], v8, s[48:49] offset:16
	s_nop 0
	v_add_f32_dpp v126, v126, v126 row_half_mirror row_mask:0xf bank_mask:0xf
	v_cndmask_b32_e64 v12, v12, v126, s[70:71]
	s_waitcnt vmcnt(45)
	v_cvt_scalef32_pk32_f32_fp6 v[128:159], v[196:201], 1.0
	v_pk_mul_f32 v[116:117], v[128:129], v[80:81]
	v_pk_mul_f32 v[118:119], v[130:131], v[82:83]
	v_pk_mul_f32 v[120:121], v[132:133], v[84:85]
	v_pk_mul_f32 v[122:123], v[134:135], v[86:87]
	v_pk_fma_f32 v[116:117], v[136:137], v[88:89], v[116:117]
	v_pk_fma_f32 v[118:119], v[138:139], v[90:91], v[118:119]
	v_pk_fma_f32 v[120:121], v[140:141], v[92:93], v[120:121]
	v_pk_fma_f32 v[122:123], v[142:143], v[94:95], v[122:123]
	v_pk_fma_f32 v[116:117], v[144:145], v[96:97], v[116:117]
	v_pk_fma_f32 v[118:119], v[146:147], v[98:99], v[118:119]
	v_pk_fma_f32 v[120:121], v[148:149], v[100:101], v[120:121]
	v_pk_fma_f32 v[122:123], v[150:151], v[102:103], v[122:123]
	v_pk_fma_f32 v[116:117], v[152:153], v[104:105], v[116:117]
	v_pk_fma_f32 v[118:119], v[154:155], v[106:107], v[118:119]
	v_pk_fma_f32 v[120:121], v[156:157], v[108:109], v[120:121]
	v_pk_fma_f32 v[122:123], v[158:159], v[110:111], v[122:123]
	v_pk_add_f32 v[116:117], v[116:117], v[118:119]
	v_pk_add_f32 v[120:121], v[120:121], v[122:123]
	v_pk_add_f32 v[116:117], v[116:117], v[120:121]
	v_add_f32_e32 v126, v116, v117
	v_mad_u32_u24 v7, v22, s19, v1
	s_nop 0
	v_add_f32_dpp v126, v126, v126 quad_perm:[1,0,3,2] row_mask:0xf bank_mask:0xf
	global_load_dwordx4 v[196:199], v7, s[48:49]
	s_nop 0
	v_add_f32_dpp v126, v126, v126 quad_perm:[2,3,0,1] row_mask:0xf bank_mask:0xf
	global_load_dwordx2 v[200:201], v7, s[48:49] offset:16
	s_nop 0
	v_add_f32_dpp v126, v126, v126 row_half_mirror row_mask:0xf bank_mask:0xf
	v_cndmask_b32_e64 v12, v12, v126, s[72:73]
	s_waitcnt vmcnt(45)
	v_cvt_scalef32_pk32_f32_fp6 v[128:159], v[202:207], 1.0
	v_pk_mul_f32 v[116:117], v[128:129], v[80:81]
	v_pk_mul_f32 v[118:119], v[130:131], v[82:83]
	v_pk_mul_f32 v[120:121], v[132:133], v[84:85]
	v_pk_mul_f32 v[122:123], v[134:135], v[86:87]
	v_pk_fma_f32 v[116:117], v[136:137], v[88:89], v[116:117]
	v_pk_fma_f32 v[118:119], v[138:139], v[90:91], v[118:119]
	v_pk_fma_f32 v[120:121], v[140:141], v[92:93], v[120:121]
	v_pk_fma_f32 v[122:123], v[142:143], v[94:95], v[122:123]
	v_pk_fma_f32 v[116:117], v[144:145], v[96:97], v[116:117]
	v_pk_fma_f32 v[118:119], v[146:147], v[98:99], v[118:119]
	v_pk_fma_f32 v[120:121], v[148:149], v[100:101], v[120:121]
	v_pk_fma_f32 v[122:123], v[150:151], v[102:103], v[122:123]
	v_pk_fma_f32 v[116:117], v[152:153], v[104:105], v[116:117]
	v_pk_fma_f32 v[118:119], v[154:155], v[106:107], v[118:119]
	v_pk_fma_f32 v[120:121], v[156:157], v[108:109], v[120:121]
	v_pk_fma_f32 v[122:123], v[158:159], v[110:111], v[122:123]
	v_pk_add_f32 v[116:117], v[116:117], v[118:119]
	v_pk_add_f32 v[120:121], v[120:121], v[122:123]
	v_pk_add_f32 v[116:117], v[116:117], v[120:121]
	v_add_f32_e32 v126, v116, v117
	v_mad_u32_u24 v8, v23, s19, v1
	s_nop 0
	v_add_f32_dpp v126, v126, v126 quad_perm:[1,0,3,2] row_mask:0xf bank_mask:0xf
	global_load_dwordx4 v[202:205], v8, s[48:49]
	s_nop 0
	v_add_f32_dpp v126, v126, v126 quad_perm:[2,3,0,1] row_mask:0xf bank_mask:0xf
	global_load_dwordx2 v[206:207], v8, s[48:49] offset:16
	s_nop 0
	v_add_f32_dpp v126, v126, v126 row_half_mirror row_mask:0xf bank_mask:0xf
	v_cndmask_b32_e64 v12, v12, v126, s[74:75]
	s_waitcnt vmcnt(45)
	v_cvt_scalef32_pk32_f32_fp6 v[128:159], v[208:213], 1.0
	v_pk_mul_f32 v[116:117], v[128:129], v[80:81]
	v_pk_mul_f32 v[118:119], v[130:131], v[82:83]
	v_pk_mul_f32 v[120:121], v[132:133], v[84:85]
	v_pk_mul_f32 v[122:123], v[134:135], v[86:87]
	v_pk_fma_f32 v[116:117], v[136:137], v[88:89], v[116:117]
	v_pk_fma_f32 v[118:119], v[138:139], v[90:91], v[118:119]
	v_pk_fma_f32 v[120:121], v[140:141], v[92:93], v[120:121]
	v_pk_fma_f32 v[122:123], v[142:143], v[94:95], v[122:123]
	v_pk_fma_f32 v[116:117], v[144:145], v[96:97], v[116:117]
	v_pk_fma_f32 v[118:119], v[146:147], v[98:99], v[118:119]
	v_pk_fma_f32 v[120:121], v[148:149], v[100:101], v[120:121]
	v_pk_fma_f32 v[122:123], v[150:151], v[102:103], v[122:123]
	v_pk_fma_f32 v[116:117], v[152:153], v[104:105], v[116:117]
	v_pk_fma_f32 v[118:119], v[154:155], v[106:107], v[118:119]
	v_pk_fma_f32 v[120:121], v[156:157], v[108:109], v[120:121]
	v_pk_fma_f32 v[122:123], v[158:159], v[110:111], v[122:123]
	v_pk_add_f32 v[116:117], v[116:117], v[118:119]
	v_pk_add_f32 v[120:121], v[120:121], v[122:123]
	v_pk_add_f32 v[116:117], v[116:117], v[120:121]
	v_add_f32_e32 v126, v116, v117
	v_mad_u32_u24 v7, v24, s19, v1
	s_nop 0
	v_add_f32_dpp v126, v126, v126 quad_perm:[1,0,3,2] row_mask:0xf bank_mask:0xf
	global_load_dwordx4 v[208:211], v7, s[48:49]
	s_nop 0
	v_add_f32_dpp v126, v126, v126 quad_perm:[2,3,0,1] row_mask:0xf bank_mask:0xf
	global_load_dwordx2 v[212:213], v7, s[48:49] offset:16
	s_nop 0
	v_add_f32_dpp v126, v126, v126 row_half_mirror row_mask:0xf bank_mask:0xf
	v_cndmask_b32_e64 v15, v15, v126, s[60:61]
	s_waitcnt vmcnt(45)
	v_cvt_scalef32_pk32_f32_fp6 v[128:159], v[214:219], 1.0
	v_pk_mul_f32 v[116:117], v[128:129], v[80:81]
	v_pk_mul_f32 v[118:119], v[130:131], v[82:83]
	v_pk_mul_f32 v[120:121], v[132:133], v[84:85]
	v_pk_mul_f32 v[122:123], v[134:135], v[86:87]
	v_pk_fma_f32 v[116:117], v[136:137], v[88:89], v[116:117]
	v_pk_fma_f32 v[118:119], v[138:139], v[90:91], v[118:119]
	v_pk_fma_f32 v[120:121], v[140:141], v[92:93], v[120:121]
	v_pk_fma_f32 v[122:123], v[142:143], v[94:95], v[122:123]
	v_pk_fma_f32 v[116:117], v[144:145], v[96:97], v[116:117]
	v_pk_fma_f32 v[118:119], v[146:147], v[98:99], v[118:119]
	v_pk_fma_f32 v[120:121], v[148:149], v[100:101], v[120:121]
	v_pk_fma_f32 v[122:123], v[150:151], v[102:103], v[122:123]
	v_pk_fma_f32 v[116:117], v[152:153], v[104:105], v[116:117]
	v_pk_fma_f32 v[118:119], v[154:155], v[106:107], v[118:119]
	v_pk_fma_f32 v[120:121], v[156:157], v[108:109], v[120:121]
	v_pk_fma_f32 v[122:123], v[158:159], v[110:111], v[122:123]
	v_pk_add_f32 v[116:117], v[116:117], v[118:119]
	v_pk_add_f32 v[120:121], v[120:121], v[122:123]
	v_pk_add_f32 v[116:117], v[116:117], v[120:121]
	v_add_f32_e32 v126, v116, v117
	v_mad_u32_u24 v8, v25, s19, v1
	s_nop 0
	v_add_f32_dpp v126, v126, v126 quad_perm:[1,0,3,2] row_mask:0xf bank_mask:0xf
	global_load_dwordx4 v[214:217], v8, s[48:49]
	s_nop 0
	v_add_f32_dpp v126, v126, v126 quad_perm:[2,3,0,1] row_mask:0xf bank_mask:0xf
	global_load_dwordx2 v[218:219], v8, s[48:49] offset:16
	s_nop 0
	v_add_f32_dpp v126, v126, v126 row_half_mirror row_mask:0xf bank_mask:0xf
	v_cndmask_b32_e64 v15, v15, v126, s[62:63]
	s_waitcnt vmcnt(45)
	v_cvt_scalef32_pk32_f32_fp6 v[128:159], v[220:225], 1.0
	v_pk_mul_f32 v[116:117], v[128:129], v[80:81]
	v_pk_mul_f32 v[118:119], v[130:131], v[82:83]
	v_pk_mul_f32 v[120:121], v[132:133], v[84:85]
	v_pk_mul_f32 v[122:123], v[134:135], v[86:87]
	v_pk_fma_f32 v[116:117], v[136:137], v[88:89], v[116:117]
	v_pk_fma_f32 v[118:119], v[138:139], v[90:91], v[118:119]
	v_pk_fma_f32 v[120:121], v[140:141], v[92:93], v[120:121]
	v_pk_fma_f32 v[122:123], v[142:143], v[94:95], v[122:123]
	v_pk_fma_f32 v[116:117], v[144:145], v[96:97], v[116:117]
	v_pk_fma_f32 v[118:119], v[146:147], v[98:99], v[118:119]
	v_pk_fma_f32 v[120:121], v[148:149], v[100:101], v[120:121]
	v_pk_fma_f32 v[122:123], v[150:151], v[102:103], v[122:123]
	v_pk_fma_f32 v[116:117], v[152:153], v[104:105], v[116:117]
	v_pk_fma_f32 v[118:119], v[154:155], v[106:107], v[118:119]
	v_pk_fma_f32 v[120:121], v[156:157], v[108:109], v[120:121]
	v_pk_fma_f32 v[122:123], v[158:159], v[110:111], v[122:123]
	v_pk_add_f32 v[116:117], v[116:117], v[118:119]
	v_pk_add_f32 v[120:121], v[120:121], v[122:123]
	v_pk_add_f32 v[116:117], v[116:117], v[120:121]
	v_add_f32_e32 v126, v116, v117
	v_mad_u32_u24 v7, v26, s19, v1
	s_nop 0
	v_add_f32_dpp v126, v126, v126 quad_perm:[1,0,3,2] row_mask:0xf bank_mask:0xf
	global_load_dwordx4 v[220:223], v7, s[48:49]
	s_nop 0
	v_add_f32_dpp v126, v126, v126 quad_perm:[2,3,0,1] row_mask:0xf bank_mask:0xf
	global_load_dwordx2 v[224:225], v7, s[48:49] offset:16
	s_nop 0
	v_add_f32_dpp v126, v126, v126 row_half_mirror row_mask:0xf bank_mask:0xf
	v_cndmask_b32_e64 v15, v15, v126, s[64:65]
	s_waitcnt vmcnt(45)
	v_cvt_scalef32_pk32_f32_fp6 v[128:159], v[226:231], 1.0
	v_pk_mul_f32 v[116:117], v[128:129], v[80:81]
	v_pk_mul_f32 v[118:119], v[130:131], v[82:83]
	v_pk_mul_f32 v[120:121], v[132:133], v[84:85]
	v_pk_mul_f32 v[122:123], v[134:135], v[86:87]
	v_pk_fma_f32 v[116:117], v[136:137], v[88:89], v[116:117]
	v_pk_fma_f32 v[118:119], v[138:139], v[90:91], v[118:119]
	v_pk_fma_f32 v[120:121], v[140:141], v[92:93], v[120:121]
	v_pk_fma_f32 v[122:123], v[142:143], v[94:95], v[122:123]
	v_pk_fma_f32 v[116:117], v[144:145], v[96:97], v[116:117]
	v_pk_fma_f32 v[118:119], v[146:147], v[98:99], v[118:119]
	v_pk_fma_f32 v[120:121], v[148:149], v[100:101], v[120:121]
	v_pk_fma_f32 v[122:123], v[150:151], v[102:103], v[122:123]
	v_pk_fma_f32 v[116:117], v[152:153], v[104:105], v[116:117]
	v_pk_fma_f32 v[118:119], v[154:155], v[106:107], v[118:119]
	v_pk_fma_f32 v[120:121], v[156:157], v[108:109], v[120:121]
	v_pk_fma_f32 v[122:123], v[158:159], v[110:111], v[122:123]
	v_pk_add_f32 v[116:117], v[116:117], v[118:119]
	v_pk_add_f32 v[120:121], v[120:121], v[122:123]
	v_pk_add_f32 v[116:117], v[116:117], v[120:121]
	v_add_f32_e32 v126, v116, v117
	v_mad_u32_u24 v8, v27, s19, v1
	s_nop 0
	v_add_f32_dpp v126, v126, v126 quad_perm:[1,0,3,2] row_mask:0xf bank_mask:0xf
	global_load_dwordx4 v[226:229], v8, s[48:49]
	s_nop 0
	v_add_f32_dpp v126, v126, v126 quad_perm:[2,3,0,1] row_mask:0xf bank_mask:0xf
	global_load_dwordx2 v[230:231], v8, s[48:49] offset:16
	s_nop 0
	v_add_f32_dpp v126, v126, v126 row_half_mirror row_mask:0xf bank_mask:0xf
	v_cndmask_b32_e64 v15, v15, v126, s[66:67]
	s_waitcnt vmcnt(45)
	v_cvt_scalef32_pk32_f32_fp6 v[128:159], v[232:237], 1.0
	v_pk_mul_f32 v[116:117], v[128:129], v[80:81]
	v_pk_mul_f32 v[118:119], v[130:131], v[82:83]
	v_pk_mul_f32 v[120:121], v[132:133], v[84:85]
	v_pk_mul_f32 v[122:123], v[134:135], v[86:87]
	v_pk_fma_f32 v[116:117], v[136:137], v[88:89], v[116:117]
	v_pk_fma_f32 v[118:119], v[138:139], v[90:91], v[118:119]
	v_pk_fma_f32 v[120:121], v[140:141], v[92:93], v[120:121]
	v_pk_fma_f32 v[122:123], v[142:143], v[94:95], v[122:123]
	v_pk_fma_f32 v[116:117], v[144:145], v[96:97], v[116:117]
	v_pk_fma_f32 v[118:119], v[146:147], v[98:99], v[118:119]
	v_pk_fma_f32 v[120:121], v[148:149], v[100:101], v[120:121]
	v_pk_fma_f32 v[122:123], v[150:151], v[102:103], v[122:123]
	v_pk_fma_f32 v[116:117], v[152:153], v[104:105], v[116:117]
	v_pk_fma_f32 v[118:119], v[154:155], v[106:107], v[118:119]
	v_pk_fma_f32 v[120:121], v[156:157], v[108:109], v[120:121]
	v_pk_fma_f32 v[122:123], v[158:159], v[110:111], v[122:123]
	v_pk_add_f32 v[116:117], v[116:117], v[118:119]
	v_pk_add_f32 v[120:121], v[120:121], v[122:123]
	v_pk_add_f32 v[116:117], v[116:117], v[120:121]
	v_add_f32_e32 v126, v116, v117
	v_mad_u32_u24 v7, v28, s19, v1
	s_nop 0
	v_add_f32_dpp v126, v126, v126 quad_perm:[1,0,3,2] row_mask:0xf bank_mask:0xf
	global_load_dwordx4 v[232:235], v7, s[48:49]
	s_nop 0
	v_add_f32_dpp v126, v126, v126 quad_perm:[2,3,0,1] row_mask:0xf bank_mask:0xf
	global_load_dwordx2 v[236:237], v7, s[48:49] offset:16
	s_nop 0
	v_add_f32_dpp v126, v126, v126 row_half_mirror row_mask:0xf bank_mask:0xf
	v_cndmask_b32_e64 v15, v15, v126, s[68:69]
	s_waitcnt vmcnt(45)
	v_cvt_scalef32_pk32_f32_fp6 v[128:159], v[238:243], 1.0
	v_pk_mul_f32 v[116:117], v[128:129], v[80:81]
	v_pk_mul_f32 v[118:119], v[130:131], v[82:83]
	v_pk_mul_f32 v[120:121], v[132:133], v[84:85]
	v_pk_mul_f32 v[122:123], v[134:135], v[86:87]
	v_pk_fma_f32 v[116:117], v[136:137], v[88:89], v[116:117]
	v_pk_fma_f32 v[118:119], v[138:139], v[90:91], v[118:119]
	v_pk_fma_f32 v[120:121], v[140:141], v[92:93], v[120:121]
	v_pk_fma_f32 v[122:123], v[142:143], v[94:95], v[122:123]
	v_pk_fma_f32 v[116:117], v[144:145], v[96:97], v[116:117]
	v_pk_fma_f32 v[118:119], v[146:147], v[98:99], v[118:119]
	v_pk_fma_f32 v[120:121], v[148:149], v[100:101], v[120:121]
	v_pk_fma_f32 v[122:123], v[150:151], v[102:103], v[122:123]
	v_pk_fma_f32 v[116:117], v[152:153], v[104:105], v[116:117]
	v_pk_fma_f32 v[118:119], v[154:155], v[106:107], v[118:119]
	v_pk_fma_f32 v[120:121], v[156:157], v[108:109], v[120:121]
	v_pk_fma_f32 v[122:123], v[158:159], v[110:111], v[122:123]
	v_pk_add_f32 v[116:117], v[116:117], v[118:119]
	v_pk_add_f32 v[120:121], v[120:121], v[122:123]
	v_pk_add_f32 v[116:117], v[116:117], v[120:121]
	v_add_f32_e32 v126, v116, v117
	v_mad_u32_u24 v8, v29, s19, v1
	s_nop 0
	v_add_f32_dpp v126, v126, v126 quad_perm:[1,0,3,2] row_mask:0xf bank_mask:0xf
	global_load_dwordx4 v[238:241], v8, s[48:49]
	s_nop 0
	v_add_f32_dpp v126, v126, v126 quad_perm:[2,3,0,1] row_mask:0xf bank_mask:0xf
	global_load_dwordx2 v[242:243], v8, s[48:49] offset:16
	s_nop 0
	v_add_f32_dpp v126, v126, v126 row_half_mirror row_mask:0xf bank_mask:0xf
	v_cndmask_b32_e64 v15, v15, v126, s[70:71]
	s_waitcnt vmcnt(45)
	v_cvt_scalef32_pk32_f32_fp6 v[128:159], v[244:249], 1.0
	v_pk_mul_f32 v[116:117], v[128:129], v[80:81]
	v_pk_mul_f32 v[118:119], v[130:131], v[82:83]
	v_pk_mul_f32 v[120:121], v[132:133], v[84:85]
	v_pk_mul_f32 v[122:123], v[134:135], v[86:87]
	v_pk_fma_f32 v[116:117], v[136:137], v[88:89], v[116:117]
	v_pk_fma_f32 v[118:119], v[138:139], v[90:91], v[118:119]
	v_pk_fma_f32 v[120:121], v[140:141], v[92:93], v[120:121]
	v_pk_fma_f32 v[122:123], v[142:143], v[94:95], v[122:123]
	v_pk_fma_f32 v[116:117], v[144:145], v[96:97], v[116:117]
	v_pk_fma_f32 v[118:119], v[146:147], v[98:99], v[118:119]
	v_pk_fma_f32 v[120:121], v[148:149], v[100:101], v[120:121]
	v_pk_fma_f32 v[122:123], v[150:151], v[102:103], v[122:123]
	v_pk_fma_f32 v[116:117], v[152:153], v[104:105], v[116:117]
	v_pk_fma_f32 v[118:119], v[154:155], v[106:107], v[118:119]
	v_pk_fma_f32 v[120:121], v[156:157], v[108:109], v[120:121]
	v_pk_fma_f32 v[122:123], v[158:159], v[110:111], v[122:123]
	v_pk_add_f32 v[116:117], v[116:117], v[118:119]
	v_pk_add_f32 v[120:121], v[120:121], v[122:123]
	v_pk_add_f32 v[116:117], v[116:117], v[120:121]
	v_add_f32_e32 v126, v116, v117
	v_mad_u32_u24 v7, v30, s19, v1
	s_nop 0
	v_add_f32_dpp v126, v126, v126 quad_perm:[1,0,3,2] row_mask:0xf bank_mask:0xf
	global_load_dwordx4 v[244:247], v7, s[48:49]
	s_nop 0
	v_add_f32_dpp v126, v126, v126 quad_perm:[2,3,0,1] row_mask:0xf bank_mask:0xf
	global_load_dwordx2 v[248:249], v7, s[48:49] offset:16
	s_nop 0
	v_add_f32_dpp v126, v126, v126 row_half_mirror row_mask:0xf bank_mask:0xf
	v_cndmask_b32_e64 v15, v15, v126, s[72:73]
	s_waitcnt vmcnt(45)
	v_cvt_scalef32_pk32_f32_fp6 v[128:159], v[250:255], 1.0
	v_pk_mul_f32 v[116:117], v[128:129], v[80:81]
	v_pk_mul_f32 v[118:119], v[130:131], v[82:83]
	v_pk_mul_f32 v[120:121], v[132:133], v[84:85]
	v_pk_mul_f32 v[122:123], v[134:135], v[86:87]
	v_pk_fma_f32 v[116:117], v[136:137], v[88:89], v[116:117]
	v_pk_fma_f32 v[118:119], v[138:139], v[90:91], v[118:119]
	v_pk_fma_f32 v[120:121], v[140:141], v[92:93], v[120:121]
	v_pk_fma_f32 v[122:123], v[142:143], v[94:95], v[122:123]
	v_pk_fma_f32 v[116:117], v[144:145], v[96:97], v[116:117]
	v_pk_fma_f32 v[118:119], v[146:147], v[98:99], v[118:119]
	v_pk_fma_f32 v[120:121], v[148:149], v[100:101], v[120:121]
	v_pk_fma_f32 v[122:123], v[150:151], v[102:103], v[122:123]
	v_pk_fma_f32 v[116:117], v[152:153], v[104:105], v[116:117]
	v_pk_fma_f32 v[118:119], v[154:155], v[106:107], v[118:119]
	v_pk_fma_f32 v[120:121], v[156:157], v[108:109], v[120:121]
	v_pk_fma_f32 v[122:123], v[158:159], v[110:111], v[122:123]
	v_pk_add_f32 v[116:117], v[116:117], v[118:119]
	v_pk_add_f32 v[120:121], v[120:121], v[122:123]
	v_pk_add_f32 v[116:117], v[116:117], v[120:121]
	v_add_f32_e32 v126, v116, v117
	v_mad_u32_u24 v8, v31, s19, v1
	s_nop 0
	v_add_f32_dpp v126, v126, v126 quad_perm:[1,0,3,2] row_mask:0xf bank_mask:0xf
	global_load_dwordx4 v[250:253], v8, s[48:49]
	s_nop 0
	v_add_f32_dpp v126, v126, v126 quad_perm:[2,3,0,1] row_mask:0xf bank_mask:0xf
	global_load_dwordx2 v[254:255], v8, s[48:49] offset:16
	s_nop 0
	v_add_f32_dpp v126, v126, v126 row_half_mirror row_mask:0xf bank_mask:0xf
	v_cndmask_b32_e64 v15, v15, v126, s[74:75]
	v_mul_f32_e32 v12, v12, v127
	v_mul_f32_e32 v15, v15, v127
	global_store_dword v9, v12, s[44:45]
	global_store_dword v9, v15, s[44:45] offset:32
	s_add_u32 s28, s28, 1
	s_cmp_lt_u32 s28, 128
	s_cbranch_scc1 .Lpa_tokloop
	s_waitcnt vmcnt(0)
	s_waitcnt vmcnt(0) lgkmcnt(0)
	s_barrier
	s_cmp_lg_u32 s21, 0
	s_cbranch_scc1 .Lpb_skip_g
	s_mov_b64 exec, 1
	v_mov_b32_e32 v10, 0x12000
	ds_read_b32 v12, v10
	ds_read_b32 v13, v10 offset:4
	s_getreg_b32 s44, hwreg(HW_REG_XCC_ID, 0, 4)
	s_and_b32 s44, s44, 15
	s_lshl_b32 s44, s44, 2
	s_waitcnt lgkmcnt(0)
	v_readfirstlane_b32 s45, v12
	v_readfirstlane_b32 s46, v13
	v_mov_b32_e32 v10, s44
	v_mov_b32_e32 v11, 1
	global_atomic_add v12, v10, v11, s[14:15] offset:384 sc0
	s_waitcnt vmcnt(0)
	v_readfirstlane_b32 s47, v12
	s_nop 3
	s_add_u32 s47, s47, 1
	s_cmp_lg_u32 s47, s45
	v_mov_b32_e32 v10, 0
	s_cbranch_scc1 .Lpb_notlast_g
	buffer_wbl2 sc1
	s_waitcnt vmcnt(0)
	global_atomic_add v10, v11, s[14:15] offset:448
	s_waitcnt vmcnt(0)
.Lpb_notlast_g:
	s_mov_b32 s41, 0
.Lpb_spin_g:
	global_load_dword v12, v10, s[14:15] offset:448 sc1
	s_waitcnt vmcnt(0)
	v_readfirstlane_b32 s42, v12
	s_nop 3
	s_cmp_ge_u32 s42, s46
	s_cbranch_scc1 .Lpb_done_g
	s_add_u32 s41, s41, 1
	s_cmp_gt_u32 s41, 0x8000
	s_cbranch_scc1 .Lpb_done_g
	s_sleep 20
	s_branch .Lpb_spin_g
.Lpb_done_g:
	buffer_inv sc1
	s_waitcnt vmcnt(0)
	s_mov_b64 exec, -1
.Lpb_skip_g:
	s_barrier
	v_lshlrev_b32_e32 v15, 2, v0
	s_mov_b32 s28, 0
.Lpg_loop:
	s_add_u32 s40, s28, 0
	s_lshl_b32 s40, s40, 11
	s_add_u32 s40, s40, s20
	s_lshl_b32 s29, s40, 9
	s_add_u32 s30, s4, s29
	s_addc_u32 s31, s5, 0
	s_lshl_b32 s29, s40, 9
	s_add_u32 s32, s6, s29
	s_addc_u32 s33, s7, 0
	s_lshl_b32 s29, s40, 12
	s_add_u32 s34, s78, s29
	s_addc_u32 s35, s79, 0
	global_load_dword v16, v15, s[30:31]
	global_load_dword v17, v15, s[30:31] offset:256
	global_load_dword v18, v15, s[32:33]
	global_load_dword v19, v15, s[32:33] offset:256
	global_load_dword v20, v15, s[34:35] offset:0
	global_load_dword v21, v15, s[34:35] offset:256
	global_load_dword v22, v15, s[34:35] offset:512
	global_load_dword v23, v15, s[34:35] offset:768
	global_load_dword v24, v15, s[34:35] offset:1024
	global_load_dword v25, v15, s[34:35] offset:1280
	global_load_dword v26, v15, s[34:35] offset:1536
	global_load_dword v27, v15, s[34:35] offset:1792
	global_load_dword v28, v15, s[34:35] offset:2048
	global_load_dword v29, v15, s[34:35] offset:2304
	global_load_dword v30, v15, s[34:35] offset:2560
	global_load_dword v31, v15, s[34:35] offset:2816
	global_load_dword v32, v15, s[34:35] offset:3072
	global_load_dword v33, v15, s[34:35] offset:3328
	global_load_dword v34, v15, s[34:35] offset:3584
	global_load_dword v35, v15, s[34:35] offset:3840
	s_add_u32 s40, s28, 1
	s_lshl_b32 s40, s40, 11
	s_add_u32 s40, s40, s20
	s_lshl_b32 s29, s40, 9
	s_add_u32 s30, s4, s29
	s_addc_u32 s31, s5, 0
	s_lshl_b32 s29, s40, 9
	s_add_u32 s32, s6, s29
	s_addc_u32 s33, s7, 0
	s_lshl_b32 s29, s40, 12
	s_add_u32 s34, s78, s29
	s_addc_u32 s35, s79, 0
	global_load_dword v40, v15, s[30:31]
	global_load_dword v41, v15, s[30:31] offset:256
	global_load_dword v42, v15, s[32:33]
	global_load_dword v43, v15, s[32:33] offset:256
	global_load_dword v44, v15, s[34:35] offset:0
	global_load_dword v45, v15, s[34:35] offset:256
	global_load_dword v46, v15, s[34:35] offset:512
	global_load_dword v47, v15, s[34:35] offset:768
	global_load_dword v48, v15, s[34:35] offset:1024
	global_load_dword v49, v15, s[34:35] offset:1280
	global_load_dword v50, v15, s[34:35] offset:1536
	global_load_dword v51, v15, s[34:35] offset:1792
	global_load_dword v52, v15, s[34:35] offset:2048
	global_load_dword v53, v15, s[34:35] offset:2304
	global_load_dword v54, v15, s[34:35] offset:2560
	global_load_dword v55, v15, s[34:35] offset:2816
	global_load_dword v56, v15, s[34:35] offset:3072
	global_load_dword v57, v15, s[34:35] offset:3328
	global_load_dword v58, v15, s[34:35] offset:3584
	global_load_dword v59, v15, s[34:35] offset:3840
	s_add_u32 s40, s28, 2
	s_lshl_b32 s40, s40, 11
	s_add_u32 s40, s40, s20
	s_lshl_b32 s29, s40, 9
	s_add_u32 s30, s4, s29
	s_addc_u32 s31, s5, 0
	s_lshl_b32 s29, s40, 9
	s_add_u32 s32, s6, s29
	s_addc_u32 s33, s7, 0
	s_lshl_b32 s29, s40, 12
	s_add_u32 s34, s78, s29
	s_addc_u32 s35, s79, 0
	global_load_dword v64, v15, s[30:31]
	global_load_dword v65, v15, s[30:31] offset:256
	global_load_dword v66, v15, s[32:33]
	global_load_dword v67, v15, s[32:33] offset:256
	global_load_dword v68, v15, s[34:35] offset:0
	global_load_dword v69, v15, s[34:35] offset:256
	global_load_dword v70, v15, s[34:35] offset:512
	global_load_dword v71, v15, s[34:35] offset:768
	global_load_dword v72, v15, s[34:35] offset:1024
	global_load_dword v73, v15, s[34:35] offset:1280
	global_load_dword v74, v15, s[34:35] offset:1536
	global_load_dword v75, v15, s[34:35] offset:1792
	global_load_dword v76, v15, s[34:35] offset:2048
	global_load_dword v77, v15, s[34:35] offset:2304
	global_load_dword v78, v15, s[34:35] offset:2560
	global_load_dword v79, v15, s[34:35] offset:2816
	global_load_dword v80, v15, s[34:35] offset:3072
	global_load_dword v81, v15, s[34:35] offset:3328
	global_load_dword v82, v15, s[34:35] offset:3584
	global_load_dword v83, v15, s[34:35] offset:3840
	s_add_u32 s40, s28, 3
	s_lshl_b32 s40, s40, 11
	s_add_u32 s40, s40, s20
	s_lshl_b32 s29, s40, 9
	s_add_u32 s30, s4, s29
	s_addc_u32 s31, s5, 0
	s_lshl_b32 s29, s40, 9
	s_add_u32 s32, s6, s29
	s_addc_u32 s33, s7, 0
	s_lshl_b32 s29, s40, 12
	s_add_u32 s34, s78, s29
	s_addc_u32 s35, s79, 0
	global_load_dword v88, v15, s[30:31]
	global_load_dword v89, v15, s[30:31] offset:256
	global_load_dword v90, v15, s[32:33]
	global_load_dword v91, v15, s[32:33] offset:256
	global_load_dword v92, v15, s[34:35] offset:0
	global_load_dword v93, v15, s[34:35] offset:256
	global_load_dword v94, v15, s[34:35] offset:512
	global_load_dword v95, v15, s[34:35] offset:768
	global_load_dword v96, v15, s[34:35] offset:1024
	global_load_dword v97, v15, s[34:35] offset:1280
	global_load_dword v98, v15, s[34:35] offset:1536
	global_load_dword v99, v15, s[34:35] offset:1792
	global_load_dword v100, v15, s[34:35] offset:2048
	global_load_dword v101, v15, s[34:35] offset:2304
	global_load_dword v102, v15, s[34:35] offset:2560
	global_load_dword v103, v15, s[34:35] offset:2816
	global_load_dword v104, v15, s[34:35] offset:3072
	global_load_dword v105, v15, s[34:35] offset:3328
	global_load_dword v106, v15, s[34:35] offset:3584
	global_load_dword v107, v15, s[34:35] offset:3840
	s_waitcnt vmcnt(60)
	v_lshlrev_b32_e32 v16, 2, v16
	v_lshlrev_b32_e32 v17, 2, v17
	global_load_dword v36, v16, s[58:59]
	global_load_dword v37, v17, s[58:59]
	global_load_dword v38, v16, s[76:77]
	global_load_dword v39, v17, s[76:77]
	s_waitcnt vmcnt(44)
	v_lshlrev_b32_e32 v40, 2, v40
	v_lshlrev_b32_e32 v41, 2, v41
	global_load_dword v60, v40, s[58:59]
	global_load_dword v61, v41, s[58:59]
	global_load_dword v62, v40, s[76:77]
	global_load_dword v63, v41, s[76:77]
	s_waitcnt vmcnt(28)
	v_lshlrev_b32_e32 v64, 2, v64
	v_lshlrev_b32_e32 v65, 2, v65
	global_load_dword v84, v64, s[58:59]
	global_load_dword v85, v65, s[58:59]
	global_load_dword v86, v64, s[76:77]
	global_load_dword v87, v65, s[76:77]
	s_waitcnt vmcnt(12)
	v_lshlrev_b32_e32 v88, 2, v88
	v_lshlrev_b32_e32 v89, 2, v89
	global_load_dword v108, v88, s[58:59]
	global_load_dword v109, v89, s[58:59]
	global_load_dword v110, v88, s[76:77]
	global_load_dword v111, v89, s[76:77]
	v_add_f32_e32 v20, v20, v22
	v_add_f32_e32 v24, v24, v26
	v_add_f32_e32 v28, v28, v30
	v_add_f32_e32 v32, v32, v34
	v_add_f32_e32 v20, v20, v24
	v_add_f32_e32 v28, v28, v32
	v_add_f32_e32 v20, v20, v28
	v_add_f32_e32 v21, v21, v23
	v_add_f32_e32 v25, v25, v27
	v_add_f32_e32 v29, v29, v31
	v_add_f32_e32 v33, v33, v35
	v_add_f32_e32 v21, v21, v25
	v_add_f32_e32 v29, v29, v33
	v_add_f32_e32 v21, v21, v29
	s_waitcnt vmcnt(12)
	v_mul_f32_e32 v20, v20, v36
	v_mul_f32_e32 v24, v20, v20
	v_mov_b32_e32 v28, 1.0
	v_fmac_f32_e32 v28, 0x3d372713, v24
	v_mul_f32_e32 v28, v28, v20
	v_mul_f32_e32 v28, 0xc0135761, v28
	v_exp_f32_e32 v28, v28
	s_nop 0
	v_add_f32_e32 v28, 1.0, v28
	v_rcp_f32_e32 v28, v28
	s_nop 0
	v_mul_f32_e32 v28, v28, v20
	v_mul_f32_e32 v28, v28, v18
	v_mul_f32_e32 v28, v28, v38
	v_mul_f32_e32 v21, v21, v37
	v_mul_f32_e32 v25, v21, v21
	v_mov_b32_e32 v29, 1.0
	v_fmac_f32_e32 v29, 0x3d372713, v25
	v_mul_f32_e32 v29, v29, v21
	v_mul_f32_e32 v29, 0xc0135761, v29
	v_exp_f32_e32 v29, v29
	s_nop 0
	v_add_f32_e32 v29, 1.0, v29
	v_rcp_f32_e32 v29, v29
	s_nop 0
	v_mul_f32_e32 v29, v29, v21
	v_mul_f32_e32 v29, v29, v19
	v_mul_f32_e32 v29, v29, v39
	s_add_u32 s40, s28, 0
	s_lshl_b32 s40, s40, 11
	s_add_u32 s40, s40, s20
	s_lshl_b32 s29, s40, 9
	s_add_u32 s32, s6, s29
	s_addc_u32 s33, s7, 0
	global_store_dword v15, v28, s[32:33]
	global_store_dword v15, v29, s[32:33] offset:256
	v_add_f32_e32 v44, v44, v46
	v_add_f32_e32 v48, v48, v50
	v_add_f32_e32 v52, v52, v54
	v_add_f32_e32 v56, v56, v58
	v_add_f32_e32 v44, v44, v48
	v_add_f32_e32 v52, v52, v56
	v_add_f32_e32 v44, v44, v52
	v_add_f32_e32 v45, v45, v47
	v_add_f32_e32 v49, v49, v51
	v_add_f32_e32 v53, v53, v55
	v_add_f32_e32 v57, v57, v59
	v_add_f32_e32 v45, v45, v49
	v_add_f32_e32 v53, v53, v57
	v_add_f32_e32 v45, v45, v53
	s_waitcnt vmcnt(8)
	v_mul_f32_e32 v44, v44, v60
	v_mul_f32_e32 v48, v44, v44
	v_mov_b32_e32 v52, 1.0
	v_fmac_f32_e32 v52, 0x3d372713, v48
	v_mul_f32_e32 v52, v52, v44
	v_mul_f32_e32 v52, 0xc0135761, v52
	v_exp_f32_e32 v52, v52
	s_nop 0
	v_add_f32_e32 v52, 1.0, v52
	v_rcp_f32_e32 v52, v52
	s_nop 0
	v_mul_f32_e32 v52, v52, v44
	v_mul_f32_e32 v52, v52, v42
	v_mul_f32_e32 v52, v52, v62
	v_mul_f32_e32 v45, v45, v61
	v_mul_f32_e32 v49, v45, v45
	v_mov_b32_e32 v53, 1.0
	v_fmac_f32_e32 v53, 0x3d372713, v49
	v_mul_f32_e32 v53, v53, v45
	v_mul_f32_e32 v53, 0xc0135761, v53
	v_exp_f32_e32 v53, v53
	s_nop 0
	v_add_f32_e32 v53, 1.0, v53
	v_rcp_f32_e32 v53, v53
	s_nop 0
	v_mul_f32_e32 v53, v53, v45
	v_mul_f32_e32 v53, v53, v43
	v_mul_f32_e32 v53, v53, v63
	s_add_u32 s40, s28, 1
	s_lshl_b32 s40, s40, 11
	s_add_u32 s40, s40, s20
	s_lshl_b32 s29, s40, 9
	s_add_u32 s32, s6, s29
	s_addc_u32 s33, s7, 0
	global_store_dword v15, v52, s[32:33]
	global_store_dword v15, v53, s[32:33] offset:256
	v_add_f32_e32 v68, v68, v70
	v_add_f32_e32 v72, v72, v74
	v_add_f32_e32 v76, v76, v78
	v_add_f32_e32 v80, v80, v82
	v_add_f32_e32 v68, v68, v72
	v_add_f32_e32 v76, v76, v80
	v_add_f32_e32 v68, v68, v76
	v_add_f32_e32 v69, v69, v71
	v_add_f32_e32 v73, v73, v75
	v_add_f32_e32 v77, v77, v79
	v_add_f32_e32 v81, v81, v83
	v_add_f32_e32 v69, v69, v73
	v_add_f32_e32 v77, v77, v81
	v_add_f32_e32 v69, v69, v77
	s_waitcnt vmcnt(4)
	v_mul_f32_e32 v68, v68, v84
	v_mul_f32_e32 v72, v68, v68
	v_mov_b32_e32 v76, 1.0
	v_fmac_f32_e32 v76, 0x3d372713, v72
	v_mul_f32_e32 v76, v76, v68
	v_mul_f32_e32 v76, 0xc0135761, v76
	v_exp_f32_e32 v76, v76
	s_nop 0
	v_add_f32_e32 v76, 1.0, v76
	v_rcp_f32_e32 v76, v76
	s_nop 0
	v_mul_f32_e32 v76, v76, v68
	v_mul_f32_e32 v76, v76, v66
	v_mul_f32_e32 v76, v76, v86
	v_mul_f32_e32 v69, v69, v85
	v_mul_f32_e32 v73, v69, v69
	v_mov_b32_e32 v77, 1.0
	v_fmac_f32_e32 v77, 0x3d372713, v73
	v_mul_f32_e32 v77, v77, v69
	v_mul_f32_e32 v77, 0xc0135761, v77
	v_exp_f32_e32 v77, v77
	s_nop 0
	v_add_f32_e32 v77, 1.0, v77
	v_rcp_f32_e32 v77, v77
	s_nop 0
	v_mul_f32_e32 v77, v77, v69
	v_mul_f32_e32 v77, v77, v67
	v_mul_f32_e32 v77, v77, v87
	s_add_u32 s40, s28, 2
	s_lshl_b32 s40, s40, 11
	s_add_u32 s40, s40, s20
	s_lshl_b32 s29, s40, 9
	s_add_u32 s32, s6, s29
	s_addc_u32 s33, s7, 0
	global_store_dword v15, v76, s[32:33]
	global_store_dword v15, v77, s[32:33] offset:256
	v_add_f32_e32 v92, v92, v94
	v_add_f32_e32 v96, v96, v98
	v_add_f32_e32 v100, v100, v102
	v_add_f32_e32 v104, v104, v106
	v_add_f32_e32 v92, v92, v96
	v_add_f32_e32 v100, v100, v104
	v_add_f32_e32 v92, v92, v100
	v_add_f32_e32 v93, v93, v95
	v_add_f32_e32 v97, v97, v99
	v_add_f32_e32 v101, v101, v103
	v_add_f32_e32 v105, v105, v107
	v_add_f32_e32 v93, v93, v97
	v_add_f32_e32 v101, v101, v105
	v_add_f32_e32 v93, v93, v101
	s_waitcnt vmcnt(0)
	v_mul_f32_e32 v92, v92, v108
	v_mul_f32_e32 v96, v92, v92
	v_mov_b32_e32 v100, 1.0
	v_fmac_f32_e32 v100, 0x3d372713, v96
	v_mul_f32_e32 v100, v100, v92
	v_mul_f32_e32 v100, 0xc0135761, v100
	v_exp_f32_e32 v100, v100
	s_nop 0
	v_add_f32_e32 v100, 1.0, v100
	v_rcp_f32_e32 v100, v100
	s_nop 0
	v_mul_f32_e32 v100, v100, v92
	v_mul_f32_e32 v100, v100, v90
	v_mul_f32_e32 v100, v100, v110
	v_mul_f32_e32 v93, v93, v109
	v_mul_f32_e32 v97, v93, v93
	v_mov_b32_e32 v101, 1.0
	v_fmac_f32_e32 v101, 0x3d372713, v97
	v_mul_f32_e32 v101, v101, v93
	v_mul_f32_e32 v101, 0xc0135761, v101
	v_exp_f32_e32 v101, v101
	s_nop 0
	v_add_f32_e32 v101, 1.0, v101
	v_rcp_f32_e32 v101, v101
	s_nop 0
	v_mul_f32_e32 v101, v101, v93
	v_mul_f32_e32 v101, v101, v91
	v_mul_f32_e32 v101, v101, v111
	s_add_u32 s40, s28, 3
	s_lshl_b32 s40, s40, 11
	s_add_u32 s40, s40, s20
	s_lshl_b32 s29, s40, 9
	s_add_u32 s32, s6, s29
	s_addc_u32 s33, s7, 0
	global_store_dword v15, v100, s[32:33]
	global_store_dword v15, v101, s[32:33] offset:256
	s_add_u32 s28, s28, 4
	s_cmp_lt_u32 s28, 16
	s_cbranch_scc1 .Lpg_loop
	s_waitcnt vmcnt(0)
	s_waitcnt vmcnt(0) lgkmcnt(0)
	s_barrier
	s_cmp_lg_u32 s21, 0
	s_cbranch_scc1 .Lpb_skip_a
	s_mov_b64 exec, 1
	v_mov_b32_e32 v10, 0x12000
	ds_read_b32 v12, v10
	ds_read_b32 v13, v10 offset:4
	s_getreg_b32 s44, hwreg(HW_REG_XCC_ID, 0, 4)
	s_and_b32 s44, s44, 15
	s_lshl_b32 s44, s44, 2
	s_waitcnt lgkmcnt(0)
	v_readfirstlane_b32 s45, v12
	v_readfirstlane_b32 s46, v13
	v_mov_b32_e32 v10, s44
	v_mov_b32_e32 v11, 1
	global_atomic_add v12, v10, v11, s[14:15] offset:128 sc0
	s_waitcnt vmcnt(0)
	v_readfirstlane_b32 s47, v12
	s_nop 3
	s_add_u32 s47, s47, 1
	s_cmp_lg_u32 s47, s45
	v_mov_b32_e32 v10, 0
	s_cbranch_scc1 .Lpb_notlast_a
	buffer_wbl2 sc1
	s_waitcnt vmcnt(0)
	global_atomic_add v10, v11, s[14:15] offset:192
	s_waitcnt vmcnt(0)

.Lpb_spin_a:
	global_load_dword v12, v10, s[14:15] offset:192 sc1
	s_waitcnt vmcnt(0)
	v_readfirstlane_b32 s42, v12
	s_nop 3
	s_cmp_ge_u32 s42, s46
	s_cbranch_scc1 .Lpb_done_a
	s_add_u32 s41, s41, 1
	s_cmp_gt_u32 s41, 0x8000
	s_cbranch_scc1 .Lpb_done_a
	s_sleep 20
	s_branch .Lpb_spin_a

.Lpb_skip_a:
	s_barrier
	s_mov_b32 s28, 0
	s_add_u32 s40, s28, 0
	s_min_u32 s40, s40, 127
	s_lshl_b32 s40, s40, 8
	s_add_u32 s40, s40, s24
	s_lshl_b32 s29, s40, 9
	s_add_u32 s30, s4, s29
	s_addc_u32 s31, s5, 0
	global_load_dwordx4 v[16:19], v2, s[30:31] offset:0
	global_load_dwordx4 v[20:23], v2, s[30:31] offset:16
	global_load_dwordx4 v[24:27], v2, s[30:31] offset:32
	global_load_dwordx4 v[28:31], v2, s[30:31] offset:48
	s_add_u32 s40, s28, 0
	s_min_u32 s40, s40, 127
	s_lshl_b32 s40, s40, 8
	s_add_u32 s40, s40, s24
	s_lshl_b32 s29, s40, 9
	s_add_u32 s32, s6, s29
	s_addc_u32 s33, s7, 0
	global_load_dwordx4 v[48:51], v2, s[32:33] offset:0
	global_load_dwordx4 v[52:55], v2, s[32:33] offset:16
	global_load_dwordx4 v[56:59], v2, s[32:33] offset:32
	global_load_dwordx4 v[60:63], v2, s[32:33] offset:48
	s_add_u32 s40, s28, 1
	s_min_u32 s40, s40, 127
	s_lshl_b32 s40, s40, 8
	s_add_u32 s40, s40, s24
	s_lshl_b32 s29, s40, 9
	s_add_u32 s30, s4, s29
	s_addc_u32 s31, s5, 0
	global_load_dwordx4 v[32:35], v2, s[30:31] offset:0
	global_load_dwordx4 v[36:39], v2, s[30:31] offset:16
	global_load_dwordx4 v[40:43], v2, s[30:31] offset:32
	global_load_dwordx4 v[44:47], v2, s[30:31] offset:48
	s_waitcnt vmcnt(0)
	v_mad_u32_u24 v7, v16, s19, v1
	global_load_dwordx4 v[160:163], v7, s[26:27]
	global_load_dwordx2 v[164:165], v7, s[26:27] offset:16
	v_mad_u32_u24 v8, v17, s19, v1
	global_load_dwordx4 v[166:169], v8, s[26:27]
	global_load_dwordx2 v[170:171], v8, s[26:27] offset:16
	v_mad_u32_u24 v7, v18, s19, v1
	global_load_dwordx4 v[172:175], v7, s[26:27]
	global_load_dwordx2 v[176:177], v7, s[26:27] offset:16
	v_mad_u32_u24 v8, v19, s19, v1
	global_load_dwordx4 v[178:181], v8, s[26:27]
	global_load_dwordx2 v[182:183], v8, s[26:27] offset:16
	v_mad_u32_u24 v7, v20, s19, v1
	global_load_dwordx4 v[184:187], v7, s[26:27]
	global_load_dwordx2 v[188:189], v7, s[26:27] offset:16
	v_mad_u32_u24 v8, v21, s19, v1
	global_load_dwordx4 v[190:193], v8, s[26:27]
	global_load_dwordx2 v[194:195], v8, s[26:27] offset:16
	v_mad_u32_u24 v7, v22, s19, v1
	global_load_dwordx4 v[196:199], v7, s[26:27]
	global_load_dwordx2 v[200:201], v7, s[26:27] offset:16
	v_mad_u32_u24 v8, v23, s19, v1
	global_load_dwordx4 v[202:205], v8, s[26:27]
	global_load_dwordx2 v[206:207], v8, s[26:27] offset:16
	v_mad_u32_u24 v7, v24, s19, v1
	global_load_dwordx4 v[208:211], v7, s[26:27]
	global_load_dwordx2 v[212:213], v7, s[26:27] offset:16
	v_mad_u32_u24 v8, v25, s19, v1
	global_load_dwordx4 v[214:217], v8, s[26:27]
	global_load_dwordx2 v[218:219], v8, s[26:27] offset:16
	v_mad_u32_u24 v7, v26, s19, v1
	global_load_dwordx4 v[220:223], v7, s[26:27]
	global_load_dwordx2 v[224:225], v7, s[26:27] offset:16
	v_mad_u32_u24 v8, v27, s19, v1
	global_load_dwordx4 v[226:229], v8, s[26:27]
	global_load_dwordx2 v[230:231], v8, s[26:27] offset:16
	v_mad_u32_u24 v7, v28, s19, v1
	global_load_dwordx4 v[232:235], v7, s[26:27]
	global_load_dwordx2 v[236:237], v7, s[26:27] offset:16
	v_mad_u32_u24 v8, v29, s19, v1
	global_load_dwordx4 v[238:241], v8, s[26:27]
	global_load_dwordx2 v[242:243], v8, s[26:27] offset:16
	v_mad_u32_u24 v7, v30, s19, v1
	global_load_dwordx4 v[244:247], v7, s[26:27]
	global_load_dwordx2 v[248:249], v7, s[26:27] offset:16
	v_mad_u32_u24 v8, v31, s19, v1
	global_load_dwordx4 v[250:253], v8, s[26:27]
	global_load_dwordx2 v[254:255], v8, s[26:27] offset:16
	global_store_dword v3, v3, s[14:15] offset:480
	global_store_dword v3, v3, s[14:15] offset:484
.Lpb_tokloop:
	s_add_u32 s40, s28, 0
	s_min_u32 s40, s40, 127
	s_lshl_b32 s40, s40, 8
	s_add_u32 s40, s40, s24
	s_lshl_b32 s29, s40, 13
	s_add_u32 s34, s10, s29
	s_addc_u32 s35, s11, 0
	global_load_dwordx4 v[80:83], v6, s[34:35]
	s_lshl_b32 s29, s40, 5
	s_add_u32 s29, s29, s43
	s_add_u32 s38, s12, s29
	s_addc_u32 s39, s13, 0
	s_add_u32 s40, s28, 2
	s_min_u32 s40, s40, 127
	s_lshl_b32 s40, s40, 8
	s_add_u32 s40, s40, s24
	s_lshl_b32 s29, s40, 9
	s_add_u32 s30, s4, s29
	s_addc_u32 s31, s5, 0
	global_load_dwordx4 v[16:19], v2, s[30:31] offset:0
	global_load_dwordx4 v[20:23], v2, s[30:31] offset:16
	global_load_dwordx4 v[24:27], v2, s[30:31] offset:32
	global_load_dwordx4 v[28:31], v2, s[30:31] offset:48
	s_add_u32 s40, s28, 1
	s_min_u32 s40, s40, 127
	s_lshl_b32 s40, s40, 8
	s_add_u32 s40, s40, s24
	s_lshl_b32 s29, s40, 9
	s_add_u32 s32, s6, s29
	s_addc_u32 s33, s7, 0
	global_load_dwordx4 v[64:67], v2, s[32:33] offset:0
	global_load_dwordx4 v[68:71], v2, s[32:33] offset:16
	global_load_dwordx4 v[72:75], v2, s[32:33] offset:32
	global_load_dwordx4 v[76:79], v2, s[32:33] offset:48
	s_waitcnt vmcnt(41)
	v_cvt_scalef32_pk32_f32_fp6 v[128:159], v[160:165], 1.0
	v_pk_mul_f32 v[84:85], v[128:129], v[48:49] op_sel_hi:[1,0]
	v_pk_mul_f32 v[86:87], v[130:131], v[48:49] op_sel_hi:[1,0]
	v_pk_mul_f32 v[88:89], v[132:133], v[48:49] op_sel_hi:[1,0]
	v_pk_mul_f32 v[90:91], v[134:135], v[48:49] op_sel_hi:[1,0]
	v_pk_mul_f32 v[92:93], v[136:137], v[48:49] op_sel_hi:[1,0]
	v_pk_mul_f32 v[94:95], v[138:139], v[48:49] op_sel_hi:[1,0]
	v_pk_mul_f32 v[96:97], v[140:141], v[48:49] op_sel_hi:[1,0]
	v_pk_mul_f32 v[98:99], v[142:143], v[48:49] op_sel_hi:[1,0]
	v_pk_mul_f32 v[100:101], v[144:145], v[48:49] op_sel_hi:[1,0]
	v_pk_mul_f32 v[102:103], v[146:147], v[48:49] op_sel_hi:[1,0]
	v_pk_mul_f32 v[104:105], v[148:149], v[48:49] op_sel_hi:[1,0]
	v_pk_mul_f32 v[106:107], v[150:151], v[48:49] op_sel_hi:[1,0]
	v_pk_mul_f32 v[108:109], v[152:153], v[48:49] op_sel_hi:[1,0]
	v_pk_mul_f32 v[110:111], v[154:155], v[48:49] op_sel_hi:[1,0]
	v_pk_mul_f32 v[112:113], v[156:157], v[48:49] op_sel_hi:[1,0]
	v_pk_mul_f32 v[114:115], v[158:159], v[48:49] op_sel_hi:[1,0]
	v_mad_u32_u24 v7, v32, s19, v1
	global_load_dwordx4 v[160:163], v7, s[26:27]
	global_load_dwordx2 v[164:165], v7, s[26:27] offset:16
	s_waitcnt vmcnt(41)
	v_cvt_scalef32_pk32_f32_fp6 v[128:159], v[166:171], 1.0
	v_pk_fma_f32 v[84:85], v[128:129], v[48:49], v[84:85] op_sel:[0,1,0] op_sel_hi:[1,1,1]
	v_pk_fma_f32 v[86:87], v[130:131], v[48:49], v[86:87] op_sel:[0,1,0] op_sel_hi:[1,1,1]
	v_pk_fma_f32 v[88:89], v[132:133], v[48:49], v[88:89] op_sel:[0,1,0] op_sel_hi:[1,1,1]
	v_pk_fma_f32 v[90:91], v[134:135], v[48:49], v[90:91] op_sel:[0,1,0] op_sel_hi:[1,1,1]
	v_pk_fma_f32 v[92:93], v[136:137], v[48:49], v[92:93] op_sel:[0,1,0] op_sel_hi:[1,1,1]
	v_pk_fma_f32 v[94:95], v[138:139], v[48:49], v[94:95] op_sel:[0,1,0] op_sel_hi:[1,1,1]
	v_pk_fma_f32 v[96:97], v[140:141], v[48:49], v[96:97] op_sel:[0,1,0] op_sel_hi:[1,1,1]
	v_pk_fma_f32 v[98:99], v[142:143], v[48:49], v[98:99] op_sel:[0,1,0] op_sel_hi:[1,1,1]
	v_pk_fma_f32 v[100:101], v[144:145], v[48:49], v[100:101] op_sel:[0,1,0] op_sel_hi:[1,1,1]
	v_pk_fma_f32 v[102:103], v[146:147], v[48:49], v[102:103] op_sel:[0,1,0] op_sel_hi:[1,1,1]
	v_pk_fma_f32 v[104:105], v[148:149], v[48:49], v[104:105] op_sel:[0,1,0] op_sel_hi:[1,1,1]
	v_pk_fma_f32 v[106:107], v[150:151], v[48:49], v[106:107] op_sel:[0,1,0] op_sel_hi:[1,1,1]
	v_pk_fma_f32 v[108:109], v[152:153], v[48:49], v[108:109] op_sel:[0,1,0] op_sel_hi:[1,1,1]
	v_pk_fma_f32 v[110:111], v[154:155], v[48:49], v[110:111] op_sel:[0,1,0] op_sel_hi:[1,1,1]
	v_pk_fma_f32 v[112:113], v[156:157], v[48:49], v[112:113] op_sel:[0,1,0] op_sel_hi:[1,1,1]
	v_pk_fma_f32 v[114:115], v[158:159], v[48:49], v[114:115] op_sel:[0,1,0] op_sel_hi:[1,1,1]
	v_mad_u32_u24 v8, v33, s19, v1
	global_load_dwordx4 v[166:169], v8, s[26:27]
	global_load_dwordx2 v[170:171], v8, s[26:27] offset:16
	s_waitcnt vmcnt(41)
	v_cvt_scalef32_pk32_f32_fp6 v[128:159], v[172:177], 1.0
	v_pk_fma_f32 v[84:85], v[128:129], v[50:51], v[84:85] op_sel_hi:[1,0,1]
	v_pk_fma_f32 v[86:87], v[130:131], v[50:51], v[86:87] op_sel_hi:[1,0,1]
	v_pk_fma_f32 v[88:89], v[132:133], v[50:51], v[88:89] op_sel_hi:[1,0,1]
	v_pk_fma_f32 v[90:91], v[134:135], v[50:51], v[90:91] op_sel_hi:[1,0,1]
	v_pk_fma_f32 v[92:93], v[136:137], v[50:51], v[92:93] op_sel_hi:[1,0,1]
	v_pk_fma_f32 v[94:95], v[138:139], v[50:51], v[94:95] op_sel_hi:[1,0,1]
	v_pk_fma_f32 v[96:97], v[140:141], v[50:51], v[96:97] op_sel_hi:[1,0,1]
	v_pk_fma_f32 v[98:99], v[142:143], v[50:51], v[98:99] op_sel_hi:[1,0,1]
	v_pk_fma_f32 v[100:101], v[144:145], v[50:51], v[100:101] op_sel_hi:[1,0,1]
	v_pk_fma_f32 v[102:103], v[146:147], v[50:51], v[102:103] op_sel_hi:[1,0,1]
	v_pk_fma_f32 v[104:105], v[148:149], v[50:51], v[104:105] op_sel_hi:[1,0,1]
	v_pk_fma_f32 v[106:107], v[150:151], v[50:51], v[106:107] op_sel_hi:[1,0,1]
	v_pk_fma_f32 v[108:109], v[152:153], v[50:51], v[108:109] op_sel_hi:[1,0,1]
	v_pk_fma_f32 v[110:111], v[154:155], v[50:51], v[110:111] op_sel_hi:[1,0,1]
	v_pk_fma_f32 v[112:113], v[156:157], v[50:51], v[112:113] op_sel_hi:[1,0,1]
	v_pk_fma_f32 v[114:115], v[158:159], v[50:51], v[114:115] op_sel_hi:[1,0,1]
	v_mad_u32_u24 v7, v34, s19, v1
	global_load_dwordx4 v[172:175], v7, s[26:27]
	global_load_dwordx2 v[176:177], v7, s[26:27] offset:16
	s_waitcnt vmcnt(41)
	v_cvt_scalef32_pk32_f32_fp6 v[128:159], v[178:183], 1.0
	v_pk_fma_f32 v[84:85], v[128:129], v[50:51], v[84:85] op_sel:[0,1,0] op_sel_hi:[1,1,1]
	v_pk_fma_f32 v[86:87], v[130:131], v[50:51], v[86:87] op_sel:[0,1,0] op_sel_hi:[1,1,1]
	v_pk_fma_f32 v[88:89], v[132:133], v[50:51], v[88:89] op_sel:[0,1,0] op_sel_hi:[1,1,1]
	v_pk_fma_f32 v[90:91], v[134:135], v[50:51], v[90:91] op_sel:[0,1,0] op_sel_hi:[1,1,1]
	v_pk_fma_f32 v[92:93], v[136:137], v[50:51], v[92:93] op_sel:[0,1,0] op_sel_hi:[1,1,1]
	v_pk_fma_f32 v[94:95], v[138:139], v[50:51], v[94:95] op_sel:[0,1,0] op_sel_hi:[1,1,1]
	v_pk_fma_f32 v[96:97], v[140:141], v[50:51], v[96:97] op_sel:[0,1,0] op_sel_hi:[1,1,1]
	v_pk_fma_f32 v[98:99], v[142:143], v[50:51], v[98:99] op_sel:[0,1,0] op_sel_hi:[1,1,1]
	v_pk_fma_f32 v[100:101], v[144:145], v[50:51], v[100:101] op_sel:[0,1,0] op_sel_hi:[1,1,1]
	v_pk_fma_f32 v[102:103], v[146:147], v[50:51], v[102:103] op_sel:[0,1,0] op_sel_hi:[1,1,1]
	v_pk_fma_f32 v[104:105], v[148:149], v[50:51], v[104:105] op_sel:[0,1,0] op_sel_hi:[1,1,1]
	v_pk_fma_f32 v[106:107], v[150:151], v[50:51], v[106:107] op_sel:[0,1,0] op_sel_hi:[1,1,1]
	v_pk_fma_f32 v[108:109], v[152:153], v[50:51], v[108:109] op_sel:[0,1,0] op_sel_hi:[1,1,1]
	v_pk_fma_f32 v[110:111], v[154:155], v[50:51], v[110:111] op_sel:[0,1,0] op_sel_hi:[1,1,1]
	v_pk_fma_f32 v[112:113], v[156:157], v[50:51], v[112:113] op_sel:[0,1,0] op_sel_hi:[1,1,1]
	v_pk_fma_f32 v[114:115], v[158:159], v[50:51], v[114:115] op_sel:[0,1,0] op_sel_hi:[1,1,1]
	v_mad_u32_u24 v8, v35, s19, v1
	global_load_dwordx4 v[178:181], v8, s[26:27]
	global_load_dwordx2 v[182:183], v8, s[26:27] offset:16
	s_waitcnt vmcnt(41)
	v_cvt_scalef32_pk32_f32_fp6 v[128:159], v[184:189], 1.0
	v_pk_fma_f32 v[84:85], v[128:129], v[52:53], v[84:85] op_sel_hi:[1,0,1]
	v_pk_fma_f32 v[86:87], v[130:131], v[52:53], v[86:87] op_sel_hi:[1,0,1]
	v_pk_fma_f32 v[88:89], v[132:133], v[52:53], v[88:89] op_sel_hi:[1,0,1]
	v_pk_fma_f32 v[90:91], v[134:135], v[52:53], v[90:91] op_sel_hi:[1,0,1]
	v_pk_fma_f32 v[92:93], v[136:137], v[52:53], v[92:93] op_sel_hi:[1,0,1]
	v_pk_fma_f32 v[94:95], v[138:139], v[52:53], v[94:95] op_sel_hi:[1,0,1]
	v_pk_fma_f32 v[96:97], v[140:141], v[52:53], v[96:97] op_sel_hi:[1,0,1]
	v_pk_fma_f32 v[98:99], v[142:143], v[52:53], v[98:99] op_sel_hi:[1,0,1]
	v_pk_fma_f32 v[100:101], v[144:145], v[52:53], v[100:101] op_sel_hi:[1,0,1]
	v_pk_fma_f32 v[102:103], v[146:147], v[52:53], v[102:103] op_sel_hi:[1,0,1]
	v_pk_fma_f32 v[104:105], v[148:149], v[52:53], v[104:105] op_sel_hi:[1,0,1]
	v_pk_fma_f32 v[106:107], v[150:151], v[52:53], v[106:107] op_sel_hi:[1,0,1]
	v_pk_fma_f32 v[108:109], v[152:153], v[52:53], v[108:109] op_sel_hi:[1,0,1]
	v_pk_fma_f32 v[110:111], v[154:155], v[52:53], v[110:111] op_sel_hi:[1,0,1]
	v_pk_fma_f32 v[112:113], v[156:157], v[52:53], v[112:113] op_sel_hi:[1,0,1]
	v_pk_fma_f32 v[114:115], v[158:159], v[52:53], v[114:115] op_sel_hi:[1,0,1]
	v_mad_u32_u24 v7, v36, s19, v1
	global_load_dwordx4 v[184:187], v7, s[26:27]
	global_load_dwordx2 v[188:189], v7, s[26:27] offset:16
	s_waitcnt vmcnt(41)
	v_cvt_scalef32_pk32_f32_fp6 v[128:159], v[190:195], 1.0
	v_pk_fma_f32 v[84:85], v[128:129], v[52:53], v[84:85] op_sel:[0,1,0] op_sel_hi:[1,1,1]
	v_pk_fma_f32 v[86:87], v[130:131], v[52:53], v[86:87] op_sel:[0,1,0] op_sel_hi:[1,1,1]
	v_pk_fma_f32 v[88:89], v[132:133], v[52:53], v[88:89] op_sel:[0,1,0] op_sel_hi:[1,1,1]
	v_pk_fma_f32 v[90:91], v[134:135], v[52:53], v[90:91] op_sel:[0,1,0] op_sel_hi:[1,1,1]
	v_pk_fma_f32 v[92:93], v[136:137], v[52:53], v[92:93] op_sel:[0,1,0] op_sel_hi:[1,1,1]
	v_pk_fma_f32 v[94:95], v[138:139], v[52:53], v[94:95] op_sel:[0,1,0] op_sel_hi:[1,1,1]
	v_pk_fma_f32 v[96:97], v[140:141], v[52:53], v[96:97] op_sel:[0,1,0] op_sel_hi:[1,1,1]
	v_pk_fma_f32 v[98:99], v[142:143], v[52:53], v[98:99] op_sel:[0,1,0] op_sel_hi:[1,1,1]
	v_pk_fma_f32 v[100:101], v[144:145], v[52:53], v[100:101] op_sel:[0,1,0] op_sel_hi:[1,1,1]
	v_pk_fma_f32 v[102:103], v[146:147], v[52:53], v[102:103] op_sel:[0,1,0] op_sel_hi:[1,1,1]
	v_pk_fma_f32 v[104:105], v[148:149], v[52:53], v[104:105] op_sel:[0,1,0] op_sel_hi:[1,1,1]
	v_pk_fma_f32 v[106:107], v[150:151], v[52:53], v[106:107] op_sel:[0,1,0] op_sel_hi:[1,1,1]
	v_pk_fma_f32 v[108:109], v[152:153], v[52:53], v[108:109] op_sel:[0,1,0] op_sel_hi:[1,1,1]
	v_pk_fma_f32 v[110:111], v[154:155], v[52:53], v[110:111] op_sel:[0,1,0] op_sel_hi:[1,1,1]
	v_pk_fma_f32 v[112:113], v[156:157], v[52:53], v[112:113] op_sel:[0,1,0] op_sel_hi:[1,1,1]
	v_pk_fma_f32 v[114:115], v[158:159], v[52:53], v[114:115] op_sel:[0,1,0] op_sel_hi:[1,1,1]
	v_mad_u32_u24 v8, v37, s19, v1
	global_load_dwordx4 v[190:193], v8, s[26:27]
	global_load_dwordx2 v[194:195], v8, s[26:27] offset:16
	s_waitcnt vmcnt(41)
	v_cvt_scalef32_pk32_f32_fp6 v[128:159], v[196:201], 1.0
	v_pk_fma_f32 v[84:85], v[128:129], v[54:55], v[84:85] op_sel_hi:[1,0,1]
	v_pk_fma_f32 v[86:87], v[130:131], v[54:55], v[86:87] op_sel_hi:[1,0,1]
	v_pk_fma_f32 v[88:89], v[132:133], v[54:55], v[88:89] op_sel_hi:[1,0,1]
	v_pk_fma_f32 v[90:91], v[134:135], v[54:55], v[90:91] op_sel_hi:[1,0,1]
	v_pk_fma_f32 v[92:93], v[136:137], v[54:55], v[92:93] op_sel_hi:[1,0,1]
	v_pk_fma_f32 v[94:95], v[138:139], v[54:55], v[94:95] op_sel_hi:[1,0,1]
	v_pk_fma_f32 v[96:97], v[140:141], v[54:55], v[96:97] op_sel_hi:[1,0,1]
	v_pk_fma_f32 v[98:99], v[142:143], v[54:55], v[98:99] op_sel_hi:[1,0,1]
	v_pk_fma_f32 v[100:101], v[144:145], v[54:55], v[100:101] op_sel_hi:[1,0,1]
	v_pk_fma_f32 v[102:103], v[146:147], v[54:55], v[102:103] op_sel_hi:[1,0,1]
	v_pk_fma_f32 v[104:105], v[148:149], v[54:55], v[104:105] op_sel_hi:[1,0,1]
	v_pk_fma_f32 v[106:107], v[150:151], v[54:55], v[106:107] op_sel_hi:[1,0,1]
	v_pk_fma_f32 v[108:109], v[152:153], v[54:55], v[108:109] op_sel_hi:[1,0,1]
	v_pk_fma_f32 v[110:111], v[154:155], v[54:55], v[110:111] op_sel_hi:[1,0,1]
	v_pk_fma_f32 v[112:113], v[156:157], v[54:55], v[112:113] op_sel_hi:[1,0,1]
	v_pk_fma_f32 v[114:115], v[158:159], v[54:55], v[114:115] op_sel_hi:[1,0,1]
	v_mad_u32_u24 v7, v38, s19, v1
	global_load_dwordx4 v[196:199], v7, s[26:27]
	global_load_dwordx2 v[200:201], v7, s[26:27] offset:16
	s_waitcnt vmcnt(41)
	v_cvt_scalef32_pk32_f32_fp6 v[128:159], v[202:207], 1.0
	v_pk_fma_f32 v[84:85], v[128:129], v[54:55], v[84:85] op_sel:[0,1,0] op_sel_hi:[1,1,1]
	v_pk_fma_f32 v[86:87], v[130:131], v[54:55], v[86:87] op_sel:[0,1,0] op_sel_hi:[1,1,1]
	v_pk_fma_f32 v[88:89], v[132:133], v[54:55], v[88:89] op_sel:[0,1,0] op_sel_hi:[1,1,1]
	v_pk_fma_f32 v[90:91], v[134:135], v[54:55], v[90:91] op_sel:[0,1,0] op_sel_hi:[1,1,1]
	v_pk_fma_f32 v[92:93], v[136:137], v[54:55], v[92:93] op_sel:[0,1,0] op_sel_hi:[1,1,1]
	v_pk_fma_f32 v[94:95], v[138:139], v[54:55], v[94:95] op_sel:[0,1,0] op_sel_hi:[1,1,1]
	v_pk_fma_f32 v[96:97], v[140:141], v[54:55], v[96:97] op_sel:[0,1,0] op_sel_hi:[1,1,1]
	v_pk_fma_f32 v[98:99], v[142:143], v[54:55], v[98:99] op_sel:[0,1,0] op_sel_hi:[1,1,1]
	v_pk_fma_f32 v[100:101], v[144:145], v[54:55], v[100:101] op_sel:[0,1,0] op_sel_hi:[1,1,1]
	v_pk_fma_f32 v[102:103], v[146:147], v[54:55], v[102:103] op_sel:[0,1,0] op_sel_hi:[1,1,1]
	v_pk_fma_f32 v[104:105], v[148:149], v[54:55], v[104:105] op_sel:[0,1,0] op_sel_hi:[1,1,1]
	v_pk_fma_f32 v[106:107], v[150:151], v[54:55], v[106:107] op_sel:[0,1,0] op_sel_hi:[1,1,1]
	v_pk_fma_f32 v[108:109], v[152:153], v[54:55], v[108:109] op_sel:[0,1,0] op_sel_hi:[1,1,1]
	v_pk_fma_f32 v[110:111], v[154:155], v[54:55], v[110:111] op_sel:[0,1,0] op_sel_hi:[1,1,1]
	v_pk_fma_f32 v[112:113], v[156:157], v[54:55], v[112:113] op_sel:[0,1,0] op_sel_hi:[1,1,1]
	v_pk_fma_f32 v[114:115], v[158:159], v[54:55], v[114:115] op_sel:[0,1,0] op_sel_hi:[1,1,1]
	v_mad_u32_u24 v8, v39, s19, v1
	global_load_dwordx4 v[202:205], v8, s[26:27]
	global_load_dwordx2 v[206:207], v8, s[26:27] offset:16
	s_waitcnt vmcnt(41)
	v_cvt_scalef32_pk32_f32_fp6 v[128:159], v[208:213], 1.0
	v_pk_fma_f32 v[84:85], v[128:129], v[56:57], v[84:85] op_sel_hi:[1,0,1]
	v_pk_fma_f32 v[86:87], v[130:131], v[56:57], v[86:87] op_sel_hi:[1,0,1]
	v_pk_fma_f32 v[88:89], v[132:133], v[56:57], v[88:89] op_sel_hi:[1,0,1]
	v_pk_fma_f32 v[90:91], v[134:135], v[56:57], v[90:91] op_sel_hi:[1,0,1]
	v_pk_fma_f32 v[92:93], v[136:137], v[56:57], v[92:93] op_sel_hi:[1,0,1]
	v_pk_fma_f32 v[94:95], v[138:139], v[56:57], v[94:95] op_sel_hi:[1,0,1]
	v_pk_fma_f32 v[96:97], v[140:141], v[56:57], v[96:97] op_sel_hi:[1,0,1]
	v_pk_fma_f32 v[98:99], v[142:143], v[56:57], v[98:99] op_sel_hi:[1,0,1]
	v_pk_fma_f32 v[100:101], v[144:145], v[56:57], v[100:101] op_sel_hi:[1,0,1]
	v_pk_fma_f32 v[102:103], v[146:147], v[56:57], v[102:103] op_sel_hi:[1,0,1]
	v_pk_fma_f32 v[104:105], v[148:149], v[56:57], v[104:105] op_sel_hi:[1,0,1]
	v_pk_fma_f32 v[106:107], v[150:151], v[56:57], v[106:107] op_sel_hi:[1,0,1]
	v_pk_fma_f32 v[108:109], v[152:153], v[56:57], v[108:109] op_sel_hi:[1,0,1]
	v_pk_fma_f32 v[110:111], v[154:155], v[56:57], v[110:111] op_sel_hi:[1,0,1]
	v_pk_fma_f32 v[112:113], v[156:157], v[56:57], v[112:113] op_sel_hi:[1,0,1]
	v_pk_fma_f32 v[114:115], v[158:159], v[56:57], v[114:115] op_sel_hi:[1,0,1]
	v_mad_u32_u24 v7, v40, s19, v1
	global_load_dwordx4 v[208:211], v7, s[26:27]
	global_load_dwordx2 v[212:213], v7, s[26:27] offset:16
	s_waitcnt vmcnt(41)
	v_cvt_scalef32_pk32_f32_fp6 v[128:159], v[214:219], 1.0
	v_pk_fma_f32 v[84:85], v[128:129], v[56:57], v[84:85] op_sel:[0,1,0] op_sel_hi:[1,1,1]
	v_pk_fma_f32 v[86:87], v[130:131], v[56:57], v[86:87] op_sel:[0,1,0] op_sel_hi:[1,1,1]
	v_pk_fma_f32 v[88:89], v[132:133], v[56:57], v[88:89] op_sel:[0,1,0] op_sel_hi:[1,1,1]
	v_pk_fma_f32 v[90:91], v[134:135], v[56:57], v[90:91] op_sel:[0,1,0] op_sel_hi:[1,1,1]
	v_pk_fma_f32 v[92:93], v[136:137], v[56:57], v[92:93] op_sel:[0,1,0] op_sel_hi:[1,1,1]
	v_pk_fma_f32 v[94:95], v[138:139], v[56:57], v[94:95] op_sel:[0,1,0] op_sel_hi:[1,1,1]
	v_pk_fma_f32 v[96:97], v[140:141], v[56:57], v[96:97] op_sel:[0,1,0] op_sel_hi:[1,1,1]
	v_pk_fma_f32 v[98:99], v[142:143], v[56:57], v[98:99] op_sel:[0,1,0] op_sel_hi:[1,1,1]
	v_pk_fma_f32 v[100:101], v[144:145], v[56:57], v[100:101] op_sel:[0,1,0] op_sel_hi:[1,1,1]
	v_pk_fma_f32 v[102:103], v[146:147], v[56:57], v[102:103] op_sel:[0,1,0] op_sel_hi:[1,1,1]
	v_pk_fma_f32 v[104:105], v[148:149], v[56:57], v[104:105] op_sel:[0,1,0] op_sel_hi:[1,1,1]
	v_pk_fma_f32 v[106:107], v[150:151], v[56:57], v[106:107] op_sel:[0,1,0] op_sel_hi:[1,1,1]
	v_pk_fma_f32 v[108:109], v[152:153], v[56:57], v[108:109] op_sel:[0,1,0] op_sel_hi:[1,1,1]
	v_pk_fma_f32 v[110:111], v[154:155], v[56:57], v[110:111] op_sel:[0,1,0] op_sel_hi:[1,1,1]
	v_pk_fma_f32 v[112:113], v[156:157], v[56:57], v[112:113] op_sel:[0,1,0] op_sel_hi:[1,1,1]
	v_pk_fma_f32 v[114:115], v[158:159], v[56:57], v[114:115] op_sel:[0,1,0] op_sel_hi:[1,1,1]
	v_mad_u32_u24 v8, v41, s19, v1
	global_load_dwordx4 v[214:217], v8, s[26:27]
	global_load_dwordx2 v[218:219], v8, s[26:27] offset:16
	s_waitcnt vmcnt(41)
	v_cvt_scalef32_pk32_f32_fp6 v[128:159], v[220:225], 1.0
	v_pk_fma_f32 v[84:85], v[128:129], v[58:59], v[84:85] op_sel_hi:[1,0,1]
	v_pk_fma_f32 v[86:87], v[130:131], v[58:59], v[86:87] op_sel_hi:[1,0,1]
	v_pk_fma_f32 v[88:89], v[132:133], v[58:59], v[88:89] op_sel_hi:[1,0,1]
	v_pk_fma_f32 v[90:91], v[134:135], v[58:59], v[90:91] op_sel_hi:[1,0,1]
	v_pk_fma_f32 v[92:93], v[136:137], v[58:59], v[92:93] op_sel_hi:[1,0,1]
	v_pk_fma_f32 v[94:95], v[138:139], v[58:59], v[94:95] op_sel_hi:[1,0,1]
	v_pk_fma_f32 v[96:97], v[140:141], v[58:59], v[96:97] op_sel_hi:[1,0,1]
	v_pk_fma_f32 v[98:99], v[142:143], v[58:59], v[98:99] op_sel_hi:[1,0,1]
	v_pk_fma_f32 v[100:101], v[144:145], v[58:59], v[100:101] op_sel_hi:[1,0,1]
	v_pk_fma_f32 v[102:103], v[146:147], v[58:59], v[102:103] op_sel_hi:[1,0,1]
	v_pk_fma_f32 v[104:105], v[148:149], v[58:59], v[104:105] op_sel_hi:[1,0,1]
	v_pk_fma_f32 v[106:107], v[150:151], v[58:59], v[106:107] op_sel_hi:[1,0,1]
	v_pk_fma_f32 v[108:109], v[152:153], v[58:59], v[108:109] op_sel_hi:[1,0,1]
	v_pk_fma_f32 v[110:111], v[154:155], v[58:59], v[110:111] op_sel_hi:[1,0,1]
	v_pk_fma_f32 v[112:113], v[156:157], v[58:59], v[112:113] op_sel_hi:[1,0,1]
	v_pk_fma_f32 v[114:115], v[158:159], v[58:59], v[114:115] op_sel_hi:[1,0,1]
	v_mad_u32_u24 v7, v42, s19, v1
	global_load_dwordx4 v[220:223], v7, s[26:27]
	global_load_dwordx2 v[224:225], v7, s[26:27] offset:16
	s_waitcnt vmcnt(41)
	v_cvt_scalef32_pk32_f32_fp6 v[128:159], v[226:231], 1.0
	v_pk_fma_f32 v[84:85], v[128:129], v[58:59], v[84:85] op_sel:[0,1,0] op_sel_hi:[1,1,1]
	v_pk_fma_f32 v[86:87], v[130:131], v[58:59], v[86:87] op_sel:[0,1,0] op_sel_hi:[1,1,1]
	v_pk_fma_f32 v[88:89], v[132:133], v[58:59], v[88:89] op_sel:[0,1,0] op_sel_hi:[1,1,1]
	v_pk_fma_f32 v[90:91], v[134:135], v[58:59], v[90:91] op_sel:[0,1,0] op_sel_hi:[1,1,1]
	v_pk_fma_f32 v[92:93], v[136:137], v[58:59], v[92:93] op_sel:[0,1,0] op_sel_hi:[1,1,1]
	v_pk_fma_f32 v[94:95], v[138:139], v[58:59], v[94:95] op_sel:[0,1,0] op_sel_hi:[1,1,1]
	v_pk_fma_f32 v[96:97], v[140:141], v[58:59], v[96:97] op_sel:[0,1,0] op_sel_hi:[1,1,1]
	v_pk_fma_f32 v[98:99], v[142:143], v[58:59], v[98:99] op_sel:[0,1,0] op_sel_hi:[1,1,1]
	v_pk_fma_f32 v[100:101], v[144:145], v[58:59], v[100:101] op_sel:[0,1,0] op_sel_hi:[1,1,1]
	v_pk_fma_f32 v[102:103], v[146:147], v[58:59], v[102:103] op_sel:[0,1,0] op_sel_hi:[1,1,1]
	v_pk_fma_f32 v[104:105], v[148:149], v[58:59], v[104:105] op_sel:[0,1,0] op_sel_hi:[1,1,1]
	v_pk_fma_f32 v[106:107], v[150:151], v[58:59], v[106:107] op_sel:[0,1,0] op_sel_hi:[1,1,1]
	v_pk_fma_f32 v[108:109], v[152:153], v[58:59], v[108:109] op_sel:[0,1,0] op_sel_hi:[1,1,1]
	v_pk_fma_f32 v[110:111], v[154:155], v[58:59], v[110:111] op_sel:[0,1,0] op_sel_hi:[1,1,1]
	v_pk_fma_f32 v[112:113], v[156:157], v[58:59], v[112:113] op_sel:[0,1,0] op_sel_hi:[1,1,1]
	v_pk_fma_f32 v[114:115], v[158:159], v[58:59], v[114:115] op_sel:[0,1,0] op_sel_hi:[1,1,1]
	v_mad_u32_u24 v8, v43, s19, v1
	global_load_dwordx4 v[226:229], v8, s[26:27]
	global_load_dwordx2 v[230:231], v8, s[26:27] offset:16
	s_waitcnt vmcnt(41)
	v_cvt_scalef32_pk32_f32_fp6 v[128:159], v[232:237], 1.0
	v_pk_fma_f32 v[84:85], v[128:129], v[60:61], v[84:85] op_sel_hi:[1,0,1]
	v_pk_fma_f32 v[86:87], v[130:131], v[60:61], v[86:87] op_sel_hi:[1,0,1]
	v_pk_fma_f32 v[88:89], v[132:133], v[60:61], v[88:89] op_sel_hi:[1,0,1]
	v_pk_fma_f32 v[90:91], v[134:135], v[60:61], v[90:91] op_sel_hi:[1,0,1]
	v_pk_fma_f32 v[92:93], v[136:137], v[60:61], v[92:93] op_sel_hi:[1,0,1]
	v_pk_fma_f32 v[94:95], v[138:139], v[60:61], v[94:95] op_sel_hi:[1,0,1]
	v_pk_fma_f32 v[96:97], v[140:141], v[60:61], v[96:97] op_sel_hi:[1,0,1]
	v_pk_fma_f32 v[98:99], v[142:143], v[60:61], v[98:99] op_sel_hi:[1,0,1]
	v_pk_fma_f32 v[100:101], v[144:145], v[60:61], v[100:101] op_sel_hi:[1,0,1]
	v_pk_fma_f32 v[102:103], v[146:147], v[60:61], v[102:103] op_sel_hi:[1,0,1]
	v_pk_fma_f32 v[104:105], v[148:149], v[60:61], v[104:105] op_sel_hi:[1,0,1]
	v_pk_fma_f32 v[106:107], v[150:151], v[60:61], v[106:107] op_sel_hi:[1,0,1]
	v_pk_fma_f32 v[108:109], v[152:153], v[60:61], v[108:109] op_sel_hi:[1,0,1]
	v_pk_fma_f32 v[110:111], v[154:155], v[60:61], v[110:111] op_sel_hi:[1,0,1]
	v_pk_fma_f32 v[112:113], v[156:157], v[60:61], v[112:113] op_sel_hi:[1,0,1]
	v_pk_fma_f32 v[114:115], v[158:159], v[60:61], v[114:115] op_sel_hi:[1,0,1]
	v_mad_u32_u24 v7, v44, s19, v1
	global_load_dwordx4 v[232:235], v7, s[26:27]
	global_load_dwordx2 v[236:237], v7, s[26:27] offset:16
	s_waitcnt vmcnt(41)
	v_cvt_scalef32_pk32_f32_fp6 v[128:159], v[238:243], 1.0
	v_pk_fma_f32 v[84:85], v[128:129], v[60:61], v[84:85] op_sel:[0,1,0] op_sel_hi:[1,1,1]
	v_pk_fma_f32 v[86:87], v[130:131], v[60:61], v[86:87] op_sel:[0,1,0] op_sel_hi:[1,1,1]
	v_pk_fma_f32 v[88:89], v[132:133], v[60:61], v[88:89] op_sel:[0,1,0] op_sel_hi:[1,1,1]
	v_pk_fma_f32 v[90:91], v[134:135], v[60:61], v[90:91] op_sel:[0,1,0] op_sel_hi:[1,1,1]
	v_pk_fma_f32 v[92:93], v[136:137], v[60:61], v[92:93] op_sel:[0,1,0] op_sel_hi:[1,1,1]
	v_pk_fma_f32 v[94:95], v[138:139], v[60:61], v[94:95] op_sel:[0,1,0] op_sel_hi:[1,1,1]
	v_pk_fma_f32 v[96:97], v[140:141], v[60:61], v[96:97] op_sel:[0,1,0] op_sel_hi:[1,1,1]
	v_pk_fma_f32 v[98:99], v[142:143], v[60:61], v[98:99] op_sel:[0,1,0] op_sel_hi:[1,1,1]
	v_pk_fma_f32 v[100:101], v[144:145], v[60:61], v[100:101] op_sel:[0,1,0] op_sel_hi:[1,1,1]
	v_pk_fma_f32 v[102:103], v[146:147], v[60:61], v[102:103] op_sel:[0,1,0] op_sel_hi:[1,1,1]
	v_pk_fma_f32 v[104:105], v[148:149], v[60:61], v[104:105] op_sel:[0,1,0] op_sel_hi:[1,1,1]
	v_pk_fma_f32 v[106:107], v[150:151], v[60:61], v[106:107] op_sel:[0,1,0] op_sel_hi:[1,1,1]
	v_pk_fma_f32 v[108:109], v[152:153], v[60:61], v[108:109] op_sel:[0,1,0] op_sel_hi:[1,1,1]
	v_pk_fma_f32 v[110:111], v[154:155], v[60:61], v[110:111] op_sel:[0,1,0] op_sel_hi:[1,1,1]
	v_pk_fma_f32 v[112:113], v[156:157], v[60:61], v[112:113] op_sel:[0,1,0] op_sel_hi:[1,1,1]
	v_pk_fma_f32 v[114:115], v[158:159], v[60:61], v[114:115] op_sel:[0,1,0] op_sel_hi:[1,1,1]
	v_mad_u32_u24 v8, v45, s19, v1
	global_load_dwordx4 v[238:241], v8, s[26:27]
	global_load_dwordx2 v[242:243], v8, s[26:27] offset:16
	s_waitcnt vmcnt(41)
	v_cvt_scalef32_pk32_f32_fp6 v[128:159], v[244:249], 1.0
	v_pk_fma_f32 v[84:85], v[128:129], v[62:63], v[84:85] op_sel_hi:[1,0,1]
	v_pk_fma_f32 v[86:87], v[130:131], v[62:63], v[86:87] op_sel_hi:[1,0,1]
	v_pk_fma_f32 v[88:89], v[132:133], v[62:63], v[88:89] op_sel_hi:[1,0,1]
	v_pk_fma_f32 v[90:91], v[134:135], v[62:63], v[90:91] op_sel_hi:[1,0,1]
	v_pk_fma_f32 v[92:93], v[136:137], v[62:63], v[92:93] op_sel_hi:[1,0,1]
	v_pk_fma_f32 v[94:95], v[138:139], v[62:63], v[94:95] op_sel_hi:[1,0,1]
	v_pk_fma_f32 v[96:97], v[140:141], v[62:63], v[96:97] op_sel_hi:[1,0,1]
	v_pk_fma_f32 v[98:99], v[142:143], v[62:63], v[98:99] op_sel_hi:[1,0,1]
	v_pk_fma_f32 v[100:101], v[144:145], v[62:63], v[100:101] op_sel_hi:[1,0,1]
	v_pk_fma_f32 v[102:103], v[146:147], v[62:63], v[102:103] op_sel_hi:[1,0,1]
	v_pk_fma_f32 v[104:105], v[148:149], v[62:63], v[104:105] op_sel_hi:[1,0,1]
	v_pk_fma_f32 v[106:107], v[150:151], v[62:63], v[106:107] op_sel_hi:[1,0,1]
	v_pk_fma_f32 v[108:109], v[152:153], v[62:63], v[108:109] op_sel_hi:[1,0,1]
	v_pk_fma_f32 v[110:111], v[154:155], v[62:63], v[110:111] op_sel_hi:[1,0,1]
	v_pk_fma_f32 v[112:113], v[156:157], v[62:63], v[112:113] op_sel_hi:[1,0,1]
	v_pk_fma_f32 v[114:115], v[158:159], v[62:63], v[114:115] op_sel_hi:[1,0,1]
	v_mad_u32_u24 v7, v46, s19, v1
	global_load_dwordx4 v[244:247], v7, s[26:27]
	global_load_dwordx2 v[248:249], v7, s[26:27] offset:16
	s_waitcnt vmcnt(41)
	v_cvt_scalef32_pk32_f32_fp6 v[128:159], v[250:255], 1.0
	v_pk_fma_f32 v[84:85], v[128:129], v[62:63], v[84:85] op_sel:[0,1,0] op_sel_hi:[1,1,1]
	v_pk_fma_f32 v[86:87], v[130:131], v[62:63], v[86:87] op_sel:[0,1,0] op_sel_hi:[1,1,1]
	v_pk_fma_f32 v[88:89], v[132:133], v[62:63], v[88:89] op_sel:[0,1,0] op_sel_hi:[1,1,1]
	v_pk_fma_f32 v[90:91], v[134:135], v[62:63], v[90:91] op_sel:[0,1,0] op_sel_hi:[1,1,1]
	v_pk_fma_f32 v[92:93], v[136:137], v[62:63], v[92:93] op_sel:[0,1,0] op_sel_hi:[1,1,1]
	v_pk_fma_f32 v[94:95], v[138:139], v[62:63], v[94:95] op_sel:[0,1,0] op_sel_hi:[1,1,1]
	v_pk_fma_f32 v[96:97], v[140:141], v[62:63], v[96:97] op_sel:[0,1,0] op_sel_hi:[1,1,1]
	v_pk_fma_f32 v[98:99], v[142:143], v[62:63], v[98:99] op_sel:[0,1,0] op_sel_hi:[1,1,1]
	v_pk_fma_f32 v[100:101], v[144:145], v[62:63], v[100:101] op_sel:[0,1,0] op_sel_hi:[1,1,1]
	v_pk_fma_f32 v[102:103], v[146:147], v[62:63], v[102:103] op_sel:[0,1,0] op_sel_hi:[1,1,1]
	v_pk_fma_f32 v[104:105], v[148:149], v[62:63], v[104:105] op_sel:[0,1,0] op_sel_hi:[1,1,1]
	v_pk_fma_f32 v[106:107], v[150:151], v[62:63], v[106:107] op_sel:[0,1,0] op_sel_hi:[1,1,1]
	v_pk_fma_f32 v[108:109], v[152:153], v[62:63], v[108:109] op_sel:[0,1,0] op_sel_hi:[1,1,1]
	v_pk_fma_f32 v[110:111], v[154:155], v[62:63], v[110:111] op_sel:[0,1,0] op_sel_hi:[1,1,1]
	v_pk_fma_f32 v[112:113], v[156:157], v[62:63], v[112:113] op_sel:[0,1,0] op_sel_hi:[1,1,1]
	v_pk_fma_f32 v[114:115], v[158:159], v[62:63], v[114:115] op_sel:[0,1,0] op_sel_hi:[1,1,1]
	v_mad_u32_u24 v8, v47, s19, v1
	global_load_dwordx4 v[250:253], v8, s[26:27]
	global_load_dwordx2 v[254:255], v8, s[26:27] offset:16
	ds_write_b128 v4, v[84:87] offset:0
	ds_write_b128 v4, v[88:91] offset:16
	ds_write_b128 v4, v[92:95] offset:32
	ds_write_b128 v4, v[96:99] offset:48
	ds_write_b128 v4, v[100:103] offset:64
	ds_write_b128 v4, v[104:107] offset:80
	ds_write_b128 v4, v[108:111] offset:96
	ds_write_b128 v4, v[112:115] offset:112
	ds_read_b128 v[128:131], v5 offset:0
	ds_read_b128 v[132:135], v5 offset:1152
	ds_read_b128 v[136:139], v5 offset:2304
	ds_read_b128 v[140:143], v5 offset:3456
	ds_read_b128 v[144:147], v5 offset:4608
	ds_read_b128 v[148:151], v5 offset:5760
	ds_read_b128 v[152:155], v5 offset:6912
	ds_read_b128 v[156:159], v5 offset:8064
	s_waitcnt lgkmcnt(0)
	v_add_f32_e32 v128, v128, v132
	v_add_f32_e32 v136, v136, v140
	v_add_f32_e32 v144, v144, v148
	v_add_f32_e32 v152, v152, v156
	v_add_f32_e32 v129, v129, v133
	v_add_f32_e32 v137, v137, v141
	v_add_f32_e32 v145, v145, v149
	v_add_f32_e32 v153, v153, v157
	v_add_f32_e32 v130, v130, v134
	v_add_f32_e32 v138, v138, v142
	v_add_f32_e32 v146, v146, v150
	v_add_f32_e32 v154, v154, v158
	v_add_f32_e32 v131, v131, v135
	v_add_f32_e32 v139, v139, v143
	v_add_f32_e32 v147, v147, v151
	v_add_f32_e32 v155, v155, v159
	v_add_f32_e32 v128, v128, v136
	v_add_f32_e32 v144, v144, v152
	v_add_f32_e32 v129, v129, v137
	v_add_f32_e32 v145, v145, v153
	v_add_f32_e32 v130, v130, v138
	v_add_f32_e32 v146, v146, v154
	v_add_f32_e32 v131, v131, v139
	v_add_f32_e32 v147, v147, v155
	v_add_f32_e32 v128, v128, v144
	v_add_f32_e32 v129, v129, v145
	v_add_f32_e32 v130, v130, v146
	v_add_f32_e32 v131, v131, v147
	s_waitcnt vmcnt(40)
	v_add_f32_e32 v116, v80, v128
	v_add_f32_e32 v117, v81, v129
	v_add_f32_e32 v118, v82, v130
	v_add_f32_e32 v119, v83, v131
	global_store_dwordx4 v6, v[116:119], s[34:35]
	v_mul_f32_e32 v9, v116, v116
	v_fmac_f32_e32 v9, v117, v117
	v_fmac_f32_e32 v9, v118, v118
	v_fmac_f32_e32 v9, v119, v119
	s_nop 1
	v_add_f32_dpp v9, v9, v9 quad_perm:[1,0,3,2] row_mask:0xf bank_mask:0xf
	s_nop 1
	v_add_f32_dpp v9, v9, v9 quad_perm:[2,3,0,1] row_mask:0xf bank_mask:0xf
	s_nop 1
	v_add_f32_dpp v9, v9, v9 row_half_mirror row_mask:0xf bank_mask:0xf
	s_nop 1
	v_add_f32_dpp v9, v9, v9 row_mirror row_mask:0xf bank_mask:0xf
	s_nop 1
	v_add_f32_dpp v9, v9, v9 row_bcast:15 row_mask:0xa bank_mask:0xf
	s_nop 1
	v_add_f32_dpp v9, v9, v9 row_bcast:31 row_mask:0xc bank_mask:0xf
	s_nop 1
	s_mov_b64 exec, s[36:37]
	s_nop 1
	global_store_dword v3, v9, s[38:39]
	s_mov_b64 exec, -1
	s_add_u32 s28, s28, 1
	s_add_u32 s40, s28, 0
	s_min_u32 s40, s40, 127
	s_lshl_b32 s40, s40, 8
	s_add_u32 s40, s40, s24
	s_lshl_b32 s29, s40, 13
	s_add_u32 s34, s10, s29
	s_addc_u32 s35, s11, 0
	global_load_dwordx4 v[80:83], v6, s[34:35]
	s_lshl_b32 s29, s40, 5
	s_add_u32 s29, s29, s43
	s_add_u32 s38, s12, s29
	s_addc_u32 s39, s13, 0
	s_add_u32 s40, s28, 2
	s_min_u32 s40, s40, 127
	s_lshl_b32 s40, s40, 8
	s_add_u32 s40, s40, s24
	s_lshl_b32 s29, s40, 9
	s_add_u32 s30, s4, s29
	s_addc_u32 s31, s5, 0
	global_load_dwordx4 v[32:35], v2, s[30:31] offset:0
	global_load_dwordx4 v[36:39], v2, s[30:31] offset:16
	global_load_dwordx4 v[40:43], v2, s[30:31] offset:32
	global_load_dwordx4 v[44:47], v2, s[30:31] offset:48
	s_add_u32 s40, s28, 1
	s_min_u32 s40, s40, 127
	s_lshl_b32 s40, s40, 8
	s_add_u32 s40, s40, s24
	s_lshl_b32 s29, s40, 9
	s_add_u32 s32, s6, s29
	s_addc_u32 s33, s7, 0
	global_load_dwordx4 v[48:51], v2, s[32:33] offset:0
	global_load_dwordx4 v[52:55], v2, s[32:33] offset:16
	global_load_dwordx4 v[56:59], v2, s[32:33] offset:32
	global_load_dwordx4 v[60:63], v2, s[32:33] offset:48
	s_waitcnt vmcnt(41)
	v_cvt_scalef32_pk32_f32_fp6 v[128:159], v[160:165], 1.0
	v_pk_mul_f32 v[84:85], v[128:129], v[64:65] op_sel_hi:[1,0]
	v_pk_mul_f32 v[86:87], v[130:131], v[64:65] op_sel_hi:[1,0]
	v_pk_mul_f32 v[88:89], v[132:133], v[64:65] op_sel_hi:[1,0]
	v_pk_mul_f32 v[90:91], v[134:135], v[64:65] op_sel_hi:[1,0]
	v_pk_mul_f32 v[92:93], v[136:137], v[64:65] op_sel_hi:[1,0]
	v_pk_mul_f32 v[94:95], v[138:139], v[64:65] op_sel_hi:[1,0]
	v_pk_mul_f32 v[96:97], v[140:141], v[64:65] op_sel_hi:[1,0]
	v_pk_mul_f32 v[98:99], v[142:143], v[64:65] op_sel_hi:[1,0]
	v_pk_mul_f32 v[100:101], v[144:145], v[64:65] op_sel_hi:[1,0]
	v_pk_mul_f32 v[102:103], v[146:147], v[64:65] op_sel_hi:[1,0]
	v_pk_mul_f32 v[104:105], v[148:149], v[64:65] op_sel_hi:[1,0]
	v_pk_mul_f32 v[106:107], v[150:151], v[64:65] op_sel_hi:[1,0]
	v_pk_mul_f32 v[108:109], v[152:153], v[64:65] op_sel_hi:[1,0]
	v_pk_mul_f32 v[110:111], v[154:155], v[64:65] op_sel_hi:[1,0]
	v_pk_mul_f32 v[112:113], v[156:157], v[64:65] op_sel_hi:[1,0]
	v_pk_mul_f32 v[114:115], v[158:159], v[64:65] op_sel_hi:[1,0]
	v_mad_u32_u24 v7, v16, s19, v1
	global_load_dwordx4 v[160:163], v7, s[26:27]
	global_load_dwordx2 v[164:165], v7, s[26:27] offset:16
	s_waitcnt vmcnt(41)
	v_cvt_scalef32_pk32_f32_fp6 v[128:159], v[166:171], 1.0
	v_pk_fma_f32 v[84:85], v[128:129], v[64:65], v[84:85] op_sel:[0,1,0] op_sel_hi:[1,1,1]
	v_pk_fma_f32 v[86:87], v[130:131], v[64:65], v[86:87] op_sel:[0,1,0] op_sel_hi:[1,1,1]
	v_pk_fma_f32 v[88:89], v[132:133], v[64:65], v[88:89] op_sel:[0,1,0] op_sel_hi:[1,1,1]
	v_pk_fma_f32 v[90:91], v[134:135], v[64:65], v[90:91] op_sel:[0,1,0] op_sel_hi:[1,1,1]
	v_pk_fma_f32 v[92:93], v[136:137], v[64:65], v[92:93] op_sel:[0,1,0] op_sel_hi:[1,1,1]
	v_pk_fma_f32 v[94:95], v[138:139], v[64:65], v[94:95] op_sel:[0,1,0] op_sel_hi:[1,1,1]
	v_pk_fma_f32 v[96:97], v[140:141], v[64:65], v[96:97] op_sel:[0,1,0] op_sel_hi:[1,1,1]
	v_pk_fma_f32 v[98:99], v[142:143], v[64:65], v[98:99] op_sel:[0,1,0] op_sel_hi:[1,1,1]
	v_pk_fma_f32 v[100:101], v[144:145], v[64:65], v[100:101] op_sel:[0,1,0] op_sel_hi:[1,1,1]
	v_pk_fma_f32 v[102:103], v[146:147], v[64:65], v[102:103] op_sel:[0,1,0] op_sel_hi:[1,1,1]
	v_pk_fma_f32 v[104:105], v[148:149], v[64:65], v[104:105] op_sel:[0,1,0] op_sel_hi:[1,1,1]
	v_pk_fma_f32 v[106:107], v[150:151], v[64:65], v[106:107] op_sel:[0,1,0] op_sel_hi:[1,1,1]
	v_pk_fma_f32 v[108:109], v[152:153], v[64:65], v[108:109] op_sel:[0,1,0] op_sel_hi:[1,1,1]
	v_pk_fma_f32 v[110:111], v[154:155], v[64:65], v[110:111] op_sel:[0,1,0] op_sel_hi:[1,1,1]
	v_pk_fma_f32 v[112:113], v[156:157], v[64:65], v[112:113] op_sel:[0,1,0] op_sel_hi:[1,1,1]
	v_pk_fma_f32 v[114:115], v[158:159], v[64:65], v[114:115] op_sel:[0,1,0] op_sel_hi:[1,1,1]
	v_mad_u32_u24 v8, v17, s19, v1
	global_load_dwordx4 v[166:169], v8, s[26:27]
	global_load_dwordx2 v[170:171], v8, s[26:27] offset:16
	s_waitcnt vmcnt(41)
	v_cvt_scalef32_pk32_f32_fp6 v[128:159], v[172:177], 1.0
	v_pk_fma_f32 v[84:85], v[128:129], v[66:67], v[84:85] op_sel_hi:[1,0,1]
	v_pk_fma_f32 v[86:87], v[130:131], v[66:67], v[86:87] op_sel_hi:[1,0,1]
	v_pk_fma_f32 v[88:89], v[132:133], v[66:67], v[88:89] op_sel_hi:[1,0,1]
	v_pk_fma_f32 v[90:91], v[134:135], v[66:67], v[90:91] op_sel_hi:[1,0,1]
	v_pk_fma_f32 v[92:93], v[136:137], v[66:67], v[92:93] op_sel_hi:[1,0,1]
	v_pk_fma_f32 v[94:95], v[138:139], v[66:67], v[94:95] op_sel_hi:[1,0,1]
	v_pk_fma_f32 v[96:97], v[140:141], v[66:67], v[96:97] op_sel_hi:[1,0,1]
	v_pk_fma_f32 v[98:99], v[142:143], v[66:67], v[98:99] op_sel_hi:[1,0,1]
	v_pk_fma_f32 v[100:101], v[144:145], v[66:67], v[100:101] op_sel_hi:[1,0,1]
	v_pk_fma_f32 v[102:103], v[146:147], v[66:67], v[102:103] op_sel_hi:[1,0,1]
	v_pk_fma_f32 v[104:105], v[148:149], v[66:67], v[104:105] op_sel_hi:[1,0,1]
	v_pk_fma_f32 v[106:107], v[150:151], v[66:67], v[106:107] op_sel_hi:[1,0,1]
	v_pk_fma_f32 v[108:109], v[152:153], v[66:67], v[108:109] op_sel_hi:[1,0,1]
	v_pk_fma_f32 v[110:111], v[154:155], v[66:67], v[110:111] op_sel_hi:[1,0,1]
	v_pk_fma_f32 v[112:113], v[156:157], v[66:67], v[112:113] op_sel_hi:[1,0,1]
	v_pk_fma_f32 v[114:115], v[158:159], v[66:67], v[114:115] op_sel_hi:[1,0,1]
	v_mad_u32_u24 v7, v18, s19, v1
	global_load_dwordx4 v[172:175], v7, s[26:27]
	global_load_dwordx2 v[176:177], v7, s[26:27] offset:16
	s_waitcnt vmcnt(41)
	v_cvt_scalef32_pk32_f32_fp6 v[128:159], v[178:183], 1.0
	v_pk_fma_f32 v[84:85], v[128:129], v[66:67], v[84:85] op_sel:[0,1,0] op_sel_hi:[1,1,1]
	v_pk_fma_f32 v[86:87], v[130:131], v[66:67], v[86:87] op_sel:[0,1,0] op_sel_hi:[1,1,1]
	v_pk_fma_f32 v[88:89], v[132:133], v[66:67], v[88:89] op_sel:[0,1,0] op_sel_hi:[1,1,1]
	v_pk_fma_f32 v[90:91], v[134:135], v[66:67], v[90:91] op_sel:[0,1,0] op_sel_hi:[1,1,1]
	v_pk_fma_f32 v[92:93], v[136:137], v[66:67], v[92:93] op_sel:[0,1,0] op_sel_hi:[1,1,1]
	v_pk_fma_f32 v[94:95], v[138:139], v[66:67], v[94:95] op_sel:[0,1,0] op_sel_hi:[1,1,1]
	v_pk_fma_f32 v[96:97], v[140:141], v[66:67], v[96:97] op_sel:[0,1,0] op_sel_hi:[1,1,1]
	v_pk_fma_f32 v[98:99], v[142:143], v[66:67], v[98:99] op_sel:[0,1,0] op_sel_hi:[1,1,1]
	v_pk_fma_f32 v[100:101], v[144:145], v[66:67], v[100:101] op_sel:[0,1,0] op_sel_hi:[1,1,1]
	v_pk_fma_f32 v[102:103], v[146:147], v[66:67], v[102:103] op_sel:[0,1,0] op_sel_hi:[1,1,1]
	v_pk_fma_f32 v[104:105], v[148:149], v[66:67], v[104:105] op_sel:[0,1,0] op_sel_hi:[1,1,1]
	v_pk_fma_f32 v[106:107], v[150:151], v[66:67], v[106:107] op_sel:[0,1,0] op_sel_hi:[1,1,1]
	v_pk_fma_f32 v[108:109], v[152:153], v[66:67], v[108:109] op_sel:[0,1,0] op_sel_hi:[1,1,1]
	v_pk_fma_f32 v[110:111], v[154:155], v[66:67], v[110:111] op_sel:[0,1,0] op_sel_hi:[1,1,1]
	v_pk_fma_f32 v[112:113], v[156:157], v[66:67], v[112:113] op_sel:[0,1,0] op_sel_hi:[1,1,1]
	v_pk_fma_f32 v[114:115], v[158:159], v[66:67], v[114:115] op_sel:[0,1,0] op_sel_hi:[1,1,1]
	v_mad_u32_u24 v8, v19, s19, v1
	global_load_dwordx4 v[178:181], v8, s[26:27]
	global_load_dwordx2 v[182:183], v8, s[26:27] offset:16
	s_waitcnt vmcnt(41)
	v_cvt_scalef32_pk32_f32_fp6 v[128:159], v[184:189], 1.0
	v_pk_fma_f32 v[84:85], v[128:129], v[68:69], v[84:85] op_sel_hi:[1,0,1]
	v_pk_fma_f32 v[86:87], v[130:131], v[68:69], v[86:87] op_sel_hi:[1,0,1]
	v_pk_fma_f32 v[88:89], v[132:133], v[68:69], v[88:89] op_sel_hi:[1,0,1]
	v_pk_fma_f32 v[90:91], v[134:135], v[68:69], v[90:91] op_sel_hi:[1,0,1]
	v_pk_fma_f32 v[92:93], v[136:137], v[68:69], v[92:93] op_sel_hi:[1,0,1]
	v_pk_fma_f32 v[94:95], v[138:139], v[68:69], v[94:95] op_sel_hi:[1,0,1]
	v_pk_fma_f32 v[96:97], v[140:141], v[68:69], v[96:97] op_sel_hi:[1,0,1]
	v_pk_fma_f32 v[98:99], v[142:143], v[68:69], v[98:99] op_sel_hi:[1,0,1]
	v_pk_fma_f32 v[100:101], v[144:145], v[68:69], v[100:101] op_sel_hi:[1,0,1]
	v_pk_fma_f32 v[102:103], v[146:147], v[68:69], v[102:103] op_sel_hi:[1,0,1]
	v_pk_fma_f32 v[104:105], v[148:149], v[68:69], v[104:105] op_sel_hi:[1,0,1]
	v_pk_fma_f32 v[106:107], v[150:151], v[68:69], v[106:107] op_sel_hi:[1,0,1]
	v_pk_fma_f32 v[108:109], v[152:153], v[68:69], v[108:109] op_sel_hi:[1,0,1]
	v_pk_fma_f32 v[110:111], v[154:155], v[68:69], v[110:111] op_sel_hi:[1,0,1]
	v_pk_fma_f32 v[112:113], v[156:157], v[68:69], v[112:113] op_sel_hi:[1,0,1]
	v_pk_fma_f32 v[114:115], v[158:159], v[68:69], v[114:115] op_sel_hi:[1,0,1]
	v_mad_u32_u24 v7, v20, s19, v1
	global_load_dwordx4 v[184:187], v7, s[26:27]
	global_load_dwordx2 v[188:189], v7, s[26:27] offset:16
	s_waitcnt vmcnt(41)
	v_cvt_scalef32_pk32_f32_fp6 v[128:159], v[190:195], 1.0
	v_pk_fma_f32 v[84:85], v[128:129], v[68:69], v[84:85] op_sel:[0,1,0] op_sel_hi:[1,1,1]
	v_pk_fma_f32 v[86:87], v[130:131], v[68:69], v[86:87] op_sel:[0,1,0] op_sel_hi:[1,1,1]
	v_pk_fma_f32 v[88:89], v[132:133], v[68:69], v[88:89] op_sel:[0,1,0] op_sel_hi:[1,1,1]
	v_pk_fma_f32 v[90:91], v[134:135], v[68:69], v[90:91] op_sel:[0,1,0] op_sel_hi:[1,1,1]
	v_pk_fma_f32 v[92:93], v[136:137], v[68:69], v[92:93] op_sel:[0,1,0] op_sel_hi:[1,1,1]
	v_pk_fma_f32 v[94:95], v[138:139], v[68:69], v[94:95] op_sel:[0,1,0] op_sel_hi:[1,1,1]
	v_pk_fma_f32 v[96:97], v[140:141], v[68:69], v[96:97] op_sel:[0,1,0] op_sel_hi:[1,1,1]
	v_pk_fma_f32 v[98:99], v[142:143], v[68:69], v[98:99] op_sel:[0,1,0] op_sel_hi:[1,1,1]
	v_pk_fma_f32 v[100:101], v[144:145], v[68:69], v[100:101] op_sel:[0,1,0] op_sel_hi:[1,1,1]
	v_pk_fma_f32 v[102:103], v[146:147], v[68:69], v[102:103] op_sel:[0,1,0] op_sel_hi:[1,1,1]
	v_pk_fma_f32 v[104:105], v[148:149], v[68:69], v[104:105] op_sel:[0,1,0] op_sel_hi:[1,1,1]
	v_pk_fma_f32 v[106:107], v[150:151], v[68:69], v[106:107] op_sel:[0,1,0] op_sel_hi:[1,1,1]
	v_pk_fma_f32 v[108:109], v[152:153], v[68:69], v[108:109] op_sel:[0,1,0] op_sel_hi:[1,1,1]
	v_pk_fma_f32 v[110:111], v[154:155], v[68:69], v[110:111] op_sel:[0,1,0] op_sel_hi:[1,1,1]
	v_pk_fma_f32 v[112:113], v[156:157], v[68:69], v[112:113] op_sel:[0,1,0] op_sel_hi:[1,1,1]
	v_pk_fma_f32 v[114:115], v[158:159], v[68:69], v[114:115] op_sel:[0,1,0] op_sel_hi:[1,1,1]
	v_mad_u32_u24 v8, v21, s19, v1
	global_load_dwordx4 v[190:193], v8, s[26:27]
	global_load_dwordx2 v[194:195], v8, s[26:27] offset:16
	s_waitcnt vmcnt(41)
	v_cvt_scalef32_pk32_f32_fp6 v[128:159], v[196:201], 1.0
	v_pk_fma_f32 v[84:85], v[128:129], v[70:71], v[84:85] op_sel_hi:[1,0,1]
	v_pk_fma_f32 v[86:87], v[130:131], v[70:71], v[86:87] op_sel_hi:[1,0,1]
	v_pk_fma_f32 v[88:89], v[132:133], v[70:71], v[88:89] op_sel_hi:[1,0,1]
	v_pk_fma_f32 v[90:91], v[134:135], v[70:71], v[90:91] op_sel_hi:[1,0,1]
	v_pk_fma_f32 v[92:93], v[136:137], v[70:71], v[92:93] op_sel_hi:[1,0,1]
	v_pk_fma_f32 v[94:95], v[138:139], v[70:71], v[94:95] op_sel_hi:[1,0,1]
	v_pk_fma_f32 v[96:97], v[140:141], v[70:71], v[96:97] op_sel_hi:[1,0,1]
	v_pk_fma_f32 v[98:99], v[142:143], v[70:71], v[98:99] op_sel_hi:[1,0,1]
	v_pk_fma_f32 v[100:101], v[144:145], v[70:71], v[100:101] op_sel_hi:[1,0,1]
	v_pk_fma_f32 v[102:103], v[146:147], v[70:71], v[102:103] op_sel_hi:[1,0,1]
	v_pk_fma_f32 v[104:105], v[148:149], v[70:71], v[104:105] op_sel_hi:[1,0,1]
	v_pk_fma_f32 v[106:107], v[150:151], v[70:71], v[106:107] op_sel_hi:[1,0,1]
	v_pk_fma_f32 v[108:109], v[152:153], v[70:71], v[108:109] op_sel_hi:[1,0,1]
	v_pk_fma_f32 v[110:111], v[154:155], v[70:71], v[110:111] op_sel_hi:[1,0,1]
	v_pk_fma_f32 v[112:113], v[156:157], v[70:71], v[112:113] op_sel_hi:[1,0,1]
	v_pk_fma_f32 v[114:115], v[158:159], v[70:71], v[114:115] op_sel_hi:[1,0,1]
	v_mad_u32_u24 v7, v22, s19, v1
	global_load_dwordx4 v[196:199], v7, s[26:27]
	global_load_dwordx2 v[200:201], v7, s[26:27] offset:16
	s_waitcnt vmcnt(41)
	v_cvt_scalef32_pk32_f32_fp6 v[128:159], v[202:207], 1.0
	v_pk_fma_f32 v[84:85], v[128:129], v[70:71], v[84:85] op_sel:[0,1,0] op_sel_hi:[1,1,1]
	v_pk_fma_f32 v[86:87], v[130:131], v[70:71], v[86:87] op_sel:[0,1,0] op_sel_hi:[1,1,1]
	v_pk_fma_f32 v[88:89], v[132:133], v[70:71], v[88:89] op_sel:[0,1,0] op_sel_hi:[1,1,1]
	v_pk_fma_f32 v[90:91], v[134:135], v[70:71], v[90:91] op_sel:[0,1,0] op_sel_hi:[1,1,1]
	v_pk_fma_f32 v[92:93], v[136:137], v[70:71], v[92:93] op_sel:[0,1,0] op_sel_hi:[1,1,1]
	v_pk_fma_f32 v[94:95], v[138:139], v[70:71], v[94:95] op_sel:[0,1,0] op_sel_hi:[1,1,1]
	v_pk_fma_f32 v[96:97], v[140:141], v[70:71], v[96:97] op_sel:[0,1,0] op_sel_hi:[1,1,1]
	v_pk_fma_f32 v[98:99], v[142:143], v[70:71], v[98:99] op_sel:[0,1,0] op_sel_hi:[1,1,1]
	v_pk_fma_f32 v[100:101], v[144:145], v[70:71], v[100:101] op_sel:[0,1,0] op_sel_hi:[1,1,1]
	v_pk_fma_f32 v[102:103], v[146:147], v[70:71], v[102:103] op_sel:[0,1,0] op_sel_hi:[1,1,1]
	v_pk_fma_f32 v[104:105], v[148:149], v[70:71], v[104:105] op_sel:[0,1,0] op_sel_hi:[1,1,1]
	v_pk_fma_f32 v[106:107], v[150:151], v[70:71], v[106:107] op_sel:[0,1,0] op_sel_hi:[1,1,1]
	v_pk_fma_f32 v[108:109], v[152:153], v[70:71], v[108:109] op_sel:[0,1,0] op_sel_hi:[1,1,1]
	v_pk_fma_f32 v[110:111], v[154:155], v[70:71], v[110:111] op_sel:[0,1,0] op_sel_hi:[1,1,1]
	v_pk_fma_f32 v[112:113], v[156:157], v[70:71], v[112:113] op_sel:[0,1,0] op_sel_hi:[1,1,1]
	v_pk_fma_f32 v[114:115], v[158:159], v[70:71], v[114:115] op_sel:[0,1,0] op_sel_hi:[1,1,1]
	v_mad_u32_u24 v8, v23, s19, v1
	global_load_dwordx4 v[202:205], v8, s[26:27]
	global_load_dwordx2 v[206:207], v8, s[26:27] offset:16
	s_waitcnt vmcnt(41)
	v_cvt_scalef32_pk32_f32_fp6 v[128:159], v[208:213], 1.0
	v_pk_fma_f32 v[84:85], v[128:129], v[72:73], v[84:85] op_sel_hi:[1,0,1]
	v_pk_fma_f32 v[86:87], v[130:131], v[72:73], v[86:87] op_sel_hi:[1,0,1]
	v_pk_fma_f32 v[88:89], v[132:133], v[72:73], v[88:89] op_sel_hi:[1,0,1]
	v_pk_fma_f32 v[90:91], v[134:135], v[72:73], v[90:91] op_sel_hi:[1,0,1]
	v_pk_fma_f32 v[92:93], v[136:137], v[72:73], v[92:93] op_sel_hi:[1,0,1]
	v_pk_fma_f32 v[94:95], v[138:139], v[72:73], v[94:95] op_sel_hi:[1,0,1]
	v_pk_fma_f32 v[96:97], v[140:141], v[72:73], v[96:97] op_sel_hi:[1,0,1]
	v_pk_fma_f32 v[98:99], v[142:143], v[72:73], v[98:99] op_sel_hi:[1,0,1]
	v_pk_fma_f32 v[100:101], v[144:145], v[72:73], v[100:101] op_sel_hi:[1,0,1]
	v_pk_fma_f32 v[102:103], v[146:147], v[72:73], v[102:103] op_sel_hi:[1,0,1]
	v_pk_fma_f32 v[104:105], v[148:149], v[72:73], v[104:105] op_sel_hi:[1,0,1]
	v_pk_fma_f32 v[106:107], v[150:151], v[72:73], v[106:107] op_sel_hi:[1,0,1]
	v_pk_fma_f32 v[108:109], v[152:153], v[72:73], v[108:109] op_sel_hi:[1,0,1]
	v_pk_fma_f32 v[110:111], v[154:155], v[72:73], v[110:111] op_sel_hi:[1,0,1]
	v_pk_fma_f32 v[112:113], v[156:157], v[72:73], v[112:113] op_sel_hi:[1,0,1]
	v_pk_fma_f32 v[114:115], v[158:159], v[72:73], v[114:115] op_sel_hi:[1,0,1]
	v_mad_u32_u24 v7, v24, s19, v1
	global_load_dwordx4 v[208:211], v7, s[26:27]
	global_load_dwordx2 v[212:213], v7, s[26:27] offset:16
	s_waitcnt vmcnt(41)
	v_cvt_scalef32_pk32_f32_fp6 v[128:159], v[214:219], 1.0
	v_pk_fma_f32 v[84:85], v[128:129], v[72:73], v[84:85] op_sel:[0,1,0] op_sel_hi:[1,1,1]
	v_pk_fma_f32 v[86:87], v[130:131], v[72:73], v[86:87] op_sel:[0,1,0] op_sel_hi:[1,1,1]
	v_pk_fma_f32 v[88:89], v[132:133], v[72:73], v[88:89] op_sel:[0,1,0] op_sel_hi:[1,1,1]
	v_pk_fma_f32 v[90:91], v[134:135], v[72:73], v[90:91] op_sel:[0,1,0] op_sel_hi:[1,1,1]
	v_pk_fma_f32 v[92:93], v[136:137], v[72:73], v[92:93] op_sel:[0,1,0] op_sel_hi:[1,1,1]
	v_pk_fma_f32 v[94:95], v[138:139], v[72:73], v[94:95] op_sel:[0,1,0] op_sel_hi:[1,1,1]
	v_pk_fma_f32 v[96:97], v[140:141], v[72:73], v[96:97] op_sel:[0,1,0] op_sel_hi:[1,1,1]
	v_pk_fma_f32 v[98:99], v[142:143], v[72:73], v[98:99] op_sel:[0,1,0] op_sel_hi:[1,1,1]
	v_pk_fma_f32 v[100:101], v[144:145], v[72:73], v[100:101] op_sel:[0,1,0] op_sel_hi:[1,1,1]
	v_pk_fma_f32 v[102:103], v[146:147], v[72:73], v[102:103] op_sel:[0,1,0] op_sel_hi:[1,1,1]
	v_pk_fma_f32 v[104:105], v[148:149], v[72:73], v[104:105] op_sel:[0,1,0] op_sel_hi:[1,1,1]
	v_pk_fma_f32 v[106:107], v[150:151], v[72:73], v[106:107] op_sel:[0,1,0] op_sel_hi:[1,1,1]
	v_pk_fma_f32 v[108:109], v[152:153], v[72:73], v[108:109] op_sel:[0,1,0] op_sel_hi:[1,1,1]
	v_pk_fma_f32 v[110:111], v[154:155], v[72:73], v[110:111] op_sel:[0,1,0] op_sel_hi:[1,1,1]
	v_pk_fma_f32 v[112:113], v[156:157], v[72:73], v[112:113] op_sel:[0,1,0] op_sel_hi:[1,1,1]
	v_pk_fma_f32 v[114:115], v[158:159], v[72:73], v[114:115] op_sel:[0,1,0] op_sel_hi:[1,1,1]
	v_mad_u32_u24 v8, v25, s19, v1
	global_load_dwordx4 v[214:217], v8, s[26:27]
	global_load_dwordx2 v[218:219], v8, s[26:27] offset:16
	s_waitcnt vmcnt(41)
	v_cvt_scalef32_pk32_f32_fp6 v[128:159], v[220:225], 1.0
	v_pk_fma_f32 v[84:85], v[128:129], v[74:75], v[84:85] op_sel_hi:[1,0,1]
	v_pk_fma_f32 v[86:87], v[130:131], v[74:75], v[86:87] op_sel_hi:[1,0,1]
	v_pk_fma_f32 v[88:89], v[132:133], v[74:75], v[88:89] op_sel_hi:[1,0,1]
	v_pk_fma_f32 v[90:91], v[134:135], v[74:75], v[90:91] op_sel_hi:[1,0,1]
	v_pk_fma_f32 v[92:93], v[136:137], v[74:75], v[92:93] op_sel_hi:[1,0,1]
	v_pk_fma_f32 v[94:95], v[138:139], v[74:75], v[94:95] op_sel_hi:[1,0,1]
	v_pk_fma_f32 v[96:97], v[140:141], v[74:75], v[96:97] op_sel_hi:[1,0,1]
	v_pk_fma_f32 v[98:99], v[142:143], v[74:75], v[98:99] op_sel_hi:[1,0,1]
	v_pk_fma_f32 v[100:101], v[144:145], v[74:75], v[100:101] op_sel_hi:[1,0,1]
	v_pk_fma_f32 v[102:103], v[146:147], v[74:75], v[102:103] op_sel_hi:[1,0,1]
	v_pk_fma_f32 v[104:105], v[148:149], v[74:75], v[104:105] op_sel_hi:[1,0,1]
	v_pk_fma_f32 v[106:107], v[150:151], v[74:75], v[106:107] op_sel_hi:[1,0,1]
	v_pk_fma_f32 v[108:109], v[152:153], v[74:75], v[108:109] op_sel_hi:[1,0,1]
	v_pk_fma_f32 v[110:111], v[154:155], v[74:75], v[110:111] op_sel_hi:[1,0,1]
	v_pk_fma_f32 v[112:113], v[156:157], v[74:75], v[112:113] op_sel_hi:[1,0,1]
	v_pk_fma_f32 v[114:115], v[158:159], v[74:75], v[114:115] op_sel_hi:[1,0,1]
	v_mad_u32_u24 v7, v26, s19, v1
	global_load_dwordx4 v[220:223], v7, s[26:27]
	global_load_dwordx2 v[224:225], v7, s[26:27] offset:16
	s_waitcnt vmcnt(41)
	v_cvt_scalef32_pk32_f32_fp6 v[128:159], v[226:231], 1.0
	v_pk_fma_f32 v[84:85], v[128:129], v[74:75], v[84:85] op_sel:[0,1,0] op_sel_hi:[1,1,1]
	v_pk_fma_f32 v[86:87], v[130:131], v[74:75], v[86:87] op_sel:[0,1,0] op_sel_hi:[1,1,1]
	v_pk_fma_f32 v[88:89], v[132:133], v[74:75], v[88:89] op_sel:[0,1,0] op_sel_hi:[1,1,1]
	v_pk_fma_f32 v[90:91], v[134:135], v[74:75], v[90:91] op_sel:[0,1,0] op_sel_hi:[1,1,1]
	v_pk_fma_f32 v[92:93], v[136:137], v[74:75], v[92:93] op_sel:[0,1,0] op_sel_hi:[1,1,1]
	v_pk_fma_f32 v[94:95], v[138:139], v[74:75], v[94:95] op_sel:[0,1,0] op_sel_hi:[1,1,1]
	v_pk_fma_f32 v[96:97], v[140:141], v[74:75], v[96:97] op_sel:[0,1,0] op_sel_hi:[1,1,1]
	v_pk_fma_f32 v[98:99], v[142:143], v[74:75], v[98:99] op_sel:[0,1,0] op_sel_hi:[1,1,1]
	v_pk_fma_f32 v[100:101], v[144:145], v[74:75], v[100:101] op_sel:[0,1,0] op_sel_hi:[1,1,1]
	v_pk_fma_f32 v[102:103], v[146:147], v[74:75], v[102:103] op_sel:[0,1,0] op_sel_hi:[1,1,1]
	v_pk_fma_f32 v[104:105], v[148:149], v[74:75], v[104:105] op_sel:[0,1,0] op_sel_hi:[1,1,1]
	v_pk_fma_f32 v[106:107], v[150:151], v[74:75], v[106:107] op_sel:[0,1,0] op_sel_hi:[1,1,1]
	v_pk_fma_f32 v[108:109], v[152:153], v[74:75], v[108:109] op_sel:[0,1,0] op_sel_hi:[1,1,1]
	v_pk_fma_f32 v[110:111], v[154:155], v[74:75], v[110:111] op_sel:[0,1,0] op_sel_hi:[1,1,1]
	v_pk_fma_f32 v[112:113], v[156:157], v[74:75], v[112:113] op_sel:[0,1,0] op_sel_hi:[1,1,1]
	v_pk_fma_f32 v[114:115], v[158:159], v[74:75], v[114:115] op_sel:[0,1,0] op_sel_hi:[1,1,1]
	v_mad_u32_u24 v8, v27, s19, v1
	global_load_dwordx4 v[226:229], v8, s[26:27]
	global_load_dwordx2 v[230:231], v8, s[26:27] offset:16
	s_waitcnt vmcnt(41)
	v_cvt_scalef32_pk32_f32_fp6 v[128:159], v[232:237], 1.0
	v_pk_fma_f32 v[84:85], v[128:129], v[76:77], v[84:85] op_sel_hi:[1,0,1]
	v_pk_fma_f32 v[86:87], v[130:131], v[76:77], v[86:87] op_sel_hi:[1,0,1]
	v_pk_fma_f32 v[88:89], v[132:133], v[76:77], v[88:89] op_sel_hi:[1,0,1]
	v_pk_fma_f32 v[90:91], v[134:135], v[76:77], v[90:91] op_sel_hi:[1,0,1]
	v_pk_fma_f32 v[92:93], v[136:137], v[76:77], v[92:93] op_sel_hi:[1,0,1]
	v_pk_fma_f32 v[94:95], v[138:139], v[76:77], v[94:95] op_sel_hi:[1,0,1]
	v_pk_fma_f32 v[96:97], v[140:141], v[76:77], v[96:97] op_sel_hi:[1,0,1]
	v_pk_fma_f32 v[98:99], v[142:143], v[76:77], v[98:99] op_sel_hi:[1,0,1]
	v_pk_fma_f32 v[100:101], v[144:145], v[76:77], v[100:101] op_sel_hi:[1,0,1]
	v_pk_fma_f32 v[102:103], v[146:147], v[76:77], v[102:103] op_sel_hi:[1,0,1]
	v_pk_fma_f32 v[104:105], v[148:149], v[76:77], v[104:105] op_sel_hi:[1,0,1]
	v_pk_fma_f32 v[106:107], v[150:151], v[76:77], v[106:107] op_sel_hi:[1,0,1]
	v_pk_fma_f32 v[108:109], v[152:153], v[76:77], v[108:109] op_sel_hi:[1,0,1]
	v_pk_fma_f32 v[110:111], v[154:155], v[76:77], v[110:111] op_sel_hi:[1,0,1]
	v_pk_fma_f32 v[112:113], v[156:157], v[76:77], v[112:113] op_sel_hi:[1,0,1]
	v_pk_fma_f32 v[114:115], v[158:159], v[76:77], v[114:115] op_sel_hi:[1,0,1]
	v_mad_u32_u24 v7, v28, s19, v1
	global_load_dwordx4 v[232:235], v7, s[26:27]
	global_load_dwordx2 v[236:237], v7, s[26:27] offset:16
	s_waitcnt vmcnt(41)
	v_cvt_scalef32_pk32_f32_fp6 v[128:159], v[238:243], 1.0
	v_pk_fma_f32 v[84:85], v[128:129], v[76:77], v[84:85] op_sel:[0,1,0] op_sel_hi:[1,1,1]
	v_pk_fma_f32 v[86:87], v[130:131], v[76:77], v[86:87] op_sel:[0,1,0] op_sel_hi:[1,1,1]
	v_pk_fma_f32 v[88:89], v[132:133], v[76:77], v[88:89] op_sel:[0,1,0] op_sel_hi:[1,1,1]
	v_pk_fma_f32 v[90:91], v[134:135], v[76:77], v[90:91] op_sel:[0,1,0] op_sel_hi:[1,1,1]
	v_pk_fma_f32 v[92:93], v[136:137], v[76:77], v[92:93] op_sel:[0,1,0] op_sel_hi:[1,1,1]
	v_pk_fma_f32 v[94:95], v[138:139], v[76:77], v[94:95] op_sel:[0,1,0] op_sel_hi:[1,1,1]
	v_pk_fma_f32 v[96:97], v[140:141], v[76:77], v[96:97] op_sel:[0,1,0] op_sel_hi:[1,1,1]
	v_pk_fma_f32 v[98:99], v[142:143], v[76:77], v[98:99] op_sel:[0,1,0] op_sel_hi:[1,1,1]
	v_pk_fma_f32 v[100:101], v[144:145], v[76:77], v[100:101] op_sel:[0,1,0] op_sel_hi:[1,1,1]
	v_pk_fma_f32 v[102:103], v[146:147], v[76:77], v[102:103] op_sel:[0,1,0] op_sel_hi:[1,1,1]
	v_pk_fma_f32 v[104:105], v[148:149], v[76:77], v[104:105] op_sel:[0,1,0] op_sel_hi:[1,1,1]
	v_pk_fma_f32 v[106:107], v[150:151], v[76:77], v[106:107] op_sel:[0,1,0] op_sel_hi:[1,1,1]
	v_pk_fma_f32 v[108:109], v[152:153], v[76:77], v[108:109] op_sel:[0,1,0] op_sel_hi:[1,1,1]
	v_pk_fma_f32 v[110:111], v[154:155], v[76:77], v[110:111] op_sel:[0,1,0] op_sel_hi:[1,1,1]
	v_pk_fma_f32 v[112:113], v[156:157], v[76:77], v[112:113] op_sel:[0,1,0] op_sel_hi:[1,1,1]
	v_pk_fma_f32 v[114:115], v[158:159], v[76:77], v[114:115] op_sel:[0,1,0] op_sel_hi:[1,1,1]
	v_mad_u32_u24 v8, v29, s19, v1
	global_load_dwordx4 v[238:241], v8, s[26:27]
	global_load_dwordx2 v[242:243], v8, s[26:27] offset:16
	s_waitcnt vmcnt(41)
	v_cvt_scalef32_pk32_f32_fp6 v[128:159], v[244:249], 1.0
	v_pk_fma_f32 v[84:85], v[128:129], v[78:79], v[84:85] op_sel_hi:[1,0,1]
	v_pk_fma_f32 v[86:87], v[130:131], v[78:79], v[86:87] op_sel_hi:[1,0,1]
	v_pk_fma_f32 v[88:89], v[132:133], v[78:79], v[88:89] op_sel_hi:[1,0,1]
	v_pk_fma_f32 v[90:91], v[134:135], v[78:79], v[90:91] op_sel_hi:[1,0,1]
	v_pk_fma_f32 v[92:93], v[136:137], v[78:79], v[92:93] op_sel_hi:[1,0,1]
	v_pk_fma_f32 v[94:95], v[138:139], v[78:79], v[94:95] op_sel_hi:[1,0,1]
	v_pk_fma_f32 v[96:97], v[140:141], v[78:79], v[96:97] op_sel_hi:[1,0,1]
	v_pk_fma_f32 v[98:99], v[142:143], v[78:79], v[98:99] op_sel_hi:[1,0,1]
	v_pk_fma_f32 v[100:101], v[144:145], v[78:79], v[100:101] op_sel_hi:[1,0,1]
	v_pk_fma_f32 v[102:103], v[146:147], v[78:79], v[102:103] op_sel_hi:[1,0,1]
	v_pk_fma_f32 v[104:105], v[148:149], v[78:79], v[104:105] op_sel_hi:[1,0,1]
	v_pk_fma_f32 v[106:107], v[150:151], v[78:79], v[106:107] op_sel_hi:[1,0,1]
	v_pk_fma_f32 v[108:109], v[152:153], v[78:79], v[108:109] op_sel_hi:[1,0,1]
	v_pk_fma_f32 v[110:111], v[154:155], v[78:79], v[110:111] op_sel_hi:[1,0,1]
	v_pk_fma_f32 v[112:113], v[156:157], v[78:79], v[112:113] op_sel_hi:[1,0,1]
	v_pk_fma_f32 v[114:115], v[158:159], v[78:79], v[114:115] op_sel_hi:[1,0,1]
	v_mad_u32_u24 v7, v30, s19, v1
	global_load_dwordx4 v[244:247], v7, s[26:27]
	global_load_dwordx2 v[248:249], v7, s[26:27] offset:16
	s_waitcnt vmcnt(41)
	v_cvt_scalef32_pk32_f32_fp6 v[128:159], v[250:255], 1.0
	v_pk_fma_f32 v[84:85], v[128:129], v[78:79], v[84:85] op_sel:[0,1,0] op_sel_hi:[1,1,1]
	v_pk_fma_f32 v[86:87], v[130:131], v[78:79], v[86:87] op_sel:[0,1,0] op_sel_hi:[1,1,1]
	v_pk_fma_f32 v[88:89], v[132:133], v[78:79], v[88:89] op_sel:[0,1,0] op_sel_hi:[1,1,1]
	v_pk_fma_f32 v[90:91], v[134:135], v[78:79], v[90:91] op_sel:[0,1,0] op_sel_hi:[1,1,1]
	v_pk_fma_f32 v[92:93], v[136:137], v[78:79], v[92:93] op_sel:[0,1,0] op_sel_hi:[1,1,1]
	v_pk_fma_f32 v[94:95], v[138:139], v[78:79], v[94:95] op_sel:[0,1,0] op_sel_hi:[1,1,1]
	v_pk_fma_f32 v[96:97], v[140:141], v[78:79], v[96:97] op_sel:[0,1,0] op_sel_hi:[1,1,1]
	v_pk_fma_f32 v[98:99], v[142:143], v[78:79], v[98:99] op_sel:[0,1,0] op_sel_hi:[1,1,1]
	v_pk_fma_f32 v[100:101], v[144:145], v[78:79], v[100:101] op_sel:[0,1,0] op_sel_hi:[1,1,1]
	v_pk_fma_f32 v[102:103], v[146:147], v[78:79], v[102:103] op_sel:[0,1,0] op_sel_hi:[1,1,1]
	v_pk_fma_f32 v[104:105], v[148:149], v[78:79], v[104:105] op_sel:[0,1,0] op_sel_hi:[1,1,1]
	v_pk_fma_f32 v[106:107], v[150:151], v[78:79], v[106:107] op_sel:[0,1,0] op_sel_hi:[1,1,1]
	v_pk_fma_f32 v[108:109], v[152:153], v[78:79], v[108:109] op_sel:[0,1,0] op_sel_hi:[1,1,1]
	v_pk_fma_f32 v[110:111], v[154:155], v[78:79], v[110:111] op_sel:[0,1,0] op_sel_hi:[1,1,1]
	v_pk_fma_f32 v[112:113], v[156:157], v[78:79], v[112:113] op_sel:[0,1,0] op_sel_hi:[1,1,1]
	v_pk_fma_f32 v[114:115], v[158:159], v[78:79], v[114:115] op_sel:[0,1,0] op_sel_hi:[1,1,1]
	v_mad_u32_u24 v8, v31, s19, v1
	global_load_dwordx4 v[250:253], v8, s[26:27]
	global_load_dwordx2 v[254:255], v8, s[26:27] offset:16
	ds_write_b128 v4, v[84:87] offset:0
	ds_write_b128 v4, v[88:91] offset:16
	ds_write_b128 v4, v[92:95] offset:32
	ds_write_b128 v4, v[96:99] offset:48
	ds_write_b128 v4, v[100:103] offset:64
	ds_write_b128 v4, v[104:107] offset:80
	ds_write_b128 v4, v[108:111] offset:96
	ds_write_b128 v4, v[112:115] offset:112
	ds_read_b128 v[128:131], v5 offset:0
	ds_read_b128 v[132:135], v5 offset:1152
	ds_read_b128 v[136:139], v5 offset:2304
	ds_read_b128 v[140:143], v5 offset:3456
	ds_read_b128 v[144:147], v5 offset:4608
	ds_read_b128 v[148:151], v5 offset:5760
	ds_read_b128 v[152:155], v5 offset:6912
	ds_read_b128 v[156:159], v5 offset:8064
	s_waitcnt lgkmcnt(0)
	v_add_f32_e32 v128, v128, v132
	v_add_f32_e32 v136, v136, v140
	v_add_f32_e32 v144, v144, v148
	v_add_f32_e32 v152, v152, v156
	v_add_f32_e32 v129, v129, v133
	v_add_f32_e32 v137, v137, v141
	v_add_f32_e32 v145, v145, v149
	v_add_f32_e32 v153, v153, v157
	v_add_f32_e32 v130, v130, v134
	v_add_f32_e32 v138, v138, v142
	v_add_f32_e32 v146, v146, v150
	v_add_f32_e32 v154, v154, v158
	v_add_f32_e32 v131, v131, v135
	v_add_f32_e32 v139, v139, v143
	v_add_f32_e32 v147, v147, v151
	v_add_f32_e32 v155, v155, v159
	v_add_f32_e32 v128, v128, v136
	v_add_f32_e32 v144, v144, v152
	v_add_f32_e32 v129, v129, v137
	v_add_f32_e32 v145, v145, v153
	v_add_f32_e32 v130, v130, v138
	v_add_f32_e32 v146, v146, v154
	v_add_f32_e32 v131, v131, v139
	v_add_f32_e32 v147, v147, v155
	v_add_f32_e32 v128, v128, v144
	v_add_f32_e32 v129, v129, v145
	v_add_f32_e32 v130, v130, v146
	v_add_f32_e32 v131, v131, v147
	s_waitcnt vmcnt(40)
	v_add_f32_e32 v116, v80, v128
	v_add_f32_e32 v117, v81, v129
	v_add_f32_e32 v118, v82, v130
	v_add_f32_e32 v119, v83, v131
	global_store_dwordx4 v6, v[116:119], s[34:35]
	v_mul_f32_e32 v9, v116, v116
	v_fmac_f32_e32 v9, v117, v117
	v_fmac_f32_e32 v9, v118, v118
	v_fmac_f32_e32 v9, v119, v119
	s_nop 1
	v_add_f32_dpp v9, v9, v9 quad_perm:[1,0,3,2] row_mask:0xf bank_mask:0xf
	s_nop 1
	v_add_f32_dpp v9, v9, v9 quad_perm:[2,3,0,1] row_mask:0xf bank_mask:0xf
	s_nop 1
	v_add_f32_dpp v9, v9, v9 row_half_mirror row_mask:0xf bank_mask:0xf
	s_nop 1
	v_add_f32_dpp v9, v9, v9 row_mirror row_mask:0xf bank_mask:0xf
	s_nop 1
	v_add_f32_dpp v9, v9, v9 row_bcast:15 row_mask:0xa bank_mask:0xf
	s_nop 1
	v_add_f32_dpp v9, v9, v9 row_bcast:31 row_mask:0xc bank_mask:0xf
	s_nop 1
	s_mov_b64 exec, s[36:37]
	s_nop 1
	global_store_dword v3, v9, s[38:39]
	s_mov_b64 exec, -1
	s_add_u32 s28, s28, 1
	s_cmp_lt_u32 s28, 128
	s_cbranch_scc1 .Lpb_tokloop
	s_waitcnt vmcnt(0)
	s_waitcnt vmcnt(0) lgkmcnt(0)
	s_barrier
	s_cmp_lg_u32 s21, 0
	s_cbranch_scc1 .Lpb_skip_b
	s_mov_b64 exec, 1
	v_mov_b32_e32 v10, 0x12000
	ds_read_b32 v12, v10
	ds_read_b32 v13, v10 offset:4
	s_getreg_b32 s44, hwreg(HW_REG_XCC_ID, 0, 4)
	s_and_b32 s44, s44, 15
	s_lshl_b32 s44, s44, 2
	s_waitcnt lgkmcnt(0)
	v_readfirstlane_b32 s45, v12
	v_readfirstlane_b32 s46, v13
	v_mov_b32_e32 v10, s44
	v_mov_b32_e32 v11, 1
	global_atomic_add v12, v10, v11, s[14:15] offset:256 sc0
	s_waitcnt vmcnt(0)
	v_readfirstlane_b32 s47, v12
	s_nop 3
	s_add_u32 s47, s47, 1
	s_cmp_lg_u32 s47, s45
	v_mov_b32_e32 v10, 0
	s_cbranch_scc1 .Lpb_notlast_b
	buffer_wbl2 sc1
	s_waitcnt vmcnt(0)
	global_atomic_add v10, v11, s[14:15] offset:320
	s_waitcnt vmcnt(0)

.Lpb_spin_b:
	global_load_dword v12, v10, s[14:15] offset:320 sc1
	s_waitcnt vmcnt(0)
	v_readfirstlane_b32 s42, v12
	s_nop 3
	s_cmp_ge_u32 s42, s46
	s_cbranch_scc1 .Lpb_done_b
	s_add_u32 s41, s41, 1
	s_cmp_gt_u32 s41, 0x8000
	s_cbranch_scc1 .Lpb_done_b
	s_sleep 20
	s_branch .Lpb_spin_b

.Lpb_skip_b:
	s_barrier
	v_lshlrev_b32_e32 v1, 4, v0
	v_add_u32_e32 v8, 0x1000, v1
	global_load_dwordx4 v[16:19], v1, s[16:17] offset:0
	global_load_dwordx4 v[20:23], v1, s[16:17] offset:1024
	global_load_dwordx4 v[24:27], v1, s[16:17] offset:2048
	global_load_dwordx4 v[28:31], v1, s[16:17] offset:3072
	global_load_dwordx4 v[32:35], v8, s[16:17] offset:0
	global_load_dwordx4 v[36:39], v8, s[16:17] offset:1024
	global_load_dwordx4 v[40:43], v8, s[16:17] offset:2048
	global_load_dwordx4 v[44:47], v8, s[16:17] offset:3072
	s_mov_b32 s28, 0
	s_add_u32 s40, s28, 0
	s_min_u32 s40, s40, 15
	s_lshl_b32 s40, s40, 11
	s_add_u32 s40, s40, s20
	s_lshl_b32 s29, s40, 13
	s_add_u32 s34, s10, s29
	s_addc_u32 s35, s11, 0
	global_load_dwordx4 v[48:51], v1, s[34:35] offset:0
	global_load_dwordx4 v[52:55], v1, s[34:35] offset:1024
	global_load_dwordx4 v[56:59], v1, s[34:35] offset:2048
	global_load_dwordx4 v[60:63], v1, s[34:35] offset:3072
	global_load_dwordx4 v[64:67], v8, s[34:35] offset:0
	global_load_dwordx4 v[68:71], v8, s[34:35] offset:1024
	global_load_dwordx4 v[72:75], v8, s[34:35] offset:2048
	global_load_dwordx4 v[76:79], v8, s[34:35] offset:3072
	s_lshl_b32 s29, s40, 5
	s_add_u32 s38, s12, s29
	s_addc_u32 s39, s13, 0
	global_load_dwordx4 v[80:83], v3, s[38:39]
	global_load_dwordx4 v[84:87], v3, s[38:39] offset:16
.Lpb_finloop:
	s_add_u32 s40, s28, 1
	s_min_u32 s40, s40, 15
	s_lshl_b32 s40, s40, 11
	s_add_u32 s40, s40, s20
	s_lshl_b32 s29, s40, 13
	s_add_u32 s44, s10, s29
	s_addc_u32 s45, s11, 0
	global_load_dwordx4 v[96:99], v1, s[44:45] offset:0
	global_load_dwordx4 v[100:103], v1, s[44:45] offset:1024
	global_load_dwordx4 v[104:107], v1, s[44:45] offset:2048
	global_load_dwordx4 v[108:111], v1, s[44:45] offset:3072
	global_load_dwordx4 v[112:115], v8, s[44:45] offset:0
	global_load_dwordx4 v[116:119], v8, s[44:45] offset:1024
	global_load_dwordx4 v[120:123], v8, s[44:45] offset:2048
	global_load_dwordx4 v[124:127], v8, s[44:45] offset:3072
	s_lshl_b32 s29, s40, 5
	s_add_u32 s38, s12, s29
	s_addc_u32 s39, s13, 0
	global_load_dwordx4 v[88:91], v3, s[38:39]
	global_load_dwordx4 v[92:95], v3, s[38:39] offset:16
	s_waitcnt vmcnt(10)
	v_add_f32_e32 v12, v80, v81
	v_add_f32_e32 v13, v82, v83
	v_add_f32_e32 v14, v84, v85
	v_add_f32_e32 v15, v86, v87
	v_add_f32_e32 v12, v12, v13
	v_add_f32_e32 v14, v14, v15
	v_add_f32_e32 v12, v12, v14
	v_mov_b32_e32 v13, 0x358637bd
	v_fmac_f32_e32 v13, 0x3a000000, v12
	v_rsq_f32_e32 v13, v13
	s_nop 0
	v_mul_f32_e32 v48, v48, v13
	v_mul_f32_e32 v49, v49, v13
	v_mul_f32_e32 v50, v50, v13
	v_mul_f32_e32 v51, v51, v13
	v_mul_f32_e32 v52, v52, v13
	v_mul_f32_e32 v53, v53, v13
	v_mul_f32_e32 v54, v54, v13
	v_mul_f32_e32 v55, v55, v13
	v_mul_f32_e32 v56, v56, v13
	v_mul_f32_e32 v57, v57, v13
	v_mul_f32_e32 v58, v58, v13
	v_mul_f32_e32 v59, v59, v13
	v_mul_f32_e32 v60, v60, v13
	v_mul_f32_e32 v61, v61, v13
	v_mul_f32_e32 v62, v62, v13
	v_mul_f32_e32 v63, v63, v13
	v_mul_f32_e32 v64, v64, v13
	v_mul_f32_e32 v65, v65, v13
	v_mul_f32_e32 v66, v66, v13
	v_mul_f32_e32 v67, v67, v13
	v_mul_f32_e32 v68, v68, v13
	v_mul_f32_e32 v69, v69, v13
	v_mul_f32_e32 v70, v70, v13
	v_mul_f32_e32 v71, v71, v13
	v_mul_f32_e32 v72, v72, v13
	v_mul_f32_e32 v73, v73, v13
	v_mul_f32_e32 v74, v74, v13
	v_mul_f32_e32 v75, v75, v13
	v_mul_f32_e32 v76, v76, v13
	v_mul_f32_e32 v77, v77, v13
	v_mul_f32_e32 v78, v78, v13
	v_mul_f32_e32 v79, v79, v13
	v_mul_f32_e32 v48, v48, v16
	v_mul_f32_e32 v49, v49, v17
	v_mul_f32_e32 v50, v50, v18
	v_mul_f32_e32 v51, v51, v19
	v_mul_f32_e32 v52, v52, v20
	v_mul_f32_e32 v53, v53, v21
	v_mul_f32_e32 v54, v54, v22
	v_mul_f32_e32 v55, v55, v23
	v_mul_f32_e32 v56, v56, v24
	v_mul_f32_e32 v57, v57, v25
	v_mul_f32_e32 v58, v58, v26
	v_mul_f32_e32 v59, v59, v27
	v_mul_f32_e32 v60, v60, v28
	v_mul_f32_e32 v61, v61, v29
	v_mul_f32_e32 v62, v62, v30
	v_mul_f32_e32 v63, v63, v31
	v_mul_f32_e32 v64, v64, v32
	v_mul_f32_e32 v65, v65, v33
	v_mul_f32_e32 v66, v66, v34
	v_mul_f32_e32 v67, v67, v35
	v_mul_f32_e32 v68, v68, v36
	v_mul_f32_e32 v69, v69, v37
	v_mul_f32_e32 v70, v70, v38
	v_mul_f32_e32 v71, v71, v39
	v_mul_f32_e32 v72, v72, v40
	v_mul_f32_e32 v73, v73, v41
	v_mul_f32_e32 v74, v74, v42
	v_mul_f32_e32 v75, v75, v43
	v_mul_f32_e32 v76, v76, v44
	v_mul_f32_e32 v77, v77, v45
	v_mul_f32_e32 v78, v78, v46
	v_mul_f32_e32 v79, v79, v47
	global_store_dwordx4 v1, v[48:51], s[34:35] offset:0
	global_store_dwordx4 v1, v[52:55], s[34:35] offset:1024
	global_store_dwordx4 v1, v[56:59], s[34:35] offset:2048
	global_store_dwordx4 v1, v[60:63], s[34:35] offset:3072
	global_store_dwordx4 v8, v[64:67], s[34:35] offset:0
	global_store_dwordx4 v8, v[68:71], s[34:35] offset:1024
	global_store_dwordx4 v8, v[72:75], s[34:35] offset:2048
	global_store_dwordx4 v8, v[76:79], s[34:35] offset:3072
	s_add_u32 s40, s28, 2
	s_min_u32 s40, s40, 15
	s_lshl_b32 s40, s40, 11
	s_add_u32 s40, s40, s20
	s_lshl_b32 s29, s40, 13
	s_add_u32 s34, s10, s29
	s_addc_u32 s35, s11, 0
	global_load_dwordx4 v[48:51], v1, s[34:35] offset:0
	global_load_dwordx4 v[52:55], v1, s[34:35] offset:1024
	global_load_dwordx4 v[56:59], v1, s[34:35] offset:2048
	global_load_dwordx4 v[60:63], v1, s[34:35] offset:3072
	global_load_dwordx4 v[64:67], v8, s[34:35] offset:0
	global_load_dwordx4 v[68:71], v8, s[34:35] offset:1024
	global_load_dwordx4 v[72:75], v8, s[34:35] offset:2048
	global_load_dwordx4 v[76:79], v8, s[34:35] offset:3072
	s_lshl_b32 s29, s40, 5
	s_add_u32 s38, s12, s29
	s_addc_u32 s39, s13, 0
	global_load_dwordx4 v[80:83], v3, s[38:39]
	global_load_dwordx4 v[84:87], v3, s[38:39] offset:16
	s_waitcnt vmcnt(18)
	v_add_f32_e32 v12, v88, v89
	v_add_f32_e32 v13, v90, v91
	v_add_f32_e32 v14, v92, v93
	v_add_f32_e32 v15, v94, v95
	v_add_f32_e32 v12, v12, v13
	v_add_f32_e32 v14, v14, v15
	v_add_f32_e32 v12, v12, v14
	v_mov_b32_e32 v13, 0x358637bd
	v_fmac_f32_e32 v13, 0x3a000000, v12
	v_rsq_f32_e32 v13, v13
	s_nop 0
	v_mul_f32_e32 v96, v96, v13
	v_mul_f32_e32 v97, v97, v13
	v_mul_f32_e32 v98, v98, v13
	v_mul_f32_e32 v99, v99, v13
	v_mul_f32_e32 v100, v100, v13
	v_mul_f32_e32 v101, v101, v13
	v_mul_f32_e32 v102, v102, v13
	v_mul_f32_e32 v103, v103, v13
	v_mul_f32_e32 v104, v104, v13
	v_mul_f32_e32 v105, v105, v13
	v_mul_f32_e32 v106, v106, v13
	v_mul_f32_e32 v107, v107, v13
	v_mul_f32_e32 v108, v108, v13
	v_mul_f32_e32 v109, v109, v13
	v_mul_f32_e32 v110, v110, v13
	v_mul_f32_e32 v111, v111, v13
	v_mul_f32_e32 v112, v112, v13
	v_mul_f32_e32 v113, v113, v13
	v_mul_f32_e32 v114, v114, v13
	v_mul_f32_e32 v115, v115, v13
	v_mul_f32_e32 v116, v116, v13
	v_mul_f32_e32 v117, v117, v13
	v_mul_f32_e32 v118, v118, v13
	v_mul_f32_e32 v119, v119, v13
	v_mul_f32_e32 v120, v120, v13
	v_mul_f32_e32 v121, v121, v13
	v_mul_f32_e32 v122, v122, v13
	v_mul_f32_e32 v123, v123, v13
	v_mul_f32_e32 v124, v124, v13
	v_mul_f32_e32 v125, v125, v13
	v_mul_f32_e32 v126, v126, v13
	v_mul_f32_e32 v127, v127, v13
	v_mul_f32_e32 v96, v96, v16
	v_mul_f32_e32 v97, v97, v17
	v_mul_f32_e32 v98, v98, v18
	v_mul_f32_e32 v99, v99, v19
	v_mul_f32_e32 v100, v100, v20
	v_mul_f32_e32 v101, v101, v21
	v_mul_f32_e32 v102, v102, v22
	v_mul_f32_e32 v103, v103, v23
	v_mul_f32_e32 v104, v104, v24
	v_mul_f32_e32 v105, v105, v25
	v_mul_f32_e32 v106, v106, v26
	v_mul_f32_e32 v107, v107, v27
	v_mul_f32_e32 v108, v108, v28
	v_mul_f32_e32 v109, v109, v29
	v_mul_f32_e32 v110, v110, v30
	v_mul_f32_e32 v111, v111, v31
	v_mul_f32_e32 v112, v112, v32
	v_mul_f32_e32 v113, v113, v33
	v_mul_f32_e32 v114, v114, v34
	v_mul_f32_e32 v115, v115, v35
	v_mul_f32_e32 v116, v116, v36
	v_mul_f32_e32 v117, v117, v37
	v_mul_f32_e32 v118, v118, v38
	v_mul_f32_e32 v119, v119, v39
	v_mul_f32_e32 v120, v120, v40
	v_mul_f32_e32 v121, v121, v41
	v_mul_f32_e32 v122, v122, v42
	v_mul_f32_e32 v123, v123, v43
	v_mul_f32_e32 v124, v124, v44
	v_mul_f32_e32 v125, v125, v45
	v_mul_f32_e32 v126, v126, v46
	v_mul_f32_e32 v127, v127, v47
	global_store_dwordx4 v1, v[96:99], s[44:45] offset:0
	global_store_dwordx4 v1, v[100:103], s[44:45] offset:1024
	global_store_dwordx4 v1, v[104:107], s[44:45] offset:2048
	global_store_dwordx4 v1, v[108:111], s[44:45] offset:3072
	global_store_dwordx4 v8, v[112:115], s[44:45] offset:0
	global_store_dwordx4 v8, v[116:119], s[44:45] offset:1024
	global_store_dwordx4 v8, v[120:123], s[44:45] offset:2048
	global_store_dwordx4 v8, v[124:127], s[44:45] offset:3072
	s_add_u32 s28, s28, 2
	s_cmp_lt_u32 s28, 16
	s_cbranch_scc1 .Lpb_finloop
	s_waitcnt vmcnt(0)
	s_endpgm

	.amdhsa_kernel _Z4mega6Params
		.amdhsa_group_segment_fixed_size 73744
		.amdhsa_private_segment_fixed_size 0
		.amdhsa_kernarg_size 616
		.amdhsa_user_sgpr_count 2
		.amdhsa_user_sgpr_dispatch_ptr 0
		.amdhsa_user_sgpr_queue_ptr 0
		.amdhsa_user_sgpr_kernarg_segment_ptr 1
		.amdhsa_user_sgpr_dispatch_id 0
		.amdhsa_user_sgpr_kernarg_preload_length 0
		.amdhsa_user_sgpr_kernarg_preload_offset 0
		.amdhsa_user_sgpr_private_segment_size 0
		.amdhsa_uses_dynamic_stack 0
		.amdhsa_enable_private_segment 0
		.amdhsa_system_sgpr_workgroup_id_x 1
		.amdhsa_system_sgpr_workgroup_id_y 0
		.amdhsa_system_sgpr_workgroup_id_z 0
		.amdhsa_system_sgpr_workgroup_info 0
		.amdhsa_system_vgpr_workitem_id 2
		.amdhsa_next_free_vgpr 256
		.amdhsa_next_free_sgpr 102
		.amdhsa_accum_offset 256
		.amdhsa_reserve_vcc 1
		.amdhsa_float_round_mode_32 0
		.amdhsa_float_round_mode_16_64 0
		.amdhsa_float_denorm_mode_32 3
		.amdhsa_float_denorm_mode_16_64 3
		.amdhsa_dx10_clamp 1
		.amdhsa_ieee_mode 1
		.amdhsa_fp16_overflow 0
		.amdhsa_tg_split 0
		.amdhsa_exception_fp_ieee_invalid_op 0
		.amdhsa_exception_fp_denorm_src 0
		.amdhsa_exception_fp_ieee_div_zero 0
		.amdhsa_exception_fp_ieee_overflow 0
		.amdhsa_exception_fp_ieee_underflow 0
		.amdhsa_exception_fp_ieee_inexact 0
		.amdhsa_exception_int_div_zero 0
	.end_amdhsa_kernel

amdhsa.kernels:
  - .agpr_count:     0
    .args:
      - .offset:         0
        .size:           360
        .value_kind:     by_value
      - .offset:         360
        .size:           4
        .value_kind:     hidden_block_count_x
      - .offset:         364
        .size:           4
        .value_kind:     hidden_block_count_y
      - .offset:         368
        .size:           4
        .value_kind:     hidden_block_count_z
      - .offset:         372
        .size:           2
        .value_kind:     hidden_group_size_x
      - .offset:         374
        .size:           2
        .value_kind:     hidden_group_size_y
      - .offset:         376
        .size:           2
        .value_kind:     hidden_group_size_z
      - .offset:         378
        .size:           2
        .value_kind:     hidden_remainder_x
      - .offset:         380
        .size:           2
        .value_kind:     hidden_remainder_y
      - .offset:         382
        .size:           2
        .value_kind:     hidden_remainder_z
      - .offset:         400
        .size:           8
        .value_kind:     hidden_global_offset_x
      - .offset:         408
        .size:           8
        .value_kind:     hidden_global_offset_y
      - .offset:         416
        .size:           8
        .value_kind:     hidden_global_offset_z
      - .offset:         424
        .size:           2
        .value_kind:     hidden_grid_dims
      - .offset:         448
        .size:           8
        .value_kind:     hidden_multigrid_sync_arg
    .group_segment_fixed_size: 73744
    .kernarg_segment_align: 8
    .kernarg_segment_size: 616
    .language:       OpenCL C
    .language_version:
      - 2
      - 0
    .max_flat_workgroup_size: 256
    .name:           _Z4mega6Params
    .private_segment_fixed_size: 0
    .sgpr_count:     108
    .sgpr_spill_count: 16
    .symbol:         _Z4mega6Params.kd
    .uniform_work_group_size: 1
    .uses_dynamic_stack: false
    .vgpr_count:     256
    .vgpr_spill_count: 0
    .wavefront_size: 64
